# K-loop priority flips inverted: the loading wave is raised, the MFMA wave dropped
# baseline (speedup 1.0000x reference)
.LBB0_153:
	ds_read_b128 v[0:3], v145
	ds_read_b128 v[4:7], v145 offset:1024
	ds_read_b128 v[8:11], v145 offset:2048
	ds_read_b128 v[12:15], v145 offset:3072
	ds_read_b128 v[16:19], v146
	ds_read_b128 v[20:23], v146 offset:1024
	ds_read_b128 v[24:27], v146 offset:2048
	ds_read_b128 v[28:31], v146 offset:3072
	s_ashr_i32 s37, s36, 31
	s_lshl_b64 s[46:47], s[36:37], 17
	s_add_u32 s46, s44, s46
	s_addc_u32 s47, s45, s47
	s_and_b64 s[48:49], s[4:5], exec
	s_cselect_b32 s59, s47, s53
	s_cselect_b32 s58, s46, s52
	s_ashr_i32 s35, s34, 31
	s_lshl_b64 s[48:49], s[34:35], 17
	s_add_u32 s48, s60, s48
	s_addc_u32 s49, s61, s49
	s_and_b64 s[56:57], s[4:5], exec
	s_cselect_b32 s57, s49, s55
	s_cselect_b32 s56, s48, s54
	s_add_u32 s80, s52, 0x10080
	s_addc_u32 s81, s53, 0
	s_add_i32 s83, s51, 0xc000
	v_lshl_add_u64 v[64:65], s[80:81], 0, v[128:129]
	s_mov_b32 m0, s83
	s_add_i32 s35, s51, 0xe000
	ds_read_b128 v[32:35], v147
	ds_read_b128 v[36:39], v147 offset:1024
	ds_read_b128 v[40:43], v147 offset:2048
	ds_read_b128 v[44:47], v147 offset:3072
	ds_read_b128 v[48:51], v147 offset:4096
	ds_read_b128 v[52:55], v147 offset:5120
	ds_read_b128 v[56:59], v147 offset:6144
	ds_read_b128 v[60:63], v147 offset:7168
	global_load_lds_dwordx4 v[64:65], off
	v_lshl_add_u64 v[64:65], s[80:81], 0, v[132:133]
	s_mov_b32 m0, s35
	s_nop 0
	global_load_lds_dwordx4 v[64:65], off
	s_waitcnt vmcnt(8)
	s_waitcnt lgkmcnt(0)
	s_setprio 0
	s_barrier
	v_mfma_f32_16x16x32_bf16 v[64:67], v[0:3], v[32:35], 0
	v_mfma_f32_16x16x32_bf16 v[68:71], v[8:11], v[32:35], 0
	v_mfma_f32_16x16x32_bf16 v[72:75], v[0:3], v[40:43], 0
	v_mfma_f32_16x16x32_bf16 v[76:79], v[8:11], v[40:43], 0
	v_mfma_f32_16x16x32_bf16 v[80:83], v[0:3], v[48:51], 0
	v_mfma_f32_16x16x32_bf16 v[84:87], v[8:11], v[48:51], 0
	v_mfma_f32_16x16x32_bf16 v[88:91], v[0:3], v[56:59], 0
	v_mfma_f32_16x16x32_bf16 v[92:95], v[8:11], v[56:59], 0
	v_mfma_f32_16x16x32_bf16 v[64:67], v[4:7], v[36:39], v[64:67]
	v_mfma_f32_16x16x32_bf16 v[68:71], v[12:15], v[36:39], v[68:71]
	v_mfma_f32_16x16x32_bf16 v[72:75], v[4:7], v[44:47], v[72:75]
	v_mfma_f32_16x16x32_bf16 v[76:79], v[12:15], v[44:47], v[76:79]
	v_mfma_f32_16x16x32_bf16 v[80:83], v[4:7], v[52:55], v[80:83]
	v_mfma_f32_16x16x32_bf16 v[84:87], v[12:15], v[52:55], v[84:87]
	v_mfma_f32_16x16x32_bf16 v[88:91], v[4:7], v[60:63], v[88:91]
	v_mfma_f32_16x16x32_bf16 v[92:95], v[12:15], v[60:63], v[92:95]
	v_mfma_f32_16x16x32_bf16 v[96:99], v[16:19], v[32:35], 0
	v_mfma_f32_16x16x32_bf16 v[32:35], v[24:27], v[32:35], 0
	v_mfma_f32_16x16x32_bf16 v[96:99], v[20:23], v[36:39], v[96:99]
	v_mfma_f32_16x16x32_bf16 v[32:35], v[28:31], v[36:39], v[32:35]
	v_mfma_f32_16x16x32_bf16 v[36:39], v[16:19], v[40:43], 0
	v_mfma_f32_16x16x32_bf16 v[40:43], v[24:27], v[40:43], 0
	v_mfma_f32_16x16x32_bf16 v[36:39], v[20:23], v[44:47], v[36:39]
	v_mfma_f32_16x16x32_bf16 v[40:43], v[28:31], v[44:47], v[40:43]
	v_mfma_f32_16x16x32_bf16 v[44:47], v[16:19], v[48:51], 0
	v_mfma_f32_16x16x32_bf16 v[48:51], v[24:27], v[48:51], 0
	v_mfma_f32_16x16x32_bf16 v[44:47], v[20:23], v[52:55], v[44:47]
	v_mfma_f32_16x16x32_bf16 v[48:51], v[28:31], v[52:55], v[48:51]
	v_mfma_f32_16x16x32_bf16 v[52:55], v[16:19], v[56:59], 0
	v_mfma_f32_16x16x32_bf16 v[56:59], v[24:27], v[56:59], 0
	v_mfma_f32_16x16x32_bf16 v[52:55], v[20:23], v[60:63], v[52:55]
	v_mfma_f32_16x16x32_bf16 v[56:59], v[28:31], v[60:63], v[56:59]
	s_barrier
	s_setprio 1
	s_add_i32 s81, s72, s62
	v_lshl_add_u64 v[140:141], s[54:55], 0, v[130:131]
	s_add_i32 s37, s81, 0x2000
	v_lshl_add_u64 v[148:149], v[140:141], 0, s[18:19]
	s_mov_b32 m0, s81
	v_lshl_add_u64 v[212:213], s[54:55], 0, v[134:135]
	s_add_u32 s84, s54, 0x10100
	ds_read_b128 v[60:63], v147 offset:16384
	ds_read_b128 v[100:103], v147 offset:17408
	ds_read_b128 v[104:107], v147 offset:18432
	ds_read_b128 v[108:111], v147 offset:19456
	ds_read_b128 v[112:115], v147 offset:20480
	ds_read_b128 v[116:119], v147 offset:21504
	ds_read_b128 v[120:123], v147 offset:22528
	ds_read_b128 v[124:127], v147 offset:23552
	global_load_lds_dwordx4 v[148:149], off
	v_lshl_add_u64 v[148:149], v[212:213], 0, s[18:19]
	s_mov_b32 m0, s37
	s_addc_u32 s85, s55, 0
	s_add_i32 s79, s73, s62
	global_load_lds_dwordx4 v[148:149], off
	v_lshl_add_u64 v[148:149], s[84:85], 0, v[130:131]
	s_mov_b32 m0, s79
	s_add_i32 s80, s79, 0x2000
	global_load_lds_dwordx4 v[148:149], off
	v_lshl_add_u64 v[148:149], s[84:85], 0, v[134:135]
	s_mov_b32 m0, s80
	v_lshl_add_u64 v[214:215], s[52:53], 0, v[128:129]
	global_load_lds_dwordx4 v[148:149], off
	v_lshl_add_u64 v[148:149], v[214:215], 0, s[18:19]
	s_mov_b32 m0, s51
	v_lshl_add_u64 v[216:217], s[52:53], 0, v[132:133]
	global_load_lds_dwordx4 v[148:149], off
	v_lshl_add_u64 v[148:149], v[216:217], 0, s[18:19]
	s_mov_b32 m0, s63
	s_nop 0
	global_load_lds_dwordx4 v[148:149], off
	s_waitcnt vmcnt(8)
	s_waitcnt lgkmcnt(0)
	s_setprio 0
	s_barrier
	v_mfma_f32_16x16x32_bf16 v[148:151], v[0:3], v[60:63], 0
	v_mfma_f32_16x16x32_bf16 v[156:159], v[0:3], v[104:107], 0
	v_mfma_f32_16x16x32_bf16 v[164:167], v[0:3], v[112:115], 0
	v_mfma_f32_16x16x32_bf16 v[0:3], v[0:3], v[120:123], 0
	v_mfma_f32_16x16x32_bf16 v[148:151], v[4:7], v[100:103], v[148:151]
	v_mfma_f32_16x16x32_bf16 v[156:159], v[4:7], v[108:111], v[156:159]
	v_mfma_f32_16x16x32_bf16 v[164:167], v[4:7], v[116:119], v[164:167]
	v_mfma_f32_16x16x32_bf16 v[0:3], v[4:7], v[124:127], v[0:3]
	v_mfma_f32_16x16x32_bf16 v[4:7], v[8:11], v[120:123], 0
	v_mfma_f32_16x16x32_bf16 v[152:155], v[8:11], v[60:63], 0
	v_mfma_f32_16x16x32_bf16 v[160:163], v[8:11], v[104:107], 0
	v_mfma_f32_16x16x32_bf16 v[168:171], v[8:11], v[112:115], 0
	v_mfma_f32_16x16x32_bf16 v[4:7], v[12:15], v[124:127], v[4:7]
	v_mfma_f32_16x16x32_bf16 v[152:155], v[12:15], v[100:103], v[152:155]
	v_mfma_f32_16x16x32_bf16 v[160:163], v[12:15], v[108:111], v[160:163]
	v_mfma_f32_16x16x32_bf16 v[168:171], v[12:15], v[116:119], v[168:171]
	v_mfma_f32_16x16x32_bf16 v[8:11], v[16:19], v[60:63], 0
	v_mfma_f32_16x16x32_bf16 v[12:15], v[24:27], v[60:63], 0
	v_mfma_f32_16x16x32_bf16 v[8:11], v[20:23], v[100:103], v[8:11]
	v_mfma_f32_16x16x32_bf16 v[12:15], v[28:31], v[100:103], v[12:15]
	v_mfma_f32_16x16x32_bf16 v[60:63], v[16:19], v[104:107], 0
	v_mfma_f32_16x16x32_bf16 v[100:103], v[24:27], v[104:107], 0
	v_mfma_f32_16x16x32_bf16 v[104:107], v[16:19], v[112:115], 0
	v_mfma_f32_16x16x32_bf16 v[16:19], v[16:19], v[120:123], 0
	v_mfma_f32_16x16x32_bf16 v[60:63], v[20:23], v[108:111], v[60:63]
	v_mfma_f32_16x16x32_bf16 v[100:103], v[28:31], v[108:111], v[100:103]
	v_mfma_f32_16x16x32_bf16 v[104:107], v[20:23], v[116:119], v[104:107]
	v_mfma_f32_16x16x32_bf16 v[108:111], v[24:27], v[112:115], 0
	v_mfma_f32_16x16x32_bf16 v[16:19], v[20:23], v[124:127], v[16:19]
	v_mfma_f32_16x16x32_bf16 v[20:23], v[24:27], v[120:123], 0
	v_mfma_f32_16x16x32_bf16 v[108:111], v[28:31], v[116:119], v[108:111]
	v_mfma_f32_16x16x32_bf16 v[20:23], v[28:31], v[124:127], v[20:23]
	s_barrier
	s_setprio 1
	s_add_i32 s82, 0, 0x18000
	s_add_i32 s88, 0, 0x1c000
	v_add_u32_e32 v228, s82, v143
	v_add_u32_e32 v236, s88, v143
	ds_read_b128 v[24:27], v228
	ds_read_b128 v[28:31], v228 offset:1024
	ds_read_b128 v[112:115], v228 offset:2048
	ds_read_b128 v[116:119], v228 offset:3072
	ds_read_b128 v[120:123], v236
	ds_read_b128 v[124:127], v236 offset:1024
	ds_read_b128 v[172:175], v236 offset:2048
	ds_read_b128 v[176:179], v236 offset:3072
	s_add_u32 s84, s52, 0x10100
	s_addc_u32 s85, s53, 0
	s_mov_b32 m0, s64
	v_lshl_add_u64 v[218:219], s[84:85], 0, v[128:129]
	ds_read_b128 v[180:183], v147 offset:32768
	ds_read_b128 v[184:187], v147 offset:33792
	ds_read_b128 v[188:191], v147 offset:34816
	ds_read_b128 v[192:195], v147 offset:35840
	ds_read_b128 v[196:199], v147 offset:36864
	ds_read_b128 v[200:203], v147 offset:37888
	ds_read_b128 v[204:207], v147 offset:38912
	ds_read_b128 v[208:211], v147 offset:39936
	global_load_lds_dwordx4 v[218:219], off
	v_lshl_add_u64 v[218:219], s[84:85], 0, v[132:133]
	s_mov_b32 m0, s65
	s_nop 0
	global_load_lds_dwordx4 v[218:219], off
	s_waitcnt vmcnt(8)
	s_waitcnt lgkmcnt(0)
	s_setprio 0
	s_barrier
	v_mfma_f32_16x16x32_bf16 v[64:67], v[24:27], v[180:183], v[64:67]
	v_mfma_f32_16x16x32_bf16 v[68:71], v[112:115], v[180:183], v[68:71]
	v_mfma_f32_16x16x32_bf16 v[72:75], v[24:27], v[188:191], v[72:75]
	v_mfma_f32_16x16x32_bf16 v[76:79], v[112:115], v[188:191], v[76:79]
	v_mfma_f32_16x16x32_bf16 v[80:83], v[24:27], v[196:199], v[80:83]
	v_mfma_f32_16x16x32_bf16 v[84:87], v[112:115], v[196:199], v[84:87]
	v_mfma_f32_16x16x32_bf16 v[88:91], v[24:27], v[204:207], v[88:91]
	v_mfma_f32_16x16x32_bf16 v[92:95], v[112:115], v[204:207], v[92:95]
	v_mfma_f32_16x16x32_bf16 v[64:67], v[28:31], v[184:187], v[64:67]
	v_mfma_f32_16x16x32_bf16 v[68:71], v[116:119], v[184:187], v[68:71]
	v_mfma_f32_16x16x32_bf16 v[72:75], v[28:31], v[192:195], v[72:75]
	v_mfma_f32_16x16x32_bf16 v[76:79], v[116:119], v[192:195], v[76:79]
	v_mfma_f32_16x16x32_bf16 v[80:83], v[28:31], v[200:203], v[80:83]
	v_mfma_f32_16x16x32_bf16 v[84:87], v[116:119], v[200:203], v[84:87]
	v_mfma_f32_16x16x32_bf16 v[88:91], v[28:31], v[208:211], v[88:91]
	v_mfma_f32_16x16x32_bf16 v[92:95], v[116:119], v[208:211], v[92:95]
	v_mfma_f32_16x16x32_bf16 v[96:99], v[120:123], v[180:183], v[96:99]
	v_mfma_f32_16x16x32_bf16 v[32:35], v[172:175], v[180:183], v[32:35]
	v_mfma_f32_16x16x32_bf16 v[36:39], v[120:123], v[188:191], v[36:39]
	v_mfma_f32_16x16x32_bf16 v[40:43], v[172:175], v[188:191], v[40:43]
	v_mfma_f32_16x16x32_bf16 v[44:47], v[120:123], v[196:199], v[44:47]
	v_mfma_f32_16x16x32_bf16 v[48:51], v[172:175], v[196:199], v[48:51]
	v_mfma_f32_16x16x32_bf16 v[52:55], v[120:123], v[204:207], v[52:55]
	v_mfma_f32_16x16x32_bf16 v[56:59], v[172:175], v[204:207], v[56:59]
	v_mfma_f32_16x16x32_bf16 v[96:99], v[124:127], v[184:187], v[96:99]
	v_mfma_f32_16x16x32_bf16 v[32:35], v[176:179], v[184:187], v[32:35]
	v_mfma_f32_16x16x32_bf16 v[36:39], v[124:127], v[192:195], v[36:39]
	v_mfma_f32_16x16x32_bf16 v[40:43], v[176:179], v[192:195], v[40:43]
	v_mfma_f32_16x16x32_bf16 v[44:47], v[124:127], v[200:203], v[44:47]
	v_mfma_f32_16x16x32_bf16 v[48:51], v[176:179], v[200:203], v[48:51]
	v_mfma_f32_16x16x32_bf16 v[52:55], v[124:127], v[208:211], v[52:55]
	v_mfma_f32_16x16x32_bf16 v[56:59], v[176:179], v[208:211], v[56:59]
	s_barrier
	s_setprio 1
	s_add_i32 s84, s82, s62
	s_add_i32 s82, s84, 0x2000
	v_lshl_add_u64 v[140:141], v[140:141], 0, s[20:21]
	s_mov_b32 m0, s84
	s_add_u32 s86, s54, 0x10180
	ds_read_b128 v[180:183], v147 offset:49152
	ds_read_b128 v[184:187], v147 offset:50176
	ds_read_b128 v[188:191], v147 offset:51200
	ds_read_b128 v[192:195], v147 offset:52224
	ds_read_b128 v[196:199], v147 offset:53248
	ds_read_b128 v[200:203], v147 offset:54272
	ds_read_b128 v[204:207], v147 offset:55296
	ds_read_b128 v[208:211], v147 offset:56320
	global_load_lds_dwordx4 v[140:141], off
	v_lshl_add_u64 v[140:141], v[212:213], 0, s[20:21]
	s_mov_b32 m0, s82
	s_addc_u32 s87, s55, 0
	s_add_i32 s54, s88, s62
	global_load_lds_dwordx4 v[140:141], off
	v_lshl_add_u64 v[140:141], s[86:87], 0, v[130:131]
	s_mov_b32 m0, s54
	s_add_i32 s55, s54, 0x2000
	global_load_lds_dwordx4 v[140:141], off
	v_lshl_add_u64 v[140:141], s[86:87], 0, v[134:135]
	s_mov_b32 m0, s55
	s_nop 0
	global_load_lds_dwordx4 v[140:141], off
	v_lshl_add_u64 v[140:141], v[214:215], 0, s[20:21]
	s_mov_b32 m0, s66
	s_nop 0
	global_load_lds_dwordx4 v[140:141], off
	v_lshl_add_u64 v[140:141], v[216:217], 0, s[20:21]
	s_mov_b32 m0, s67
	s_nop 0
	global_load_lds_dwordx4 v[140:141], off
	s_waitcnt vmcnt(8)
	s_waitcnt lgkmcnt(0)
	s_setprio 0
	s_barrier
	v_mfma_f32_16x16x32_bf16 v[0:3], v[24:27], v[204:207], v[0:3]
	v_mfma_f32_16x16x32_bf16 v[4:7], v[112:115], v[204:207], v[4:7]
	v_mfma_f32_16x16x32_bf16 v[148:151], v[24:27], v[180:183], v[148:151]
	v_mfma_f32_16x16x32_bf16 v[152:155], v[112:115], v[180:183], v[152:155]
	v_mfma_f32_16x16x32_bf16 v[156:159], v[24:27], v[188:191], v[156:159]
	v_mfma_f32_16x16x32_bf16 v[160:163], v[112:115], v[188:191], v[160:163]
	v_mfma_f32_16x16x32_bf16 v[164:167], v[24:27], v[196:199], v[164:167]
	v_mfma_f32_16x16x32_bf16 v[168:171], v[112:115], v[196:199], v[168:171]
	v_mfma_f32_16x16x32_bf16 v[0:3], v[28:31], v[208:211], v[0:3]
	v_mfma_f32_16x16x32_bf16 v[4:7], v[116:119], v[208:211], v[4:7]
	v_mfma_f32_16x16x32_bf16 v[148:151], v[28:31], v[184:187], v[148:151]
	v_mfma_f32_16x16x32_bf16 v[152:155], v[116:119], v[184:187], v[152:155]
	v_mfma_f32_16x16x32_bf16 v[156:159], v[28:31], v[192:195], v[156:159]
	v_mfma_f32_16x16x32_bf16 v[160:163], v[116:119], v[192:195], v[160:163]
	v_mfma_f32_16x16x32_bf16 v[164:167], v[28:31], v[200:203], v[164:167]
	v_mfma_f32_16x16x32_bf16 v[168:171], v[116:119], v[200:203], v[168:171]
	v_mfma_f32_16x16x32_bf16 v[8:11], v[120:123], v[180:183], v[8:11]
	v_mfma_f32_16x16x32_bf16 v[12:15], v[172:175], v[180:183], v[12:15]
	v_mfma_f32_16x16x32_bf16 v[24:27], v[120:123], v[188:191], v[60:63]
	v_mfma_f32_16x16x32_bf16 v[28:31], v[172:175], v[188:191], v[100:103]
	v_mfma_f32_16x16x32_bf16 v[60:63], v[120:123], v[196:199], v[104:107]
	v_mfma_f32_16x16x32_bf16 v[100:103], v[172:175], v[196:199], v[108:111]
	v_mfma_f32_16x16x32_bf16 v[16:19], v[120:123], v[204:207], v[16:19]
	v_mfma_f32_16x16x32_bf16 v[20:23], v[172:175], v[204:207], v[20:23]
	v_mfma_f32_16x16x32_bf16 v[8:11], v[124:127], v[184:187], v[8:11]
	v_mfma_f32_16x16x32_bf16 v[12:15], v[176:179], v[184:187], v[12:15]
	v_mfma_f32_16x16x32_bf16 v[24:27], v[124:127], v[192:195], v[24:27]
	v_mfma_f32_16x16x32_bf16 v[28:31], v[176:179], v[192:195], v[28:31]
	v_mfma_f32_16x16x32_bf16 v[60:63], v[124:127], v[200:203], v[60:63]
	v_mfma_f32_16x16x32_bf16 v[100:103], v[176:179], v[200:203], v[100:103]
	v_mfma_f32_16x16x32_bf16 v[16:19], v[124:127], v[208:211], v[16:19]
	v_mfma_f32_16x16x32_bf16 v[20:23], v[176:179], v[208:211], v[20:23]
	s_barrier
	s_setprio 1
	ds_read_b128 v[104:107], v145
	ds_read_b128 v[108:111], v145 offset:1024
	ds_read_b128 v[112:115], v145 offset:2048
	ds_read_b128 v[116:119], v145 offset:3072
	ds_read_b128 v[120:123], v146
	ds_read_b128 v[124:127], v146 offset:1024
	ds_read_b128 v[172:175], v146 offset:2048
	ds_read_b128 v[176:179], v146 offset:3072
	s_add_u32 s52, s52, 0x10180
	s_addc_u32 s53, s53, 0
	s_mov_b32 m0, s83
	v_lshl_add_u64 v[140:141], s[52:53], 0, v[128:129]
	ds_read_b128 v[180:183], v147
	ds_read_b128 v[184:187], v147 offset:1024
	ds_read_b128 v[188:191], v147 offset:2048
	ds_read_b128 v[192:195], v147 offset:3072
	ds_read_b128 v[196:199], v147 offset:4096
	ds_read_b128 v[200:203], v147 offset:5120
	ds_read_b128 v[204:207], v147 offset:6144
	ds_read_b128 v[208:211], v147 offset:7168
	global_load_lds_dwordx4 v[140:141], off
	v_lshl_add_u64 v[140:141], s[52:53], 0, v[132:133]
	s_mov_b32 m0, s35
	s_nop 0
	global_load_lds_dwordx4 v[140:141], off
	s_waitcnt vmcnt(8)
	s_waitcnt lgkmcnt(0)
	s_setprio 0
	s_barrier
	v_mfma_f32_16x16x32_bf16 v[88:91], v[104:107], v[204:207], v[88:91]
	v_mfma_f32_16x16x32_bf16 v[64:67], v[104:107], v[180:183], v[64:67]
	v_mfma_f32_16x16x32_bf16 v[68:71], v[112:115], v[180:183], v[68:71]
	v_mfma_f32_16x16x32_bf16 v[72:75], v[104:107], v[188:191], v[72:75]
	v_mfma_f32_16x16x32_bf16 v[76:79], v[112:115], v[188:191], v[76:79]
	v_mfma_f32_16x16x32_bf16 v[80:83], v[104:107], v[196:199], v[80:83]
	v_mfma_f32_16x16x32_bf16 v[84:87], v[112:115], v[196:199], v[84:87]
	v_mfma_f32_16x16x32_bf16 v[212:215], v[108:111], v[208:211], v[88:91]
	v_mfma_f32_16x16x32_bf16 v[88:91], v[112:115], v[204:207], v[92:95]
	v_mfma_f32_16x16x32_bf16 v[64:67], v[108:111], v[184:187], v[64:67]
	v_mfma_f32_16x16x32_bf16 v[68:71], v[116:119], v[184:187], v[68:71]
	v_mfma_f32_16x16x32_bf16 v[72:75], v[108:111], v[192:195], v[72:75]
	v_mfma_f32_16x16x32_bf16 v[76:79], v[116:119], v[192:195], v[76:79]
	v_mfma_f32_16x16x32_bf16 v[80:83], v[108:111], v[200:203], v[80:83]
	v_mfma_f32_16x16x32_bf16 v[84:87], v[116:119], v[200:203], v[84:87]
	v_mfma_f32_16x16x32_bf16 v[92:95], v[116:119], v[208:211], v[88:91]
	v_mfma_f32_16x16x32_bf16 v[48:51], v[172:175], v[196:199], v[48:51]
	v_mfma_f32_16x16x32_bf16 v[88:91], v[120:123], v[180:183], v[96:99]
	v_mfma_f32_16x16x32_bf16 v[32:35], v[172:175], v[180:183], v[32:35]
	v_mfma_f32_16x16x32_bf16 v[36:39], v[120:123], v[188:191], v[36:39]
	v_mfma_f32_16x16x32_bf16 v[40:43], v[172:175], v[188:191], v[40:43]
	v_mfma_f32_16x16x32_bf16 v[44:47], v[120:123], v[196:199], v[44:47]
	v_mfma_f32_16x16x32_bf16 v[180:183], v[176:179], v[200:203], v[48:51]
	v_mfma_f32_16x16x32_bf16 v[48:51], v[120:123], v[204:207], v[52:55]
	v_mfma_f32_16x16x32_bf16 v[32:35], v[176:179], v[184:187], v[32:35]
	v_mfma_f32_16x16x32_bf16 v[36:39], v[124:127], v[192:195], v[36:39]
	v_mfma_f32_16x16x32_bf16 v[40:43], v[176:179], v[192:195], v[40:43]
	v_mfma_f32_16x16x32_bf16 v[44:47], v[124:127], v[200:203], v[44:47]
	v_mfma_f32_16x16x32_bf16 v[52:55], v[124:127], v[208:211], v[48:51]
	v_mfma_f32_16x16x32_bf16 v[48:51], v[172:175], v[204:207], v[56:59]
	v_mfma_f32_16x16x32_bf16 v[220:223], v[124:127], v[184:187], v[88:91]
	v_mfma_f32_16x16x32_bf16 v[184:187], v[176:179], v[208:211], v[48:51]
	s_barrier
	s_setprio 1
	s_mov_b32 m0, s81
	v_lshl_add_u64 v[140:141], s[56:57], 0, v[130:131]
	s_add_u32 s52, s56, 0x10000
	s_nop 0
	ds_read_b128 v[48:51], v147 offset:16384
	ds_read_b128 v[56:59], v147 offset:17408
	ds_read_b128 v[88:91], v147 offset:18432
	ds_read_b128 v[96:99], v147 offset:19456
	ds_read_b128 v[188:191], v147 offset:20480
	ds_read_b128 v[192:195], v147 offset:21504
	ds_read_b128 v[196:199], v147 offset:22528
	ds_read_b128 v[200:203], v147 offset:23552
	global_load_lds_dwordx4 v[140:141], off
	v_lshl_add_u64 v[252:253], s[56:57], 0, v[134:135]
	s_mov_b32 m0, s37
	s_addc_u32 s53, s57, 0
	global_load_lds_dwordx4 v[252:253], off
	v_lshl_add_u64 v[204:205], s[52:53], 0, v[130:131]
	s_mov_b32 m0, s79
	v_lshl_add_u64 v[136:137], s[58:59], 0, v[128:129]
	global_load_lds_dwordx4 v[204:205], off
	v_lshl_add_u64 v[204:205], s[52:53], 0, v[134:135]
	s_mov_b32 m0, s80
	v_lshl_add_u64 v[138:139], s[58:59], 0, v[132:133]
	global_load_lds_dwordx4 v[204:205], off
	s_mov_b32 m0, s51
	s_nop 0
	global_load_lds_dwordx4 v[136:137], off
	s_mov_b32 m0, s63
	s_nop 0
	global_load_lds_dwordx4 v[138:139], off
	s_waitcnt vmcnt(8)
	s_waitcnt lgkmcnt(0)
	s_setprio 0
	s_barrier
	v_mfma_f32_16x16x32_bf16 v[0:3], v[104:107], v[196:199], v[0:3]
	v_mfma_f32_16x16x32_bf16 v[4:7], v[112:115], v[196:199], v[4:7]
	v_mfma_f32_16x16x32_bf16 v[148:151], v[104:107], v[48:51], v[148:151]
	v_mfma_f32_16x16x32_bf16 v[152:155], v[112:115], v[48:51], v[152:155]
	v_mfma_f32_16x16x32_bf16 v[156:159], v[104:107], v[88:91], v[156:159]
	v_mfma_f32_16x16x32_bf16 v[160:163], v[112:115], v[88:91], v[160:163]
	v_mfma_f32_16x16x32_bf16 v[164:167], v[104:107], v[188:191], v[164:167]
	v_mfma_f32_16x16x32_bf16 v[168:171], v[112:115], v[188:191], v[168:171]
	v_mfma_f32_16x16x32_bf16 v[0:3], v[108:111], v[200:203], v[0:3]
	v_mfma_f32_16x16x32_bf16 v[4:7], v[116:119], v[200:203], v[4:7]
	v_mfma_f32_16x16x32_bf16 v[148:151], v[108:111], v[56:59], v[148:151]
	v_mfma_f32_16x16x32_bf16 v[152:155], v[116:119], v[56:59], v[152:155]
	v_mfma_f32_16x16x32_bf16 v[156:159], v[108:111], v[96:99], v[156:159]
	v_mfma_f32_16x16x32_bf16 v[160:163], v[116:119], v[96:99], v[160:163]
	v_mfma_f32_16x16x32_bf16 v[164:167], v[108:111], v[192:195], v[164:167]
	v_mfma_f32_16x16x32_bf16 v[168:171], v[116:119], v[192:195], v[168:171]
	v_mfma_f32_16x16x32_bf16 v[12:15], v[172:175], v[48:51], v[12:15]
	v_mfma_f32_16x16x32_bf16 v[204:207], v[176:179], v[56:59], v[12:15]
	v_mfma_f32_16x16x32_bf16 v[12:15], v[120:123], v[88:91], v[24:27]
	v_mfma_f32_16x16x32_bf16 v[24:27], v[124:127], v[96:99], v[12:15]
	v_mfma_f32_16x16x32_bf16 v[12:15], v[172:175], v[88:91], v[28:31]
	v_mfma_f32_16x16x32_bf16 v[208:211], v[176:179], v[96:99], v[12:15]
	v_mfma_f32_16x16x32_bf16 v[12:15], v[120:123], v[188:191], v[60:63]
	v_mfma_f32_16x16x32_bf16 v[224:227], v[124:127], v[192:195], v[12:15]
	v_mfma_f32_16x16x32_bf16 v[12:15], v[172:175], v[188:191], v[100:103]
	v_mfma_f32_16x16x32_bf16 v[8:11], v[120:123], v[48:51], v[8:11]
	v_mfma_f32_16x16x32_bf16 v[188:191], v[176:179], v[192:195], v[12:15]
	v_mfma_f32_16x16x32_bf16 v[12:15], v[120:123], v[196:199], v[16:19]
	v_mfma_f32_16x16x32_bf16 v[8:11], v[124:127], v[56:59], v[8:11]
	v_mfma_f32_16x16x32_bf16 v[192:195], v[124:127], v[200:203], v[12:15]
	v_mfma_f32_16x16x32_bf16 v[12:15], v[172:175], v[196:199], v[20:23]
	v_mfma_f32_16x16x32_bf16 v[172:175], v[176:179], v[200:203], v[12:15]
	s_barrier
	s_setprio 1
	s_nop 4
	ds_read_b128 v[12:15], v228
	ds_read_b128 v[16:19], v228 offset:1024
	ds_read_b128 v[176:179], v228 offset:2048
	ds_read_b128 v[196:199], v228 offset:3072
	ds_read_b128 v[200:203], v236
	ds_read_b128 v[228:231], v236 offset:1024
	ds_read_b128 v[232:235], v236 offset:2048
	ds_read_b128 v[236:239], v236 offset:3072
	s_add_u32 s52, s58, 0x10000
	s_addc_u32 s53, s59, 0
	s_mov_b32 m0, s64
	v_lshl_add_u64 v[48:49], s[52:53], 0, v[128:129]
	ds_read_b128 v[20:23], v147 offset:32768
	ds_read_b128 v[28:31], v147 offset:33792
	ds_read_b128 v[60:63], v147 offset:34816
	ds_read_b128 v[100:103], v147 offset:35840
	ds_read_b128 v[240:243], v147 offset:36864
	ds_read_b128 v[244:247], v147 offset:37888
	ds_read_b128 v[248:251], v147 offset:38912
	ds_read_b128 v[216:219], v147 offset:39936
	global_load_lds_dwordx4 v[48:49], off
	v_lshl_add_u64 v[48:49], s[52:53], 0, v[132:133]
	s_mov_b32 m0, s65
	s_nop 0
	global_load_lds_dwordx4 v[48:49], off
	s_waitcnt vmcnt(8)
	s_waitcnt lgkmcnt(0)
	s_setprio 0
	s_barrier
	v_mfma_f32_16x16x32_bf16 v[48:51], v[12:15], v[20:23], v[64:67]
	v_mfma_f32_16x16x32_bf16 v[120:123], v[16:19], v[28:31], v[48:51]
	v_mfma_f32_16x16x32_bf16 v[48:51], v[176:179], v[20:23], v[68:71]
	v_mfma_f32_16x16x32_bf16 v[112:115], v[196:199], v[28:31], v[48:51]
	v_mfma_f32_16x16x32_bf16 v[48:51], v[12:15], v[60:63], v[72:75]
	v_mfma_f32_16x16x32_bf16 v[104:107], v[16:19], v[100:103], v[48:51]
	v_mfma_f32_16x16x32_bf16 v[48:51], v[176:179], v[60:63], v[76:79]
	v_mfma_f32_16x16x32_bf16 v[96:99], v[196:199], v[100:103], v[48:51]
	v_mfma_f32_16x16x32_bf16 v[48:51], v[12:15], v[240:243], v[80:83]
	v_mfma_f32_16x16x32_bf16 v[88:91], v[16:19], v[244:247], v[48:51]
	v_mfma_f32_16x16x32_bf16 v[48:51], v[176:179], v[240:243], v[84:87]
	v_mfma_f32_16x16x32_bf16 v[80:83], v[196:199], v[244:247], v[48:51]
	v_mfma_f32_16x16x32_bf16 v[48:51], v[12:15], v[248:251], v[212:215]
	v_mfma_f32_16x16x32_bf16 v[56:59], v[16:19], v[216:219], v[48:51]
	v_mfma_f32_16x16x32_bf16 v[48:51], v[176:179], v[248:251], v[92:95]
	v_mfma_f32_16x16x32_bf16 v[48:51], v[196:199], v[216:219], v[48:51]
	v_mfma_f32_16x16x32_bf16 v[64:67], v[200:203], v[20:23], v[220:223]
	v_mfma_f32_16x16x32_bf16 v[20:23], v[232:235], v[20:23], v[32:35]
	v_mfma_f32_16x16x32_bf16 v[116:119], v[236:239], v[28:31], v[20:23]
	v_mfma_f32_16x16x32_bf16 v[20:23], v[200:203], v[60:63], v[36:39]
	v_mfma_f32_16x16x32_bf16 v[108:111], v[228:231], v[100:103], v[20:23]
	v_mfma_f32_16x16x32_bf16 v[20:23], v[232:235], v[60:63], v[40:43]
	v_mfma_f32_16x16x32_bf16 v[100:103], v[236:239], v[100:103], v[20:23]
	v_mfma_f32_16x16x32_bf16 v[20:23], v[200:203], v[240:243], v[44:47]
	v_mfma_f32_16x16x32_bf16 v[92:95], v[228:231], v[244:247], v[20:23]
	v_mfma_f32_16x16x32_bf16 v[20:23], v[232:235], v[240:243], v[180:183]
	v_mfma_f32_16x16x32_bf16 v[84:87], v[236:239], v[244:247], v[20:23]
	v_mfma_f32_16x16x32_bf16 v[20:23], v[200:203], v[248:251], v[52:55]
	v_mfma_f32_16x16x32_bf16 v[60:63], v[228:231], v[216:219], v[20:23]
	v_mfma_f32_16x16x32_bf16 v[20:23], v[232:235], v[248:251], v[184:187]
	v_mfma_f32_16x16x32_bf16 v[124:127], v[228:231], v[28:31], v[64:67]
	v_mfma_f32_16x16x32_bf16 v[52:55], v[236:239], v[216:219], v[20:23]
	s_barrier
	s_setprio 1
	s_mov_b32 m0, s84
	s_nop 2
	v_lshl_add_u64 v[20:21], v[140:141], 0, s[12:13]
	s_add_u32 s52, s56, 0x10080
	ds_read_b128 v[32:35], v147 offset:49152
	ds_read_b128 v[40:43], v147 offset:50176
	ds_read_b128 v[180:183], v147 offset:51200
	ds_read_b128 v[184:187], v147 offset:52224
	ds_read_b128 v[212:215], v147 offset:53248
	ds_read_b128 v[216:219], v147 offset:54272
	ds_read_b128 v[220:223], v147 offset:55296
	ds_read_b128 v[240:243], v147 offset:56320
	global_load_lds_dwordx4 v[20:21], off
	v_lshl_add_u64 v[20:21], v[252:253], 0, s[12:13]
	s_mov_b32 m0, s82
	s_addc_u32 s53, s57, 0
	global_load_lds_dwordx4 v[20:21], off
	v_lshl_add_u64 v[20:21], s[52:53], 0, v[130:131]
	s_mov_b32 m0, s54
	s_nop 0
	global_load_lds_dwordx4 v[20:21], off
	v_lshl_add_u64 v[20:21], s[52:53], 0, v[134:135]
	s_mov_b32 m0, s55
	s_nop 0
	global_load_lds_dwordx4 v[20:21], off
	v_lshl_add_u64 v[20:21], v[136:137], 0, s[12:13]
	s_mov_b32 m0, s66
	s_nop 0
	global_load_lds_dwordx4 v[20:21], off
	v_lshl_add_u64 v[20:21], v[138:139], 0, s[12:13]
	s_mov_b32 m0, s67
	s_nop 0
	global_load_lds_dwordx4 v[20:21], off
	s_waitcnt vmcnt(8)
	s_waitcnt lgkmcnt(0)
	s_setprio 0
	s_barrier
	v_mfma_f32_16x16x32_bf16 v[20:23], v[12:15], v[32:35], v[148:151]
	v_mfma_f32_16x16x32_bf16 v[76:79], v[16:19], v[40:43], v[20:23]
	v_mfma_f32_16x16x32_bf16 v[20:23], v[176:179], v[32:35], v[152:155]
	v_mfma_f32_16x16x32_bf16 v[68:71], v[196:199], v[40:43], v[20:23]
	v_mfma_f32_16x16x32_bf16 v[20:23], v[12:15], v[180:183], v[156:159]
	v_mfma_f32_16x16x32_bf16 v[44:47], v[16:19], v[184:187], v[20:23]
	v_mfma_f32_16x16x32_bf16 v[20:23], v[176:179], v[180:183], v[160:163]
	v_mfma_f32_16x16x32_bf16 v[36:39], v[196:199], v[184:187], v[20:23]
	v_mfma_f32_16x16x32_bf16 v[20:23], v[12:15], v[212:215], v[164:167]
	v_mfma_f32_16x16x32_bf16 v[0:3], v[12:15], v[220:223], v[0:3]
	v_mfma_f32_16x16x32_bf16 v[28:31], v[16:19], v[216:219], v[20:23]
	v_mfma_f32_16x16x32_bf16 v[20:23], v[176:179], v[212:215], v[168:171]
	v_mfma_f32_16x16x32_bf16 v[12:15], v[16:19], v[240:243], v[0:3]
	v_mfma_f32_16x16x32_bf16 v[0:3], v[176:179], v[220:223], v[4:7]
	v_mfma_f32_16x16x32_bf16 v[20:23], v[196:199], v[216:219], v[20:23]
	v_mfma_f32_16x16x32_bf16 v[4:7], v[196:199], v[240:243], v[0:3]
	v_mfma_f32_16x16x32_bf16 v[0:3], v[200:203], v[32:35], v[8:11]
	v_mfma_f32_16x16x32_bf16 v[72:75], v[228:231], v[40:43], v[0:3]
	v_mfma_f32_16x16x32_bf16 v[0:3], v[232:235], v[32:35], v[204:207]
	v_mfma_f32_16x16x32_bf16 v[64:67], v[236:239], v[40:43], v[0:3]
	v_mfma_f32_16x16x32_bf16 v[0:3], v[200:203], v[180:183], v[24:27]
	v_mfma_f32_16x16x32_bf16 v[40:43], v[228:231], v[184:187], v[0:3]
	v_mfma_f32_16x16x32_bf16 v[0:3], v[232:235], v[180:183], v[208:211]
	v_mfma_f32_16x16x32_bf16 v[32:35], v[236:239], v[184:187], v[0:3]
	v_mfma_f32_16x16x32_bf16 v[0:3], v[200:203], v[212:215], v[224:227]
	v_mfma_f32_16x16x32_bf16 v[24:27], v[228:231], v[216:219], v[0:3]
	v_mfma_f32_16x16x32_bf16 v[0:3], v[232:235], v[212:215], v[188:191]
	v_mfma_f32_16x16x32_bf16 v[16:19], v[236:239], v[216:219], v[0:3]
	v_mfma_f32_16x16x32_bf16 v[0:3], v[200:203], v[220:223], v[192:195]
	v_mfma_f32_16x16x32_bf16 v[8:11], v[228:231], v[240:243], v[0:3]
	v_mfma_f32_16x16x32_bf16 v[0:3], v[232:235], v[220:223], v[172:175]
	v_mfma_f32_16x16x32_bf16 v[0:3], v[236:239], v[240:243], v[0:3]
	s_barrier
	s_setprio 1
	s_andn2_b64 vcc, exec, s[14:15]
	s_cbranch_vccnz .LBB0_155
	s_barrier

.LBB0_178:
	ds_read_b128 v[148:151], v157
	ds_read_b128 v[162:165], v157 offset:1024
	ds_read_b128 v[166:169], v157 offset:2048
	ds_read_b128 v[170:173], v157 offset:3072
	ds_read_b128 v[174:177], v158
	ds_read_b128 v[178:181], v158 offset:1024
	ds_read_b128 v[182:185], v158 offset:2048
	ds_read_b128 v[186:189], v158 offset:3072
	s_add_u32 s48, s46, 0xfff80080
	s_addc_u32 s49, s47, -1
	s_cmp_eq_u32 s72, 28
	s_cselect_b32 s51, s31, s49
	s_cselect_b32 s50, s66, s48
	s_cselect_b32 s49, s27, s71
	s_cselect_b32 s48, s67, s70
	v_lshl_add_u64 v[152:153], s[46:47], 0, v[142:143]
	s_add_i32 m0, s13, 0xc000
	ds_read_b128 v[190:193], v159
	ds_read_b128 v[194:197], v159 offset:1024
	ds_read_b128 v[198:201], v159 offset:2048
	ds_read_b128 v[202:205], v159 offset:3072
	ds_read_b128 v[206:209], v159 offset:4096
	ds_read_b128 v[210:213], v159 offset:5120
	ds_read_b128 v[214:217], v159 offset:6144
	ds_read_b128 v[218:221], v159 offset:7168
	global_load_lds_dwordx4 v[152:153], off
	v_lshl_add_u64 v[152:153], s[46:47], 0, v[140:141]
	s_add_i32 m0, s13, 0xe000
	s_nop 0
	global_load_lds_dwordx4 v[152:153], off
	s_waitcnt vmcnt(8)
	s_waitcnt lgkmcnt(0)
	s_setprio 0
	s_barrier
	v_mfma_f32_16x16x32_bf16 v[124:127], v[148:151], v[190:193], v[124:127]
	v_mfma_f32_16x16x32_bf16 v[120:123], v[166:169], v[190:193], v[120:123]
	v_mfma_f32_16x16x32_bf16 v[108:111], v[148:151], v[198:201], v[108:111]
	v_mfma_f32_16x16x32_bf16 v[104:107], v[166:169], v[198:201], v[104:107]
	v_mfma_f32_16x16x32_bf16 v[92:95], v[148:151], v[206:209], v[92:95]
	v_mfma_f32_16x16x32_bf16 v[88:91], v[166:169], v[206:209], v[88:91]
	v_mfma_f32_16x16x32_bf16 v[76:79], v[148:151], v[214:217], v[76:79]
	v_mfma_f32_16x16x32_bf16 v[72:75], v[166:169], v[214:217], v[72:75]
	v_mfma_f32_16x16x32_bf16 v[124:127], v[162:165], v[194:197], v[124:127]
	v_mfma_f32_16x16x32_bf16 v[120:123], v[170:173], v[194:197], v[120:123]
	v_mfma_f32_16x16x32_bf16 v[108:111], v[162:165], v[202:205], v[108:111]
	v_mfma_f32_16x16x32_bf16 v[104:107], v[170:173], v[202:205], v[104:107]
	v_mfma_f32_16x16x32_bf16 v[92:95], v[162:165], v[210:213], v[92:95]
	v_mfma_f32_16x16x32_bf16 v[88:91], v[170:173], v[210:213], v[88:91]
	v_mfma_f32_16x16x32_bf16 v[76:79], v[162:165], v[218:221], v[76:79]
	v_mfma_f32_16x16x32_bf16 v[72:75], v[170:173], v[218:221], v[72:75]
	v_mfma_f32_16x16x32_bf16 v[116:119], v[174:177], v[190:193], v[116:119]
	v_mfma_f32_16x16x32_bf16 v[112:115], v[182:185], v[190:193], v[112:115]
	v_mfma_f32_16x16x32_bf16 v[100:103], v[174:177], v[198:201], v[100:103]
	v_mfma_f32_16x16x32_bf16 v[96:99], v[182:185], v[198:201], v[96:99]
	v_mfma_f32_16x16x32_bf16 v[84:87], v[174:177], v[206:209], v[84:87]
	v_mfma_f32_16x16x32_bf16 v[80:83], v[182:185], v[206:209], v[80:83]
	v_mfma_f32_16x16x32_bf16 v[68:71], v[174:177], v[214:217], v[68:71]
	v_mfma_f32_16x16x32_bf16 v[64:67], v[182:185], v[214:217], v[64:67]
	v_mfma_f32_16x16x32_bf16 v[116:119], v[178:181], v[194:197], v[116:119]
	v_mfma_f32_16x16x32_bf16 v[112:115], v[186:189], v[194:197], v[112:115]
	v_mfma_f32_16x16x32_bf16 v[100:103], v[178:181], v[202:205], v[100:103]
	v_mfma_f32_16x16x32_bf16 v[96:99], v[186:189], v[202:205], v[96:99]
	v_mfma_f32_16x16x32_bf16 v[84:87], v[178:181], v[210:213], v[84:87]
	v_mfma_f32_16x16x32_bf16 v[80:83], v[186:189], v[210:213], v[80:83]
	v_mfma_f32_16x16x32_bf16 v[68:71], v[178:181], v[218:221], v[68:71]
	v_mfma_f32_16x16x32_bf16 v[64:67], v[186:189], v[218:221], v[64:67]
	s_barrier
	s_setprio 1
	s_add_i32 s73, s62, s52
	v_lshl_add_u64 v[152:153], s[48:49], 0, v[130:131]
	s_mov_b32 m0, s73
	ds_read_b128 v[190:193], v159 offset:16384
	ds_read_b128 v[194:197], v159 offset:17408
	ds_read_b128 v[198:201], v159 offset:18432
	ds_read_b128 v[202:205], v159 offset:19456
	ds_read_b128 v[206:209], v159 offset:20480
	ds_read_b128 v[210:213], v159 offset:21504
	ds_read_b128 v[214:217], v159 offset:22528
	ds_read_b128 v[218:221], v159 offset:23552
	global_load_lds_dwordx4 v[152:153], off
	s_add_i32 m0, s73, 0x2000
	s_add_u32 s74, s48, 0x80000
	v_lshl_add_u64 v[222:223], s[48:49], 0, v[134:135]
	s_addc_u32 s75, s49, 0
	s_add_i32 s73, s63, s52
	global_load_lds_dwordx4 v[222:223], off
	v_lshl_add_u64 v[224:225], s[74:75], 0, v[130:131]
	s_mov_b32 m0, s73
	v_lshl_add_u64 v[226:227], s[50:51], 0, v[132:133]
	global_load_lds_dwordx4 v[224:225], off
	v_lshl_add_u64 v[224:225], s[74:75], 0, v[134:135]
	s_add_i32 m0, s73, 0x2000
	s_nop 0
	global_load_lds_dwordx4 v[224:225], off
	v_lshl_add_u64 v[224:225], s[50:51], 0, v[128:129]
	s_mov_b32 m0, s13
	s_nop 0
	global_load_lds_dwordx4 v[224:225], off
	s_mov_b32 m0, s53
	s_nop 0
	global_load_lds_dwordx4 v[226:227], off
	s_waitcnt vmcnt(8)
	s_waitcnt lgkmcnt(0)
	s_setprio 0
	s_barrier
	v_mfma_f32_16x16x32_bf16 v[60:63], v[148:151], v[190:193], v[60:63]
	v_mfma_f32_16x16x32_bf16 v[56:59], v[166:169], v[190:193], v[56:59]
	v_mfma_f32_16x16x32_bf16 v[44:47], v[148:151], v[198:201], v[44:47]
	v_mfma_f32_16x16x32_bf16 v[40:43], v[166:169], v[198:201], v[40:43]
	v_mfma_f32_16x16x32_bf16 v[28:31], v[148:151], v[206:209], v[28:31]
	v_mfma_f32_16x16x32_bf16 v[24:27], v[166:169], v[206:209], v[24:27]
	v_mfma_f32_16x16x32_bf16 v[12:15], v[148:151], v[214:217], v[12:15]
	v_mfma_f32_16x16x32_bf16 v[8:11], v[166:169], v[214:217], v[8:11]
	v_mfma_f32_16x16x32_bf16 v[60:63], v[162:165], v[194:197], v[60:63]
	v_mfma_f32_16x16x32_bf16 v[56:59], v[170:173], v[194:197], v[56:59]
	v_mfma_f32_16x16x32_bf16 v[44:47], v[162:165], v[202:205], v[44:47]
	v_mfma_f32_16x16x32_bf16 v[40:43], v[170:173], v[202:205], v[40:43]
	v_mfma_f32_16x16x32_bf16 v[28:31], v[162:165], v[210:213], v[28:31]
	v_mfma_f32_16x16x32_bf16 v[24:27], v[170:173], v[210:213], v[24:27]
	v_mfma_f32_16x16x32_bf16 v[12:15], v[162:165], v[218:221], v[12:15]
	v_mfma_f32_16x16x32_bf16 v[8:11], v[170:173], v[218:221], v[8:11]
	v_mfma_f32_16x16x32_bf16 v[52:55], v[174:177], v[190:193], v[52:55]
	v_mfma_f32_16x16x32_bf16 v[48:51], v[182:185], v[190:193], v[48:51]
	v_mfma_f32_16x16x32_bf16 v[36:39], v[174:177], v[198:201], v[36:39]
	v_mfma_f32_16x16x32_bf16 v[32:35], v[182:185], v[198:201], v[32:35]
	v_mfma_f32_16x16x32_bf16 v[20:23], v[174:177], v[206:209], v[20:23]
	v_mfma_f32_16x16x32_bf16 v[16:19], v[182:185], v[206:209], v[16:19]
	v_mfma_f32_16x16x32_bf16 v[4:7], v[174:177], v[214:217], v[4:7]
	v_mfma_f32_16x16x32_bf16 v[0:3], v[182:185], v[214:217], v[0:3]
	v_mfma_f32_16x16x32_bf16 v[52:55], v[178:181], v[194:197], v[52:55]
	v_mfma_f32_16x16x32_bf16 v[48:51], v[186:189], v[194:197], v[48:51]
	v_mfma_f32_16x16x32_bf16 v[36:39], v[178:181], v[202:205], v[36:39]
	v_mfma_f32_16x16x32_bf16 v[32:35], v[186:189], v[202:205], v[32:35]
	v_mfma_f32_16x16x32_bf16 v[20:23], v[178:181], v[210:213], v[20:23]
	v_mfma_f32_16x16x32_bf16 v[16:19], v[186:189], v[210:213], v[16:19]
	v_mfma_f32_16x16x32_bf16 v[4:7], v[178:181], v[218:221], v[4:7]
	v_mfma_f32_16x16x32_bf16 v[0:3], v[186:189], v[218:221], v[0:3]
	s_barrier
	s_setprio 1
	s_add_i32 s73, 0, 0x18000
	v_add_u32_e32 v137, s73, v155
	s_add_i32 s74, 0, 0x1c000
	ds_read_b128 v[148:151], v137
	ds_read_b128 v[162:165], v137 offset:1024
	ds_read_b128 v[166:169], v137 offset:2048
	ds_read_b128 v[170:173], v137 offset:3072
	v_add_u32_e32 v137, s74, v155
	ds_read_b128 v[174:177], v137
	ds_read_b128 v[178:181], v137 offset:1024
	ds_read_b128 v[182:185], v137 offset:2048
	ds_read_b128 v[186:189], v137 offset:3072
	s_add_u32 s50, s50, 0x80000
	s_addc_u32 s51, s51, 0
	s_mov_b32 m0, s54
	v_lshl_add_u64 v[228:229], s[50:51], 0, v[128:129]
	ds_read_b128 v[190:193], v159 offset:32768
	ds_read_b128 v[194:197], v159 offset:33792
	ds_read_b128 v[198:201], v159 offset:34816
	ds_read_b128 v[202:205], v159 offset:35840
	ds_read_b128 v[206:209], v159 offset:36864
	ds_read_b128 v[210:213], v159 offset:37888
	ds_read_b128 v[214:217], v159 offset:38912
	ds_read_b128 v[218:221], v159 offset:39936
	global_load_lds_dwordx4 v[228:229], off
	v_lshl_add_u64 v[228:229], s[50:51], 0, v[132:133]
	s_mov_b32 m0, s55
	s_nop 0
	global_load_lds_dwordx4 v[228:229], off
	s_waitcnt vmcnt(8)
	s_waitcnt lgkmcnt(0)
	s_setprio 0
	s_barrier
	v_mfma_f32_16x16x32_bf16 v[124:127], v[148:151], v[190:193], v[124:127]
	v_mfma_f32_16x16x32_bf16 v[120:123], v[166:169], v[190:193], v[120:123]
	v_mfma_f32_16x16x32_bf16 v[108:111], v[148:151], v[198:201], v[108:111]
	v_mfma_f32_16x16x32_bf16 v[104:107], v[166:169], v[198:201], v[104:107]
	v_mfma_f32_16x16x32_bf16 v[92:95], v[148:151], v[206:209], v[92:95]
	v_mfma_f32_16x16x32_bf16 v[88:91], v[166:169], v[206:209], v[88:91]
	v_mfma_f32_16x16x32_bf16 v[76:79], v[148:151], v[214:217], v[76:79]
	v_mfma_f32_16x16x32_bf16 v[72:75], v[166:169], v[214:217], v[72:75]
	v_mfma_f32_16x16x32_bf16 v[124:127], v[162:165], v[194:197], v[124:127]
	v_mfma_f32_16x16x32_bf16 v[120:123], v[170:173], v[194:197], v[120:123]
	v_mfma_f32_16x16x32_bf16 v[108:111], v[162:165], v[202:205], v[108:111]
	v_mfma_f32_16x16x32_bf16 v[104:107], v[170:173], v[202:205], v[104:107]
	v_mfma_f32_16x16x32_bf16 v[92:95], v[162:165], v[210:213], v[92:95]
	v_mfma_f32_16x16x32_bf16 v[88:91], v[170:173], v[210:213], v[88:91]
	v_mfma_f32_16x16x32_bf16 v[76:79], v[162:165], v[218:221], v[76:79]
	v_mfma_f32_16x16x32_bf16 v[72:75], v[170:173], v[218:221], v[72:75]
	v_mfma_f32_16x16x32_bf16 v[116:119], v[174:177], v[190:193], v[116:119]
	v_mfma_f32_16x16x32_bf16 v[112:115], v[182:185], v[190:193], v[112:115]
	v_mfma_f32_16x16x32_bf16 v[100:103], v[174:177], v[198:201], v[100:103]
	v_mfma_f32_16x16x32_bf16 v[96:99], v[182:185], v[198:201], v[96:99]
	v_mfma_f32_16x16x32_bf16 v[84:87], v[174:177], v[206:209], v[84:87]
	v_mfma_f32_16x16x32_bf16 v[80:83], v[182:185], v[206:209], v[80:83]
	v_mfma_f32_16x16x32_bf16 v[68:71], v[174:177], v[214:217], v[68:71]
	v_mfma_f32_16x16x32_bf16 v[64:67], v[182:185], v[214:217], v[64:67]
	v_mfma_f32_16x16x32_bf16 v[116:119], v[178:181], v[194:197], v[116:119]
	v_mfma_f32_16x16x32_bf16 v[112:115], v[186:189], v[194:197], v[112:115]
	v_mfma_f32_16x16x32_bf16 v[100:103], v[178:181], v[202:205], v[100:103]
	v_mfma_f32_16x16x32_bf16 v[96:99], v[186:189], v[202:205], v[96:99]
	v_mfma_f32_16x16x32_bf16 v[84:87], v[178:181], v[210:213], v[84:87]
	v_mfma_f32_16x16x32_bf16 v[80:83], v[186:189], v[210:213], v[80:83]
	v_mfma_f32_16x16x32_bf16 v[68:71], v[178:181], v[218:221], v[68:71]
	v_mfma_f32_16x16x32_bf16 v[64:67], v[186:189], v[218:221], v[64:67]
	s_barrier
	s_setprio 1
	s_add_i32 s50, s73, s52
	v_lshl_add_u64 v[152:153], v[152:153], 0, s[22:23]
	s_mov_b32 m0, s50
	ds_read_b128 v[190:193], v159 offset:49152
	ds_read_b128 v[194:197], v159 offset:50176
	ds_read_b128 v[198:201], v159 offset:51200
	ds_read_b128 v[202:205], v159 offset:52224
	ds_read_b128 v[206:209], v159 offset:53248
	ds_read_b128 v[210:213], v159 offset:54272
	ds_read_b128 v[214:217], v159 offset:55296
	ds_read_b128 v[218:221], v159 offset:56320
	global_load_lds_dwordx4 v[152:153], off
	s_add_i32 m0, s50, 0x2000
	s_add_u32 s48, s48, 0x80080
	v_lshl_add_u64 v[152:153], v[222:223], 0, s[22:23]
	s_addc_u32 s49, s49, 0
	s_add_i32 s50, s74, s52
	global_load_lds_dwordx4 v[152:153], off
	v_lshl_add_u64 v[152:153], s[48:49], 0, v[130:131]
	s_mov_b32 m0, s50
	s_nop 0
	global_load_lds_dwordx4 v[152:153], off
	v_lshl_add_u64 v[152:153], s[48:49], 0, v[134:135]
	s_add_i32 m0, s50, 0x2000
	s_nop 0
	global_load_lds_dwordx4 v[152:153], off
	v_lshl_add_u64 v[152:153], v[224:225], 0, s[22:23]
	s_mov_b32 m0, s57
	s_nop 0
	global_load_lds_dwordx4 v[152:153], off
	v_lshl_add_u64 v[152:153], v[226:227], 0, s[22:23]
	s_mov_b32 m0, s58
	s_nop 0
	global_load_lds_dwordx4 v[152:153], off
	s_waitcnt vmcnt(8)
	s_waitcnt lgkmcnt(0)
	s_setprio 0
	s_barrier
	v_mfma_f32_16x16x32_bf16 v[60:63], v[148:151], v[190:193], v[60:63]
	v_mfma_f32_16x16x32_bf16 v[56:59], v[166:169], v[190:193], v[56:59]
	v_mfma_f32_16x16x32_bf16 v[44:47], v[148:151], v[198:201], v[44:47]
	v_mfma_f32_16x16x32_bf16 v[40:43], v[166:169], v[198:201], v[40:43]
	v_mfma_f32_16x16x32_bf16 v[28:31], v[148:151], v[206:209], v[28:31]
	v_mfma_f32_16x16x32_bf16 v[24:27], v[166:169], v[206:209], v[24:27]
	v_mfma_f32_16x16x32_bf16 v[12:15], v[148:151], v[214:217], v[12:15]
	v_mfma_f32_16x16x32_bf16 v[8:11], v[166:169], v[214:217], v[8:11]
	v_mfma_f32_16x16x32_bf16 v[60:63], v[162:165], v[194:197], v[60:63]
	v_mfma_f32_16x16x32_bf16 v[56:59], v[170:173], v[194:197], v[56:59]
	v_mfma_f32_16x16x32_bf16 v[44:47], v[162:165], v[202:205], v[44:47]
	v_mfma_f32_16x16x32_bf16 v[40:43], v[170:173], v[202:205], v[40:43]
	v_mfma_f32_16x16x32_bf16 v[28:31], v[162:165], v[210:213], v[28:31]
	v_mfma_f32_16x16x32_bf16 v[24:27], v[170:173], v[210:213], v[24:27]
	v_mfma_f32_16x16x32_bf16 v[12:15], v[162:165], v[218:221], v[12:15]
	v_mfma_f32_16x16x32_bf16 v[8:11], v[170:173], v[218:221], v[8:11]
	v_mfma_f32_16x16x32_bf16 v[52:55], v[174:177], v[190:193], v[52:55]
	v_mfma_f32_16x16x32_bf16 v[48:51], v[182:185], v[190:193], v[48:51]
	v_mfma_f32_16x16x32_bf16 v[36:39], v[174:177], v[198:201], v[36:39]
	v_mfma_f32_16x16x32_bf16 v[32:35], v[182:185], v[198:201], v[32:35]
	v_mfma_f32_16x16x32_bf16 v[20:23], v[174:177], v[206:209], v[20:23]
	v_mfma_f32_16x16x32_bf16 v[16:19], v[182:185], v[206:209], v[16:19]
	v_mfma_f32_16x16x32_bf16 v[4:7], v[174:177], v[214:217], v[4:7]
	v_mfma_f32_16x16x32_bf16 v[0:3], v[182:185], v[214:217], v[0:3]
	v_mfma_f32_16x16x32_bf16 v[52:55], v[178:181], v[194:197], v[52:55]
	v_mfma_f32_16x16x32_bf16 v[48:51], v[186:189], v[194:197], v[48:51]
	v_mfma_f32_16x16x32_bf16 v[36:39], v[178:181], v[202:205], v[36:39]
	v_mfma_f32_16x16x32_bf16 v[32:35], v[186:189], v[202:205], v[32:35]
	v_mfma_f32_16x16x32_bf16 v[20:23], v[178:181], v[210:213], v[20:23]
	v_mfma_f32_16x16x32_bf16 v[16:19], v[186:189], v[210:213], v[16:19]
	v_mfma_f32_16x16x32_bf16 v[4:7], v[178:181], v[218:221], v[4:7]
	v_mfma_f32_16x16x32_bf16 v[0:3], v[186:189], v[218:221], v[0:3]
	s_barrier
	s_setprio 1
	s_add_i32 s72, s72, 2
	s_add_u32 s70, s70, 0x100
	s_addc_u32 s71, s71, 0
	s_add_u32 s46, s46, 0x100
	s_addc_u32 s47, s47, 0
	s_cmp_gt_u32 s72, 29
	s_cbranch_scc0 .LBB0_178
	s_and_b64 vcc, exec, s[24:25]
	s_cbranch_vccz .LBB0_181
	s_barrier

.LBB0_337:
	ds_read_b128 v[144:147], v151
	ds_read_b128 v[156:159], v151 offset:1024
	ds_read_b128 v[160:163], v151 offset:2048
	ds_read_b128 v[164:167], v151 offset:3072
	ds_read_b128 v[168:171], v152
	ds_read_b128 v[172:175], v152 offset:1024
	ds_read_b128 v[176:179], v152 offset:2048
	ds_read_b128 v[180:183], v152 offset:3072
	s_add_u32 s50, s48, 0xfff80080
	s_addc_u32 s51, s49, -1
	s_cmp_eq_u32 s75, 28
	s_cselect_b32 s53, s31, s51
	s_cselect_b32 s52, s47, s50
	s_cselect_b32 s51, s27, s74
	s_cselect_b32 s50, s71, s72
	v_lshl_add_u64 v[216:217], s[48:49], 0, v[138:139]
	s_add_i32 m0, s57, 0xc000
	ds_read_b128 v[184:187], v153
	ds_read_b128 v[188:191], v153 offset:1024
	ds_read_b128 v[192:195], v153 offset:2048
	ds_read_b128 v[196:199], v153 offset:3072
	ds_read_b128 v[200:203], v153 offset:4096
	ds_read_b128 v[204:207], v153 offset:5120
	ds_read_b128 v[208:211], v153 offset:6144
	ds_read_b128 v[212:215], v153 offset:7168
	global_load_lds_dwordx4 v[216:217], off
	v_lshl_add_u64 v[216:217], s[48:49], 0, v[136:137]
	s_add_i32 m0, s57, 0xe000
	s_nop 0
	global_load_lds_dwordx4 v[216:217], off
	s_waitcnt vmcnt(8)
	s_waitcnt lgkmcnt(0)
	s_setprio 0
	s_barrier
	v_mfma_f32_16x16x32_bf16 v[124:127], v[144:147], v[184:187], v[124:127]
	v_mfma_f32_16x16x32_bf16 v[120:123], v[160:163], v[184:187], v[120:123]
	v_mfma_f32_16x16x32_bf16 v[108:111], v[144:147], v[192:195], v[108:111]
	v_mfma_f32_16x16x32_bf16 v[104:107], v[160:163], v[192:195], v[104:107]
	v_mfma_f32_16x16x32_bf16 v[92:95], v[144:147], v[200:203], v[92:95]
	v_mfma_f32_16x16x32_bf16 v[88:91], v[160:163], v[200:203], v[88:91]
	v_mfma_f32_16x16x32_bf16 v[76:79], v[144:147], v[208:211], v[76:79]
	v_mfma_f32_16x16x32_bf16 v[72:75], v[160:163], v[208:211], v[72:75]
	v_mfma_f32_16x16x32_bf16 v[124:127], v[156:159], v[188:191], v[124:127]
	v_mfma_f32_16x16x32_bf16 v[120:123], v[164:167], v[188:191], v[120:123]
	v_mfma_f32_16x16x32_bf16 v[108:111], v[156:159], v[196:199], v[108:111]
	v_mfma_f32_16x16x32_bf16 v[104:107], v[164:167], v[196:199], v[104:107]
	v_mfma_f32_16x16x32_bf16 v[92:95], v[156:159], v[204:207], v[92:95]
	v_mfma_f32_16x16x32_bf16 v[88:91], v[164:167], v[204:207], v[88:91]
	v_mfma_f32_16x16x32_bf16 v[76:79], v[156:159], v[212:215], v[76:79]
	v_mfma_f32_16x16x32_bf16 v[72:75], v[164:167], v[212:215], v[72:75]
	v_mfma_f32_16x16x32_bf16 v[116:119], v[168:171], v[184:187], v[116:119]
	v_mfma_f32_16x16x32_bf16 v[112:115], v[176:179], v[184:187], v[112:115]
	v_mfma_f32_16x16x32_bf16 v[100:103], v[168:171], v[192:195], v[100:103]
	v_mfma_f32_16x16x32_bf16 v[96:99], v[176:179], v[192:195], v[96:99]
	v_mfma_f32_16x16x32_bf16 v[84:87], v[168:171], v[200:203], v[84:87]
	v_mfma_f32_16x16x32_bf16 v[80:83], v[176:179], v[200:203], v[80:83]
	v_mfma_f32_16x16x32_bf16 v[68:71], v[168:171], v[208:211], v[68:71]
	v_mfma_f32_16x16x32_bf16 v[64:67], v[176:179], v[208:211], v[64:67]
	v_mfma_f32_16x16x32_bf16 v[116:119], v[172:175], v[188:191], v[116:119]
	v_mfma_f32_16x16x32_bf16 v[112:115], v[180:183], v[188:191], v[112:115]
	v_mfma_f32_16x16x32_bf16 v[100:103], v[172:175], v[196:199], v[100:103]
	v_mfma_f32_16x16x32_bf16 v[96:99], v[180:183], v[196:199], v[96:99]
	v_mfma_f32_16x16x32_bf16 v[84:87], v[172:175], v[204:207], v[84:87]
	v_mfma_f32_16x16x32_bf16 v[80:83], v[180:183], v[204:207], v[80:83]
	v_mfma_f32_16x16x32_bf16 v[68:71], v[172:175], v[212:215], v[68:71]
	v_mfma_f32_16x16x32_bf16 v[64:67], v[180:183], v[212:215], v[64:67]
	s_barrier
	s_setprio 1
	s_add_i32 s76, s66, s56
	v_lshl_add_u64 v[216:217], s[50:51], 0, v[130:131]
	s_mov_b32 m0, s76
	ds_read_b128 v[184:187], v153 offset:16384
	ds_read_b128 v[188:191], v153 offset:17408
	ds_read_b128 v[192:195], v153 offset:18432
	ds_read_b128 v[196:199], v153 offset:19456
	ds_read_b128 v[200:203], v153 offset:20480
	ds_read_b128 v[204:207], v153 offset:21504
	ds_read_b128 v[208:211], v153 offset:22528
	ds_read_b128 v[212:215], v153 offset:23552
	global_load_lds_dwordx4 v[216:217], off
	s_add_i32 m0, s76, 0x2000
	s_add_u32 s76, s50, 0x80000
	v_lshl_add_u64 v[218:219], s[50:51], 0, v[134:135]
	s_addc_u32 s77, s51, 0
	s_add_i32 s78, s67, s56
	global_load_lds_dwordx4 v[218:219], off
	v_lshl_add_u64 v[220:221], s[76:77], 0, v[130:131]
	s_mov_b32 m0, s78
	v_lshl_add_u64 v[222:223], s[52:53], 0, v[132:133]
	global_load_lds_dwordx4 v[220:221], off
	v_lshl_add_u64 v[220:221], s[76:77], 0, v[134:135]
	s_add_i32 m0, s78, 0x2000
	s_nop 0
	global_load_lds_dwordx4 v[220:221], off
	v_lshl_add_u64 v[220:221], s[52:53], 0, v[128:129]
	s_mov_b32 m0, s57
	s_nop 0
	global_load_lds_dwordx4 v[220:221], off
	s_mov_b32 m0, s58
	s_nop 0
	global_load_lds_dwordx4 v[222:223], off
	s_waitcnt vmcnt(8)
	s_waitcnt lgkmcnt(0)
	s_setprio 0
	s_barrier
	v_mfma_f32_16x16x32_bf16 v[60:63], v[144:147], v[184:187], v[60:63]
	v_mfma_f32_16x16x32_bf16 v[56:59], v[160:163], v[184:187], v[56:59]
	v_mfma_f32_16x16x32_bf16 v[44:47], v[144:147], v[192:195], v[44:47]
	v_mfma_f32_16x16x32_bf16 v[40:43], v[160:163], v[192:195], v[40:43]
	v_mfma_f32_16x16x32_bf16 v[28:31], v[144:147], v[200:203], v[28:31]
	v_mfma_f32_16x16x32_bf16 v[24:27], v[160:163], v[200:203], v[24:27]
	v_mfma_f32_16x16x32_bf16 v[12:15], v[144:147], v[208:211], v[12:15]
	v_mfma_f32_16x16x32_bf16 v[8:11], v[160:163], v[208:211], v[8:11]
	v_mfma_f32_16x16x32_bf16 v[60:63], v[156:159], v[188:191], v[60:63]
	v_mfma_f32_16x16x32_bf16 v[56:59], v[164:167], v[188:191], v[56:59]
	v_mfma_f32_16x16x32_bf16 v[44:47], v[156:159], v[196:199], v[44:47]
	v_mfma_f32_16x16x32_bf16 v[40:43], v[164:167], v[196:199], v[40:43]
	v_mfma_f32_16x16x32_bf16 v[28:31], v[156:159], v[204:207], v[28:31]
	v_mfma_f32_16x16x32_bf16 v[24:27], v[164:167], v[204:207], v[24:27]
	v_mfma_f32_16x16x32_bf16 v[12:15], v[156:159], v[212:215], v[12:15]
	v_mfma_f32_16x16x32_bf16 v[8:11], v[164:167], v[212:215], v[8:11]
	v_mfma_f32_16x16x32_bf16 v[52:55], v[168:171], v[184:187], v[52:55]
	v_mfma_f32_16x16x32_bf16 v[48:51], v[176:179], v[184:187], v[48:51]
	v_mfma_f32_16x16x32_bf16 v[36:39], v[168:171], v[192:195], v[36:39]
	v_mfma_f32_16x16x32_bf16 v[32:35], v[176:179], v[192:195], v[32:35]
	v_mfma_f32_16x16x32_bf16 v[20:23], v[168:171], v[200:203], v[20:23]
	v_mfma_f32_16x16x32_bf16 v[16:19], v[176:179], v[200:203], v[16:19]
	v_mfma_f32_16x16x32_bf16 v[4:7], v[168:171], v[208:211], v[4:7]
	v_mfma_f32_16x16x32_bf16 v[0:3], v[176:179], v[208:211], v[0:3]
	v_mfma_f32_16x16x32_bf16 v[52:55], v[172:175], v[188:191], v[52:55]
	v_mfma_f32_16x16x32_bf16 v[48:51], v[180:183], v[188:191], v[48:51]
	v_mfma_f32_16x16x32_bf16 v[36:39], v[172:175], v[196:199], v[36:39]
	v_mfma_f32_16x16x32_bf16 v[32:35], v[180:183], v[196:199], v[32:35]
	v_mfma_f32_16x16x32_bf16 v[20:23], v[172:175], v[204:207], v[20:23]
	v_mfma_f32_16x16x32_bf16 v[16:19], v[180:183], v[204:207], v[16:19]
	v_mfma_f32_16x16x32_bf16 v[4:7], v[172:175], v[212:215], v[4:7]
	v_mfma_f32_16x16x32_bf16 v[0:3], v[180:183], v[212:215], v[0:3]
	s_barrier
	s_setprio 1
	s_add_i32 s76, 0, 0x18000
	v_add_u32_e32 v155, s76, v149
	s_add_i32 s77, 0, 0x1c000
	ds_read_b128 v[144:147], v155
	ds_read_b128 v[156:159], v155 offset:1024
	ds_read_b128 v[160:163], v155 offset:2048
	ds_read_b128 v[164:167], v155 offset:3072
	v_add_u32_e32 v155, s77, v149
	ds_read_b128 v[168:171], v155
	ds_read_b128 v[172:175], v155 offset:1024
	ds_read_b128 v[176:179], v155 offset:2048
	ds_read_b128 v[180:183], v155 offset:3072
	s_add_u32 s52, s52, 0x80000
	s_addc_u32 s53, s53, 0
	s_mov_b32 m0, s59
	v_lshl_add_u64 v[224:225], s[52:53], 0, v[128:129]
	ds_read_b128 v[184:187], v153 offset:32768
	ds_read_b128 v[188:191], v153 offset:33792
	ds_read_b128 v[192:195], v153 offset:34816
	ds_read_b128 v[196:199], v153 offset:35840
	ds_read_b128 v[200:203], v153 offset:36864
	ds_read_b128 v[204:207], v153 offset:37888
	ds_read_b128 v[208:211], v153 offset:38912
	ds_read_b128 v[212:215], v153 offset:39936
	global_load_lds_dwordx4 v[224:225], off
	v_lshl_add_u64 v[224:225], s[52:53], 0, v[132:133]
	s_mov_b32 m0, s60
	s_nop 0
	global_load_lds_dwordx4 v[224:225], off
	s_waitcnt vmcnt(8)
	s_waitcnt lgkmcnt(0)
	s_setprio 0
	s_barrier
	v_mfma_f32_16x16x32_bf16 v[124:127], v[144:147], v[184:187], v[124:127]
	v_mfma_f32_16x16x32_bf16 v[120:123], v[160:163], v[184:187], v[120:123]
	v_mfma_f32_16x16x32_bf16 v[108:111], v[144:147], v[192:195], v[108:111]
	v_mfma_f32_16x16x32_bf16 v[104:107], v[160:163], v[192:195], v[104:107]
	v_mfma_f32_16x16x32_bf16 v[92:95], v[144:147], v[200:203], v[92:95]
	v_mfma_f32_16x16x32_bf16 v[88:91], v[160:163], v[200:203], v[88:91]
	v_mfma_f32_16x16x32_bf16 v[76:79], v[144:147], v[208:211], v[76:79]
	v_mfma_f32_16x16x32_bf16 v[72:75], v[160:163], v[208:211], v[72:75]
	v_mfma_f32_16x16x32_bf16 v[124:127], v[156:159], v[188:191], v[124:127]
	v_mfma_f32_16x16x32_bf16 v[120:123], v[164:167], v[188:191], v[120:123]
	v_mfma_f32_16x16x32_bf16 v[108:111], v[156:159], v[196:199], v[108:111]
	v_mfma_f32_16x16x32_bf16 v[104:107], v[164:167], v[196:199], v[104:107]
	v_mfma_f32_16x16x32_bf16 v[92:95], v[156:159], v[204:207], v[92:95]
	v_mfma_f32_16x16x32_bf16 v[88:91], v[164:167], v[204:207], v[88:91]
	v_mfma_f32_16x16x32_bf16 v[76:79], v[156:159], v[212:215], v[76:79]
	v_mfma_f32_16x16x32_bf16 v[72:75], v[164:167], v[212:215], v[72:75]
	v_mfma_f32_16x16x32_bf16 v[116:119], v[168:171], v[184:187], v[116:119]
	v_mfma_f32_16x16x32_bf16 v[112:115], v[176:179], v[184:187], v[112:115]
	v_mfma_f32_16x16x32_bf16 v[100:103], v[168:171], v[192:195], v[100:103]
	v_mfma_f32_16x16x32_bf16 v[96:99], v[176:179], v[192:195], v[96:99]
	v_mfma_f32_16x16x32_bf16 v[84:87], v[168:171], v[200:203], v[84:87]
	v_mfma_f32_16x16x32_bf16 v[80:83], v[176:179], v[200:203], v[80:83]
	v_mfma_f32_16x16x32_bf16 v[68:71], v[168:171], v[208:211], v[68:71]
	v_mfma_f32_16x16x32_bf16 v[64:67], v[176:179], v[208:211], v[64:67]
	v_mfma_f32_16x16x32_bf16 v[116:119], v[172:175], v[188:191], v[116:119]
	v_mfma_f32_16x16x32_bf16 v[112:115], v[180:183], v[188:191], v[112:115]
	v_mfma_f32_16x16x32_bf16 v[100:103], v[172:175], v[196:199], v[100:103]
	v_mfma_f32_16x16x32_bf16 v[96:99], v[180:183], v[196:199], v[96:99]
	v_mfma_f32_16x16x32_bf16 v[84:87], v[172:175], v[204:207], v[84:87]
	v_mfma_f32_16x16x32_bf16 v[80:83], v[180:183], v[204:207], v[80:83]
	v_mfma_f32_16x16x32_bf16 v[68:71], v[172:175], v[212:215], v[68:71]
	v_mfma_f32_16x16x32_bf16 v[64:67], v[180:183], v[212:215], v[64:67]
	s_barrier
	s_setprio 1
	s_add_i32 s52, s76, s56
	v_lshl_add_u64 v[216:217], v[216:217], 0, s[22:23]
	s_mov_b32 m0, s52
	ds_read_b128 v[184:187], v153 offset:49152
	ds_read_b128 v[188:191], v153 offset:50176
	ds_read_b128 v[192:195], v153 offset:51200
	ds_read_b128 v[196:199], v153 offset:52224
	ds_read_b128 v[200:203], v153 offset:53248
	ds_read_b128 v[204:207], v153 offset:54272
	ds_read_b128 v[208:211], v153 offset:55296
	ds_read_b128 v[212:215], v153 offset:56320
	global_load_lds_dwordx4 v[216:217], off
	s_add_i32 m0, s52, 0x2000
	s_add_u32 s50, s50, 0x80080
	v_lshl_add_u64 v[216:217], v[218:219], 0, s[22:23]
	s_addc_u32 s51, s51, 0
	s_add_i32 s52, s77, s56
	global_load_lds_dwordx4 v[216:217], off
	v_lshl_add_u64 v[216:217], s[50:51], 0, v[130:131]
	s_mov_b32 m0, s52
	s_nop 0
	global_load_lds_dwordx4 v[216:217], off
	v_lshl_add_u64 v[216:217], s[50:51], 0, v[134:135]
	s_add_i32 m0, s52, 0x2000
	s_nop 0
	global_load_lds_dwordx4 v[216:217], off
	v_lshl_add_u64 v[216:217], v[220:221], 0, s[22:23]
	s_mov_b32 m0, s62
	s_nop 0
	global_load_lds_dwordx4 v[216:217], off
	v_lshl_add_u64 v[216:217], v[222:223], 0, s[22:23]
	s_mov_b32 m0, s63
	s_nop 0
	global_load_lds_dwordx4 v[216:217], off
	s_waitcnt vmcnt(8)
	s_waitcnt lgkmcnt(0)
	s_setprio 0
	s_barrier
	v_mfma_f32_16x16x32_bf16 v[60:63], v[144:147], v[184:187], v[60:63]
	v_mfma_f32_16x16x32_bf16 v[56:59], v[160:163], v[184:187], v[56:59]
	v_mfma_f32_16x16x32_bf16 v[44:47], v[144:147], v[192:195], v[44:47]
	v_mfma_f32_16x16x32_bf16 v[40:43], v[160:163], v[192:195], v[40:43]
	v_mfma_f32_16x16x32_bf16 v[28:31], v[144:147], v[200:203], v[28:31]
	v_mfma_f32_16x16x32_bf16 v[24:27], v[160:163], v[200:203], v[24:27]
	v_mfma_f32_16x16x32_bf16 v[12:15], v[144:147], v[208:211], v[12:15]
	v_mfma_f32_16x16x32_bf16 v[8:11], v[160:163], v[208:211], v[8:11]
	v_mfma_f32_16x16x32_bf16 v[60:63], v[156:159], v[188:191], v[60:63]
	v_mfma_f32_16x16x32_bf16 v[56:59], v[164:167], v[188:191], v[56:59]
	v_mfma_f32_16x16x32_bf16 v[44:47], v[156:159], v[196:199], v[44:47]
	v_mfma_f32_16x16x32_bf16 v[40:43], v[164:167], v[196:199], v[40:43]
	v_mfma_f32_16x16x32_bf16 v[28:31], v[156:159], v[204:207], v[28:31]
	v_mfma_f32_16x16x32_bf16 v[24:27], v[164:167], v[204:207], v[24:27]
	v_mfma_f32_16x16x32_bf16 v[12:15], v[156:159], v[212:215], v[12:15]
	v_mfma_f32_16x16x32_bf16 v[8:11], v[164:167], v[212:215], v[8:11]
	v_mfma_f32_16x16x32_bf16 v[52:55], v[168:171], v[184:187], v[52:55]
	v_mfma_f32_16x16x32_bf16 v[48:51], v[176:179], v[184:187], v[48:51]
	v_mfma_f32_16x16x32_bf16 v[36:39], v[168:171], v[192:195], v[36:39]
	v_mfma_f32_16x16x32_bf16 v[32:35], v[176:179], v[192:195], v[32:35]
	v_mfma_f32_16x16x32_bf16 v[20:23], v[168:171], v[200:203], v[20:23]
	v_mfma_f32_16x16x32_bf16 v[16:19], v[176:179], v[200:203], v[16:19]
	v_mfma_f32_16x16x32_bf16 v[4:7], v[168:171], v[208:211], v[4:7]
	v_mfma_f32_16x16x32_bf16 v[0:3], v[176:179], v[208:211], v[0:3]
	v_mfma_f32_16x16x32_bf16 v[52:55], v[172:175], v[188:191], v[52:55]
	v_mfma_f32_16x16x32_bf16 v[48:51], v[180:183], v[188:191], v[48:51]
	v_mfma_f32_16x16x32_bf16 v[36:39], v[172:175], v[196:199], v[36:39]
	v_mfma_f32_16x16x32_bf16 v[32:35], v[180:183], v[196:199], v[32:35]
	v_mfma_f32_16x16x32_bf16 v[20:23], v[172:175], v[204:207], v[20:23]
	v_mfma_f32_16x16x32_bf16 v[16:19], v[180:183], v[204:207], v[16:19]
	v_mfma_f32_16x16x32_bf16 v[4:7], v[172:175], v[212:215], v[4:7]
	v_mfma_f32_16x16x32_bf16 v[0:3], v[180:183], v[212:215], v[0:3]
	s_barrier
	s_setprio 1
	s_add_i32 s75, s75, 2
	s_add_u32 s72, s72, 0x100
	s_addc_u32 s74, s74, 0
	s_add_u32 s48, s48, 0x100
	s_addc_u32 s49, s49, 0
	s_cmp_gt_u32 s75, 29
	s_cbranch_scc0 .LBB0_337
	s_and_b64 vcc, exec, s[24:25]
	s_cbranch_vccz .LBB0_340
	s_barrier

.LBB0_435:
	ds_read_b128 v[148:151], v222
	ds_read_b128 v[152:155], v222 offset:1024
	ds_read_b128 v[156:159], v222 offset:2048
	ds_read_b128 v[160:163], v222 offset:3072
	ds_read_b128 v[132:135], v223
	ds_read_b128 v[136:139], v223 offset:1024
	ds_read_b128 v[140:143], v223 offset:2048
	ds_read_b128 v[144:147], v223 offset:3072
	s_add_u32 s10, s54, 0xfff80080
	s_addc_u32 s11, s55, -1
	s_cmp_eq_u32 s84, 28
	s_cselect_b32 s59, s25, s11
	s_cselect_b32 s58, s46, s10
	s_cselect_b32 s57, s23, s83
	s_cselect_b32 s56, s47, s82
	v_lshl_add_u64 v[2:3], s[54:55], 0, v[208:209]
	s_add_i32 m0, s37, 0xc000
	s_waitcnt lgkmcnt(0)
	ds_read_b128 v[164:167], v224
	ds_read_b128 v[168:171], v224 offset:1024
	ds_read_b128 v[172:175], v224 offset:2048
	ds_read_b128 v[176:179], v224 offset:3072
	ds_read_b128 v[180:183], v224 offset:4096
	ds_read_b128 v[184:187], v224 offset:5120
	ds_read_b128 v[188:191], v224 offset:6144
	ds_read_b128 v[192:195], v224 offset:7168
	global_load_lds_dwordx4 v[2:3], off
	v_lshl_add_u64 v[2:3], s[54:55], 0, v[206:207]
	s_add_i32 m0, s37, 0xe000
	s_nop 0
	global_load_lds_dwordx4 v[2:3], off
	s_waitcnt vmcnt(8)
	s_waitcnt lgkmcnt(0)
	s_setprio 0
	s_barrier
	v_mfma_f32_16x16x32_bf16 v[120:123], v[148:151], v[164:167], v[120:123]
	v_mfma_f32_16x16x32_bf16 v[116:119], v[156:159], v[164:167], v[116:119]
	v_mfma_f32_16x16x32_bf16 v[104:107], v[148:151], v[172:175], v[104:107]
	v_mfma_f32_16x16x32_bf16 v[100:103], v[156:159], v[172:175], v[100:103]
	v_mfma_f32_16x16x32_bf16 v[88:91], v[148:151], v[180:183], v[88:91]
	v_mfma_f32_16x16x32_bf16 v[84:87], v[156:159], v[180:183], v[84:87]
	v_mfma_f32_16x16x32_bf16 v[76:79], v[148:151], v[188:191], v[76:79]
	v_mfma_f32_16x16x32_bf16 v[72:75], v[156:159], v[188:191], v[72:75]
	v_mfma_f32_16x16x32_bf16 v[120:123], v[152:155], v[168:171], v[120:123]
	v_mfma_f32_16x16x32_bf16 v[116:119], v[160:163], v[168:171], v[116:119]
	v_mfma_f32_16x16x32_bf16 v[104:107], v[152:155], v[176:179], v[104:107]
	v_mfma_f32_16x16x32_bf16 v[100:103], v[160:163], v[176:179], v[100:103]
	v_mfma_f32_16x16x32_bf16 v[88:91], v[152:155], v[184:187], v[88:91]
	v_mfma_f32_16x16x32_bf16 v[84:87], v[160:163], v[184:187], v[84:87]
	v_mfma_f32_16x16x32_bf16 v[76:79], v[152:155], v[192:195], v[76:79]
	v_mfma_f32_16x16x32_bf16 v[72:75], v[160:163], v[192:195], v[72:75]
	v_mfma_f32_16x16x32_bf16 v[128:131], v[132:135], v[164:167], v[128:131]
	v_mfma_f32_16x16x32_bf16 v[124:127], v[140:143], v[164:167], v[124:127]
	v_mfma_f32_16x16x32_bf16 v[112:115], v[132:135], v[172:175], v[112:115]
	v_mfma_f32_16x16x32_bf16 v[108:111], v[140:143], v[172:175], v[108:111]
	v_mfma_f32_16x16x32_bf16 v[96:99], v[132:135], v[180:183], v[96:99]
	v_mfma_f32_16x16x32_bf16 v[92:95], v[140:143], v[180:183], v[92:95]
	v_mfma_f32_16x16x32_bf16 v[80:83], v[132:135], v[188:191], v[80:83]
	v_mfma_f32_16x16x32_bf16 v[68:71], v[140:143], v[188:191], v[68:71]
	v_mfma_f32_16x16x32_bf16 v[128:131], v[136:139], v[168:171], v[128:131]
	v_mfma_f32_16x16x32_bf16 v[124:127], v[144:147], v[168:171], v[124:127]
	v_mfma_f32_16x16x32_bf16 v[112:115], v[136:139], v[176:179], v[112:115]
	v_mfma_f32_16x16x32_bf16 v[108:111], v[144:147], v[176:179], v[108:111]
	v_mfma_f32_16x16x32_bf16 v[96:99], v[136:139], v[184:187], v[96:99]
	v_mfma_f32_16x16x32_bf16 v[92:95], v[144:147], v[184:187], v[92:95]
	v_mfma_f32_16x16x32_bf16 v[80:83], v[136:139], v[192:195], v[80:83]
	v_mfma_f32_16x16x32_bf16 v[68:71], v[144:147], v[192:195], v[68:71]
	s_barrier
	s_setprio 1
	s_add_i32 s10, s67, s48
	v_lshl_add_u64 v[2:3], s[56:57], 0, v[198:199]
	s_mov_b32 m0, s10
	ds_read_b128 v[188:191], v224 offset:16384
	ds_read_b128 v[192:195], v224 offset:17408
	ds_read_b128 v[180:183], v224 offset:18432
	ds_read_b128 v[184:187], v224 offset:19456
	ds_read_b128 v[172:175], v224 offset:20480
	ds_read_b128 v[176:179], v224 offset:21504
	ds_read_b128 v[164:167], v224 offset:22528
	ds_read_b128 v[168:171], v224 offset:23552
	global_load_lds_dwordx4 v[2:3], off
	s_add_i32 m0, s10, 0x2000
	s_add_u32 s10, s56, 0x80000
	v_lshl_add_u64 v[212:213], s[56:57], 0, v[202:203]
	s_addc_u32 s11, s57, 0
	s_add_i32 s78, s70, s48
	global_load_lds_dwordx4 v[212:213], off
	v_lshl_add_u64 v[214:215], s[10:11], 0, v[198:199]
	s_mov_b32 m0, s78
	v_lshl_add_u64 v[216:217], s[58:59], 0, v[200:201]
	global_load_lds_dwordx4 v[214:215], off
	v_lshl_add_u64 v[214:215], s[10:11], 0, v[202:203]
	s_add_i32 m0, s78, 0x2000
	v_cmp_ne_u32_e64 s[10:11], 1, v227
	global_load_lds_dwordx4 v[214:215], off
	v_lshl_add_u64 v[214:215], s[58:59], 0, v[196:197]
	s_mov_b32 m0, s37
	s_andn2_b64 vcc, exec, s[52:53]
	global_load_lds_dwordx4 v[214:215], off
	s_mov_b32 m0, s60
	s_nop 0
	global_load_lds_dwordx4 v[216:217], off
	s_waitcnt vmcnt(8)
	s_waitcnt lgkmcnt(0)
	s_cbranch_vccnz .Lsegskip_0
	s_setprio 0
	s_barrier
	v_mfma_f32_16x16x32_bf16 v[56:59], v[148:151], v[188:191], v[56:59]
	v_mfma_f32_16x16x32_bf16 v[52:55], v[156:159], v[188:191], v[52:55]
	v_mfma_f32_16x16x32_bf16 v[40:43], v[148:151], v[180:183], v[40:43]
	v_mfma_f32_16x16x32_bf16 v[36:39], v[156:159], v[180:183], v[36:39]
	v_mfma_f32_16x16x32_bf16 v[24:27], v[148:151], v[172:175], v[24:27]
	v_mfma_f32_16x16x32_bf16 v[20:23], v[156:159], v[172:175], v[20:23]
	v_mfma_f32_16x16x32_bf16 v[8:11], v[148:151], v[164:167], v[8:11]
	v_mfma_f32_16x16x32_bf16 v[4:7], v[156:159], v[164:167], v[4:7]
	v_mfma_f32_16x16x32_bf16 v[56:59], v[152:155], v[192:195], v[56:59]
	v_mfma_f32_16x16x32_bf16 v[52:55], v[160:163], v[192:195], v[52:55]
	v_mfma_f32_16x16x32_bf16 v[40:43], v[152:155], v[184:187], v[40:43]
	v_mfma_f32_16x16x32_bf16 v[36:39], v[160:163], v[184:187], v[36:39]
	v_mfma_f32_16x16x32_bf16 v[24:27], v[152:155], v[176:179], v[24:27]
	v_mfma_f32_16x16x32_bf16 v[20:23], v[160:163], v[176:179], v[20:23]
	v_mfma_f32_16x16x32_bf16 v[8:11], v[152:155], v[168:171], v[8:11]
	v_mfma_f32_16x16x32_bf16 v[4:7], v[160:163], v[168:171], v[4:7]
	v_mfma_f32_16x16x32_bf16 v[64:67], v[132:135], v[188:191], v[64:67]
	v_mfma_f32_16x16x32_bf16 v[60:63], v[140:143], v[188:191], v[60:63]
	v_mfma_f32_16x16x32_bf16 v[48:51], v[132:135], v[180:183], v[48:51]
	v_mfma_f32_16x16x32_bf16 v[44:47], v[140:143], v[180:183], v[44:47]
	v_mfma_f32_16x16x32_bf16 v[32:35], v[132:135], v[172:175], v[32:35]
	v_mfma_f32_16x16x32_bf16 v[28:31], v[140:143], v[172:175], v[28:31]
	v_mfma_f32_16x16x32_bf16 v[16:19], v[132:135], v[164:167], v[16:19]
	v_mfma_f32_16x16x32_bf16 v[12:15], v[140:143], v[164:167], v[12:15]
	v_mfma_f32_16x16x32_bf16 v[64:67], v[136:139], v[192:195], v[64:67]
	v_mfma_f32_16x16x32_bf16 v[60:63], v[144:147], v[192:195], v[60:63]
	v_mfma_f32_16x16x32_bf16 v[48:51], v[136:139], v[184:187], v[48:51]
	v_mfma_f32_16x16x32_bf16 v[44:47], v[144:147], v[184:187], v[44:47]
	v_mfma_f32_16x16x32_bf16 v[32:35], v[136:139], v[176:179], v[32:35]
	v_mfma_f32_16x16x32_bf16 v[28:31], v[144:147], v[176:179], v[28:31]
	v_mfma_f32_16x16x32_bf16 v[16:19], v[136:139], v[168:171], v[16:19]
	v_mfma_f32_16x16x32_bf16 v[12:15], v[144:147], v[168:171], v[12:15]
.LBB0_437:
	s_barrier
	s_setprio 1
	s_add_i32 s78, 0, 0x18000
	v_add_u32_e32 v1, s78, v220
	s_add_i32 s79, 0, 0x1c000
	ds_read_b128 v[148:151], v1
	ds_read_b128 v[152:155], v1 offset:1024
	ds_read_b128 v[156:159], v1 offset:2048
	ds_read_b128 v[160:163], v1 offset:3072
	v_add_u32_e32 v1, s79, v220
	ds_read_b128 v[132:135], v1
	ds_read_b128 v[136:139], v1 offset:1024
	ds_read_b128 v[140:143], v1 offset:2048
	ds_read_b128 v[144:147], v1 offset:3072
	s_add_u32 s58, s58, 0x80000
	s_addc_u32 s59, s59, 0
	s_mov_b32 m0, s61
	v_lshl_add_u64 v[228:229], s[58:59], 0, v[196:197]
	s_waitcnt lgkmcnt(0)
	ds_read_b128 v[164:167], v224 offset:32768
	ds_read_b128 v[168:171], v224 offset:33792
	ds_read_b128 v[172:175], v224 offset:34816
	ds_read_b128 v[176:179], v224 offset:35840
	ds_read_b128 v[180:183], v224 offset:36864
	ds_read_b128 v[184:187], v224 offset:37888
	ds_read_b128 v[188:191], v224 offset:38912
	ds_read_b128 v[192:195], v224 offset:39936
	global_load_lds_dwordx4 v[228:229], off
	v_lshl_add_u64 v[228:229], s[58:59], 0, v[200:201]
	s_mov_b32 m0, s62
	s_nop 0
	global_load_lds_dwordx4 v[228:229], off
	s_waitcnt vmcnt(8)
	s_waitcnt lgkmcnt(0)
	s_setprio 0
	s_barrier
	v_mfma_f32_16x16x32_bf16 v[120:123], v[148:151], v[164:167], v[120:123]
	v_mfma_f32_16x16x32_bf16 v[116:119], v[156:159], v[164:167], v[116:119]
	v_mfma_f32_16x16x32_bf16 v[104:107], v[148:151], v[172:175], v[104:107]
	v_mfma_f32_16x16x32_bf16 v[100:103], v[156:159], v[172:175], v[100:103]
	v_mfma_f32_16x16x32_bf16 v[88:91], v[148:151], v[180:183], v[88:91]
	v_mfma_f32_16x16x32_bf16 v[84:87], v[156:159], v[180:183], v[84:87]
	v_mfma_f32_16x16x32_bf16 v[76:79], v[148:151], v[188:191], v[76:79]
	v_mfma_f32_16x16x32_bf16 v[72:75], v[156:159], v[188:191], v[72:75]
	v_mfma_f32_16x16x32_bf16 v[120:123], v[152:155], v[168:171], v[120:123]
	v_mfma_f32_16x16x32_bf16 v[116:119], v[160:163], v[168:171], v[116:119]
	v_mfma_f32_16x16x32_bf16 v[104:107], v[152:155], v[176:179], v[104:107]
	v_mfma_f32_16x16x32_bf16 v[100:103], v[160:163], v[176:179], v[100:103]
	v_mfma_f32_16x16x32_bf16 v[88:91], v[152:155], v[184:187], v[88:91]
	v_mfma_f32_16x16x32_bf16 v[84:87], v[160:163], v[184:187], v[84:87]
	v_mfma_f32_16x16x32_bf16 v[76:79], v[152:155], v[192:195], v[76:79]
	v_mfma_f32_16x16x32_bf16 v[72:75], v[160:163], v[192:195], v[72:75]
	v_mfma_f32_16x16x32_bf16 v[128:131], v[132:135], v[164:167], v[128:131]
	v_mfma_f32_16x16x32_bf16 v[124:127], v[140:143], v[164:167], v[124:127]
	v_mfma_f32_16x16x32_bf16 v[112:115], v[132:135], v[172:175], v[112:115]
	v_mfma_f32_16x16x32_bf16 v[108:111], v[140:143], v[172:175], v[108:111]
	v_mfma_f32_16x16x32_bf16 v[96:99], v[132:135], v[180:183], v[96:99]
	v_mfma_f32_16x16x32_bf16 v[92:95], v[140:143], v[180:183], v[92:95]
	v_mfma_f32_16x16x32_bf16 v[80:83], v[132:135], v[188:191], v[80:83]
	v_mfma_f32_16x16x32_bf16 v[68:71], v[140:143], v[188:191], v[68:71]
	v_mfma_f32_16x16x32_bf16 v[128:131], v[136:139], v[168:171], v[128:131]
	v_mfma_f32_16x16x32_bf16 v[124:127], v[144:147], v[168:171], v[124:127]
	v_mfma_f32_16x16x32_bf16 v[112:115], v[136:139], v[176:179], v[112:115]
	v_mfma_f32_16x16x32_bf16 v[108:111], v[144:147], v[176:179], v[108:111]
	v_mfma_f32_16x16x32_bf16 v[96:99], v[136:139], v[184:187], v[96:99]
	v_mfma_f32_16x16x32_bf16 v[92:95], v[144:147], v[184:187], v[92:95]
	v_mfma_f32_16x16x32_bf16 v[80:83], v[136:139], v[192:195], v[80:83]
	v_mfma_f32_16x16x32_bf16 v[68:71], v[144:147], v[192:195], v[68:71]
	s_barrier
	s_setprio 1
	s_add_i32 s58, s78, s48
	v_lshl_add_u64 v[2:3], v[2:3], 0, s[16:17]
	s_mov_b32 m0, s58
	ds_read_b128 v[188:191], v224 offset:49152
	ds_read_b128 v[192:195], v224 offset:50176
	ds_read_b128 v[180:183], v224 offset:51200
	ds_read_b128 v[184:187], v224 offset:52224
	ds_read_b128 v[172:175], v224 offset:53248
	ds_read_b128 v[176:179], v224 offset:54272
	ds_read_b128 v[164:167], v224 offset:55296
	ds_read_b128 v[168:171], v224 offset:56320
	global_load_lds_dwordx4 v[2:3], off
	s_add_i32 m0, s58, 0x2000
	s_add_u32 s56, s56, 0x80080
	v_lshl_add_u64 v[2:3], v[212:213], 0, s[16:17]
	s_addc_u32 s57, s57, 0
	s_add_i32 s58, s79, s48
	global_load_lds_dwordx4 v[2:3], off
	v_lshl_add_u64 v[2:3], s[56:57], 0, v[198:199]
	s_mov_b32 m0, s58
	s_and_b64 vcc, exec, s[10:11]
	global_load_lds_dwordx4 v[2:3], off
	v_lshl_add_u64 v[2:3], s[56:57], 0, v[202:203]
	s_add_i32 m0, s58, 0x2000
	s_nop 0
	global_load_lds_dwordx4 v[2:3], off
	v_lshl_add_u64 v[2:3], v[214:215], 0, s[16:17]
	s_mov_b32 m0, s63
	s_nop 0
	global_load_lds_dwordx4 v[2:3], off
	v_lshl_add_u64 v[2:3], v[216:217], 0, s[16:17]
	s_mov_b32 m0, s64
	s_nop 0
	global_load_lds_dwordx4 v[2:3], off
	s_waitcnt vmcnt(8)
	s_waitcnt lgkmcnt(0)
	s_cbranch_vccnz .Lsegskip_1
	s_setprio 0
	s_barrier
	v_mfma_f32_16x16x32_bf16 v[56:59], v[148:151], v[188:191], v[56:59]
	v_mfma_f32_16x16x32_bf16 v[52:55], v[156:159], v[188:191], v[52:55]
	v_mfma_f32_16x16x32_bf16 v[40:43], v[148:151], v[180:183], v[40:43]
	v_mfma_f32_16x16x32_bf16 v[36:39], v[156:159], v[180:183], v[36:39]
	v_mfma_f32_16x16x32_bf16 v[24:27], v[148:151], v[172:175], v[24:27]
	v_mfma_f32_16x16x32_bf16 v[20:23], v[156:159], v[172:175], v[20:23]
	v_mfma_f32_16x16x32_bf16 v[8:11], v[148:151], v[164:167], v[8:11]
	v_mfma_f32_16x16x32_bf16 v[2:5], v[156:159], v[164:167], v[4:7]
	v_mfma_f32_16x16x32_bf16 v[56:59], v[152:155], v[192:195], v[56:59]
	v_mfma_f32_16x16x32_bf16 v[52:55], v[160:163], v[192:195], v[52:55]
	v_mfma_f32_16x16x32_bf16 v[40:43], v[152:155], v[184:187], v[40:43]
	v_mfma_f32_16x16x32_bf16 v[36:39], v[160:163], v[184:187], v[36:39]
	v_mfma_f32_16x16x32_bf16 v[24:27], v[152:155], v[176:179], v[24:27]
	v_mfma_f32_16x16x32_bf16 v[20:23], v[160:163], v[176:179], v[20:23]
	v_mfma_f32_16x16x32_bf16 v[8:11], v[152:155], v[168:171], v[8:11]
	v_mfma_f32_16x16x32_bf16 v[4:7], v[160:163], v[168:171], v[2:5]
	v_mfma_f32_16x16x32_bf16 v[64:67], v[132:135], v[188:191], v[64:67]
	v_mfma_f32_16x16x32_bf16 v[60:63], v[140:143], v[188:191], v[60:63]
	v_mfma_f32_16x16x32_bf16 v[48:51], v[132:135], v[180:183], v[48:51]
	v_mfma_f32_16x16x32_bf16 v[44:47], v[140:143], v[180:183], v[44:47]
	v_mfma_f32_16x16x32_bf16 v[32:35], v[132:135], v[172:175], v[32:35]
	v_mfma_f32_16x16x32_bf16 v[28:31], v[140:143], v[172:175], v[28:31]
	v_mfma_f32_16x16x32_bf16 v[16:19], v[132:135], v[164:167], v[16:19]
	v_mfma_f32_16x16x32_bf16 v[12:15], v[140:143], v[164:167], v[12:15]
	v_mfma_f32_16x16x32_bf16 v[64:67], v[136:139], v[192:195], v[64:67]
	v_mfma_f32_16x16x32_bf16 v[60:63], v[144:147], v[192:195], v[60:63]
	v_mfma_f32_16x16x32_bf16 v[48:51], v[136:139], v[184:187], v[48:51]
	v_mfma_f32_16x16x32_bf16 v[44:47], v[144:147], v[184:187], v[44:47]
	v_mfma_f32_16x16x32_bf16 v[32:35], v[136:139], v[176:179], v[32:35]
	v_mfma_f32_16x16x32_bf16 v[28:31], v[144:147], v[176:179], v[28:31]
	v_mfma_f32_16x16x32_bf16 v[16:19], v[136:139], v[168:171], v[16:19]
	v_mfma_f32_16x16x32_bf16 v[12:15], v[144:147], v[168:171], v[12:15]
	s_barrier
	s_setprio 1
	s_branch .Lsegback_1

.LBB0_523:
	ds_read_b128 v[144:147], v151
	ds_read_b128 v[156:159], v151 offset:1024
	ds_read_b128 v[160:163], v151 offset:2048
	ds_read_b128 v[164:167], v151 offset:3072
	ds_read_b128 v[168:171], v152
	ds_read_b128 v[172:175], v152 offset:1024
	ds_read_b128 v[176:179], v152 offset:2048
	ds_read_b128 v[180:183], v152 offset:3072
	s_add_u32 s36, s34, 0x100
	s_addc_u32 s37, s35, 0
	s_cmpk_eq_i32 s66, 0x54
	s_cselect_b32 s55, s13, s37
	s_cselect_b32 s54, s12, s36
	s_cselect_b32 s53, s31, s47
	s_cselect_b32 s52, s30, s46
	v_lshl_add_u64 v[216:217], s[34:35], 0, v[138:139]
	s_add_i32 m0, s49, 0xc000
	ds_read_b128 v[184:187], v153
	ds_read_b128 v[188:191], v153 offset:1024
	ds_read_b128 v[192:195], v153 offset:2048
	ds_read_b128 v[196:199], v153 offset:3072
	ds_read_b128 v[200:203], v153 offset:4096
	ds_read_b128 v[204:207], v153 offset:5120
	ds_read_b128 v[208:211], v153 offset:6144
	ds_read_b128 v[212:215], v153 offset:7168
	global_load_lds_dwordx4 v[216:217], off
	v_lshl_add_u64 v[216:217], s[34:35], 0, v[136:137]
	s_add_i32 m0, s49, 0xe000
	s_nop 0
	global_load_lds_dwordx4 v[216:217], off
	s_waitcnt vmcnt(8)
	s_waitcnt lgkmcnt(0)
	s_setprio 0
	s_barrier
	v_mfma_f32_16x16x32_bf16 v[124:127], v[144:147], v[184:187], v[124:127]
	v_mfma_f32_16x16x32_bf16 v[120:123], v[160:163], v[184:187], v[120:123]
	v_mfma_f32_16x16x32_bf16 v[108:111], v[144:147], v[192:195], v[108:111]
	v_mfma_f32_16x16x32_bf16 v[104:107], v[160:163], v[192:195], v[104:107]
	v_mfma_f32_16x16x32_bf16 v[92:95], v[144:147], v[200:203], v[92:95]
	v_mfma_f32_16x16x32_bf16 v[88:91], v[160:163], v[200:203], v[88:91]
	v_mfma_f32_16x16x32_bf16 v[76:79], v[144:147], v[208:211], v[76:79]
	v_mfma_f32_16x16x32_bf16 v[72:75], v[160:163], v[208:211], v[72:75]
	v_mfma_f32_16x16x32_bf16 v[124:127], v[156:159], v[188:191], v[124:127]
	v_mfma_f32_16x16x32_bf16 v[120:123], v[164:167], v[188:191], v[120:123]
	v_mfma_f32_16x16x32_bf16 v[108:111], v[156:159], v[196:199], v[108:111]
	v_mfma_f32_16x16x32_bf16 v[104:107], v[164:167], v[196:199], v[104:107]
	v_mfma_f32_16x16x32_bf16 v[92:95], v[156:159], v[204:207], v[92:95]
	v_mfma_f32_16x16x32_bf16 v[88:91], v[164:167], v[204:207], v[88:91]
	v_mfma_f32_16x16x32_bf16 v[76:79], v[156:159], v[212:215], v[76:79]
	v_mfma_f32_16x16x32_bf16 v[72:75], v[164:167], v[212:215], v[72:75]
	v_mfma_f32_16x16x32_bf16 v[116:119], v[168:171], v[184:187], v[116:119]
	v_mfma_f32_16x16x32_bf16 v[112:115], v[176:179], v[184:187], v[112:115]
	v_mfma_f32_16x16x32_bf16 v[100:103], v[168:171], v[192:195], v[100:103]
	v_mfma_f32_16x16x32_bf16 v[96:99], v[176:179], v[192:195], v[96:99]
	v_mfma_f32_16x16x32_bf16 v[84:87], v[168:171], v[200:203], v[84:87]
	v_mfma_f32_16x16x32_bf16 v[80:83], v[176:179], v[200:203], v[80:83]
	v_mfma_f32_16x16x32_bf16 v[68:71], v[168:171], v[208:211], v[68:71]
	v_mfma_f32_16x16x32_bf16 v[64:67], v[176:179], v[208:211], v[64:67]
	v_mfma_f32_16x16x32_bf16 v[116:119], v[172:175], v[188:191], v[116:119]
	v_mfma_f32_16x16x32_bf16 v[112:115], v[180:183], v[188:191], v[112:115]
	v_mfma_f32_16x16x32_bf16 v[100:103], v[172:175], v[196:199], v[100:103]
	v_mfma_f32_16x16x32_bf16 v[96:99], v[180:183], v[196:199], v[96:99]
	v_mfma_f32_16x16x32_bf16 v[84:87], v[172:175], v[204:207], v[84:87]
	v_mfma_f32_16x16x32_bf16 v[80:83], v[180:183], v[204:207], v[80:83]
	v_mfma_f32_16x16x32_bf16 v[68:71], v[172:175], v[212:215], v[68:71]
	v_mfma_f32_16x16x32_bf16 v[64:67], v[180:183], v[212:215], v[64:67]
	s_barrier
	s_setprio 1
	s_add_i32 s34, s62, s48
	v_lshl_add_u64 v[216:217], s[52:53], 0, v[130:131]
	s_mov_b32 m0, s34
	ds_read_b128 v[184:187], v153 offset:16384
	ds_read_b128 v[188:191], v153 offset:17408
	ds_read_b128 v[192:195], v153 offset:18432
	ds_read_b128 v[196:199], v153 offset:19456
	ds_read_b128 v[200:203], v153 offset:20480
	ds_read_b128 v[204:207], v153 offset:21504
	ds_read_b128 v[208:211], v153 offset:22528
	ds_read_b128 v[212:215], v153 offset:23552
	global_load_lds_dwordx4 v[216:217], off
	s_add_i32 m0, s34, 0x2000
	s_add_u32 s34, s52, 0x160000
	v_lshl_add_u64 v[218:219], s[52:53], 0, v[134:135]
	s_addc_u32 s35, s53, 0
	s_add_i32 s67, s63, s48
	global_load_lds_dwordx4 v[218:219], off
	v_lshl_add_u64 v[220:221], s[34:35], 0, v[130:131]
	s_mov_b32 m0, s67
	v_lshl_add_u64 v[222:223], s[54:55], 0, v[132:133]
	global_load_lds_dwordx4 v[220:221], off
	v_lshl_add_u64 v[220:221], s[34:35], 0, v[134:135]
	s_add_i32 m0, s67, 0x2000
	s_nop 0
	global_load_lds_dwordx4 v[220:221], off
	v_lshl_add_u64 v[220:221], s[54:55], 0, v[128:129]
	s_mov_b32 m0, s49
	s_nop 0
	global_load_lds_dwordx4 v[220:221], off
	s_mov_b32 m0, s56
	s_nop 0
	global_load_lds_dwordx4 v[222:223], off
	s_waitcnt vmcnt(8)
	s_waitcnt lgkmcnt(0)
	s_setprio 0
	s_barrier
	v_mfma_f32_16x16x32_bf16 v[60:63], v[144:147], v[184:187], v[60:63]
	v_mfma_f32_16x16x32_bf16 v[56:59], v[160:163], v[184:187], v[56:59]
	v_mfma_f32_16x16x32_bf16 v[44:47], v[144:147], v[192:195], v[44:47]
	v_mfma_f32_16x16x32_bf16 v[40:43], v[160:163], v[192:195], v[40:43]
	v_mfma_f32_16x16x32_bf16 v[28:31], v[144:147], v[200:203], v[28:31]
	v_mfma_f32_16x16x32_bf16 v[24:27], v[160:163], v[200:203], v[24:27]
	v_mfma_f32_16x16x32_bf16 v[12:15], v[144:147], v[208:211], v[12:15]
	v_mfma_f32_16x16x32_bf16 v[8:11], v[160:163], v[208:211], v[8:11]
	v_mfma_f32_16x16x32_bf16 v[60:63], v[156:159], v[188:191], v[60:63]
	v_mfma_f32_16x16x32_bf16 v[56:59], v[164:167], v[188:191], v[56:59]
	v_mfma_f32_16x16x32_bf16 v[44:47], v[156:159], v[196:199], v[44:47]
	v_mfma_f32_16x16x32_bf16 v[40:43], v[164:167], v[196:199], v[40:43]
	v_mfma_f32_16x16x32_bf16 v[28:31], v[156:159], v[204:207], v[28:31]
	v_mfma_f32_16x16x32_bf16 v[24:27], v[164:167], v[204:207], v[24:27]
	v_mfma_f32_16x16x32_bf16 v[12:15], v[156:159], v[212:215], v[12:15]
	v_mfma_f32_16x16x32_bf16 v[8:11], v[164:167], v[212:215], v[8:11]
	v_mfma_f32_16x16x32_bf16 v[52:55], v[168:171], v[184:187], v[52:55]
	v_mfma_f32_16x16x32_bf16 v[48:51], v[176:179], v[184:187], v[48:51]
	v_mfma_f32_16x16x32_bf16 v[36:39], v[168:171], v[192:195], v[36:39]
	v_mfma_f32_16x16x32_bf16 v[32:35], v[176:179], v[192:195], v[32:35]
	v_mfma_f32_16x16x32_bf16 v[20:23], v[168:171], v[200:203], v[20:23]
	v_mfma_f32_16x16x32_bf16 v[16:19], v[176:179], v[200:203], v[16:19]
	v_mfma_f32_16x16x32_bf16 v[4:7], v[168:171], v[208:211], v[4:7]
	v_mfma_f32_16x16x32_bf16 v[0:3], v[176:179], v[208:211], v[0:3]
	v_mfma_f32_16x16x32_bf16 v[52:55], v[172:175], v[188:191], v[52:55]
	v_mfma_f32_16x16x32_bf16 v[48:51], v[180:183], v[188:191], v[48:51]
	v_mfma_f32_16x16x32_bf16 v[36:39], v[172:175], v[196:199], v[36:39]
	v_mfma_f32_16x16x32_bf16 v[32:35], v[180:183], v[196:199], v[32:35]
	v_mfma_f32_16x16x32_bf16 v[20:23], v[172:175], v[204:207], v[20:23]
	v_mfma_f32_16x16x32_bf16 v[16:19], v[180:183], v[204:207], v[16:19]
	v_mfma_f32_16x16x32_bf16 v[4:7], v[172:175], v[212:215], v[4:7]
	v_mfma_f32_16x16x32_bf16 v[0:3], v[180:183], v[212:215], v[0:3]
	s_barrier
	s_setprio 1
	s_add_i32 s67, 0, 0x18000
	v_add_u32_e32 v155, s67, v149
	s_add_i32 s70, 0, 0x1c000
	ds_read_b128 v[144:147], v155
	ds_read_b128 v[156:159], v155 offset:1024
	ds_read_b128 v[160:163], v155 offset:2048
	ds_read_b128 v[164:167], v155 offset:3072
	v_add_u32_e32 v155, s70, v149
	ds_read_b128 v[168:171], v155
	ds_read_b128 v[172:175], v155 offset:1024
	ds_read_b128 v[176:179], v155 offset:2048
	ds_read_b128 v[180:183], v155 offset:3072
	s_add_u32 s34, s54, 0x160000
	s_addc_u32 s35, s55, 0
	s_mov_b32 m0, s57
	v_lshl_add_u64 v[224:225], s[34:35], 0, v[128:129]
	ds_read_b128 v[184:187], v153 offset:32768
	ds_read_b128 v[188:191], v153 offset:33792
	ds_read_b128 v[192:195], v153 offset:34816
	ds_read_b128 v[196:199], v153 offset:35840
	ds_read_b128 v[200:203], v153 offset:36864
	ds_read_b128 v[204:207], v153 offset:37888
	ds_read_b128 v[208:211], v153 offset:38912
	ds_read_b128 v[212:215], v153 offset:39936
	global_load_lds_dwordx4 v[224:225], off
	v_lshl_add_u64 v[224:225], s[34:35], 0, v[132:133]
	s_mov_b32 m0, s58
	s_nop 0
	global_load_lds_dwordx4 v[224:225], off
	s_waitcnt vmcnt(8)
	s_waitcnt lgkmcnt(0)
	s_setprio 0
	s_barrier
	v_mfma_f32_16x16x32_bf16 v[124:127], v[144:147], v[184:187], v[124:127]
	v_mfma_f32_16x16x32_bf16 v[120:123], v[160:163], v[184:187], v[120:123]
	v_mfma_f32_16x16x32_bf16 v[108:111], v[144:147], v[192:195], v[108:111]
	v_mfma_f32_16x16x32_bf16 v[104:107], v[160:163], v[192:195], v[104:107]
	v_mfma_f32_16x16x32_bf16 v[92:95], v[144:147], v[200:203], v[92:95]
	v_mfma_f32_16x16x32_bf16 v[88:91], v[160:163], v[200:203], v[88:91]
	v_mfma_f32_16x16x32_bf16 v[76:79], v[144:147], v[208:211], v[76:79]
	v_mfma_f32_16x16x32_bf16 v[72:75], v[160:163], v[208:211], v[72:75]
	v_mfma_f32_16x16x32_bf16 v[124:127], v[156:159], v[188:191], v[124:127]
	v_mfma_f32_16x16x32_bf16 v[120:123], v[164:167], v[188:191], v[120:123]
	v_mfma_f32_16x16x32_bf16 v[108:111], v[156:159], v[196:199], v[108:111]
	v_mfma_f32_16x16x32_bf16 v[104:107], v[164:167], v[196:199], v[104:107]
	v_mfma_f32_16x16x32_bf16 v[92:95], v[156:159], v[204:207], v[92:95]
	v_mfma_f32_16x16x32_bf16 v[88:91], v[164:167], v[204:207], v[88:91]
	v_mfma_f32_16x16x32_bf16 v[76:79], v[156:159], v[212:215], v[76:79]
	v_mfma_f32_16x16x32_bf16 v[72:75], v[164:167], v[212:215], v[72:75]
	v_mfma_f32_16x16x32_bf16 v[116:119], v[168:171], v[184:187], v[116:119]
	v_mfma_f32_16x16x32_bf16 v[112:115], v[176:179], v[184:187], v[112:115]
	v_mfma_f32_16x16x32_bf16 v[100:103], v[168:171], v[192:195], v[100:103]
	v_mfma_f32_16x16x32_bf16 v[96:99], v[176:179], v[192:195], v[96:99]
	v_mfma_f32_16x16x32_bf16 v[84:87], v[168:171], v[200:203], v[84:87]
	v_mfma_f32_16x16x32_bf16 v[80:83], v[176:179], v[200:203], v[80:83]
	v_mfma_f32_16x16x32_bf16 v[68:71], v[168:171], v[208:211], v[68:71]
	v_mfma_f32_16x16x32_bf16 v[64:67], v[176:179], v[208:211], v[64:67]
	v_mfma_f32_16x16x32_bf16 v[116:119], v[172:175], v[188:191], v[116:119]
	v_mfma_f32_16x16x32_bf16 v[112:115], v[180:183], v[188:191], v[112:115]
	v_mfma_f32_16x16x32_bf16 v[100:103], v[172:175], v[196:199], v[100:103]
	v_mfma_f32_16x16x32_bf16 v[96:99], v[180:183], v[196:199], v[96:99]
	v_mfma_f32_16x16x32_bf16 v[84:87], v[172:175], v[204:207], v[84:87]
	v_mfma_f32_16x16x32_bf16 v[80:83], v[180:183], v[204:207], v[80:83]
	v_mfma_f32_16x16x32_bf16 v[68:71], v[172:175], v[212:215], v[68:71]
	v_mfma_f32_16x16x32_bf16 v[64:67], v[180:183], v[212:215], v[64:67]
	s_barrier
	s_setprio 1
	s_add_i32 s34, s67, s48
	v_lshl_add_u64 v[216:217], v[216:217], 0, s[24:25]
	s_mov_b32 m0, s34
	ds_read_b128 v[184:187], v153 offset:49152
	ds_read_b128 v[188:191], v153 offset:50176
	ds_read_b128 v[192:195], v153 offset:51200
	ds_read_b128 v[196:199], v153 offset:52224
	ds_read_b128 v[200:203], v153 offset:53248
	ds_read_b128 v[204:207], v153 offset:54272
	ds_read_b128 v[208:211], v153 offset:55296
	ds_read_b128 v[212:215], v153 offset:56320
	global_load_lds_dwordx4 v[216:217], off
	s_add_i32 m0, s34, 0x2000
	s_add_u32 s34, s52, 0x160080
	v_lshl_add_u64 v[216:217], v[218:219], 0, s[24:25]
	s_addc_u32 s35, s53, 0
	s_add_i32 s52, s70, s48
	global_load_lds_dwordx4 v[216:217], off
	v_lshl_add_u64 v[216:217], s[34:35], 0, v[130:131]
	s_mov_b32 m0, s52
	s_nop 0
	global_load_lds_dwordx4 v[216:217], off
	v_lshl_add_u64 v[216:217], s[34:35], 0, v[134:135]
	s_add_i32 m0, s52, 0x2000
	s_nop 0
	global_load_lds_dwordx4 v[216:217], off
	v_lshl_add_u64 v[216:217], v[220:221], 0, s[24:25]
	s_mov_b32 m0, s60
	s_nop 0
	global_load_lds_dwordx4 v[216:217], off
	v_lshl_add_u64 v[216:217], v[222:223], 0, s[24:25]
	s_mov_b32 m0, s61
	s_nop 0
	global_load_lds_dwordx4 v[216:217], off
	s_waitcnt vmcnt(8)
	s_waitcnt lgkmcnt(0)
	s_setprio 0
	s_barrier
	v_mfma_f32_16x16x32_bf16 v[60:63], v[144:147], v[184:187], v[60:63]
	v_mfma_f32_16x16x32_bf16 v[56:59], v[160:163], v[184:187], v[56:59]
	v_mfma_f32_16x16x32_bf16 v[44:47], v[144:147], v[192:195], v[44:47]
	v_mfma_f32_16x16x32_bf16 v[40:43], v[160:163], v[192:195], v[40:43]
	v_mfma_f32_16x16x32_bf16 v[28:31], v[144:147], v[200:203], v[28:31]
	v_mfma_f32_16x16x32_bf16 v[24:27], v[160:163], v[200:203], v[24:27]
	v_mfma_f32_16x16x32_bf16 v[12:15], v[144:147], v[208:211], v[12:15]
	v_mfma_f32_16x16x32_bf16 v[8:11], v[160:163], v[208:211], v[8:11]
	v_mfma_f32_16x16x32_bf16 v[60:63], v[156:159], v[188:191], v[60:63]
	v_mfma_f32_16x16x32_bf16 v[56:59], v[164:167], v[188:191], v[56:59]
	v_mfma_f32_16x16x32_bf16 v[44:47], v[156:159], v[196:199], v[44:47]
	v_mfma_f32_16x16x32_bf16 v[40:43], v[164:167], v[196:199], v[40:43]
	v_mfma_f32_16x16x32_bf16 v[28:31], v[156:159], v[204:207], v[28:31]
	v_mfma_f32_16x16x32_bf16 v[24:27], v[164:167], v[204:207], v[24:27]
	v_mfma_f32_16x16x32_bf16 v[12:15], v[156:159], v[212:215], v[12:15]
	v_mfma_f32_16x16x32_bf16 v[8:11], v[164:167], v[212:215], v[8:11]
	v_mfma_f32_16x16x32_bf16 v[52:55], v[168:171], v[184:187], v[52:55]
	v_mfma_f32_16x16x32_bf16 v[48:51], v[176:179], v[184:187], v[48:51]
	v_mfma_f32_16x16x32_bf16 v[36:39], v[168:171], v[192:195], v[36:39]
	v_mfma_f32_16x16x32_bf16 v[32:35], v[176:179], v[192:195], v[32:35]
	v_mfma_f32_16x16x32_bf16 v[20:23], v[168:171], v[200:203], v[20:23]
	v_mfma_f32_16x16x32_bf16 v[16:19], v[176:179], v[200:203], v[16:19]
	v_mfma_f32_16x16x32_bf16 v[4:7], v[168:171], v[208:211], v[4:7]
	v_mfma_f32_16x16x32_bf16 v[0:3], v[176:179], v[208:211], v[0:3]
	v_mfma_f32_16x16x32_bf16 v[52:55], v[172:175], v[188:191], v[52:55]
	v_mfma_f32_16x16x32_bf16 v[48:51], v[180:183], v[188:191], v[48:51]
	v_mfma_f32_16x16x32_bf16 v[36:39], v[172:175], v[196:199], v[36:39]
	v_mfma_f32_16x16x32_bf16 v[32:35], v[180:183], v[196:199], v[32:35]
	v_mfma_f32_16x16x32_bf16 v[20:23], v[172:175], v[204:207], v[20:23]
	v_mfma_f32_16x16x32_bf16 v[16:19], v[180:183], v[204:207], v[16:19]
	v_mfma_f32_16x16x32_bf16 v[4:7], v[172:175], v[212:215], v[4:7]
	v_mfma_f32_16x16x32_bf16 v[0:3], v[180:183], v[212:215], v[0:3]
	s_barrier
	s_setprio 1
	s_add_i32 s66, s66, 2
	s_add_u32 s46, s46, 0x100
	s_addc_u32 s47, s47, 0
	s_cmpk_gt_u32 s66, 0x55
	s_mov_b64 s[34:35], s[36:37]
	s_cbranch_scc0 .LBB0_523
	s_and_b64 vcc, exec, s[26:27]
	s_cbranch_vccz .LBB0_526
	s_barrier

.LBB0_617:
	ds_read_b128 v[146:149], v159
	ds_read_b128 v[150:153], v159 offset:1024
	ds_read_b128 v[164:167], v159 offset:2048
	ds_read_b128 v[168:171], v159 offset:3072
	ds_read_b128 v[172:175], v160
	ds_read_b128 v[176:179], v160 offset:1024
	ds_read_b128 v[180:183], v160 offset:2048
	ds_read_b128 v[184:187], v160 offset:3072
	s_add_u32 s58, s56, 0xfff80080
	s_addc_u32 s59, s57, -1
	s_cmp_eq_u32 s55, 28
	s_cselect_b32 s61, s35, s59
	s_cselect_b32 s60, s46, s58
	s_cselect_b32 s59, s31, s51
	s_cselect_b32 s58, s47, s50
	v_lshl_add_u64 v[154:155], s[56:57], 0, v[140:141]
	s_add_i32 m0, s45, 0xc000
	ds_read_b128 v[188:191], v161
	ds_read_b128 v[192:195], v161 offset:1024
	ds_read_b128 v[196:199], v161 offset:2048
	ds_read_b128 v[200:203], v161 offset:3072
	ds_read_b128 v[204:207], v161 offset:4096
	ds_read_b128 v[208:211], v161 offset:5120
	ds_read_b128 v[212:215], v161 offset:6144
	ds_read_b128 v[216:219], v161 offset:7168
	global_load_lds_dwordx4 v[154:155], off
	v_lshl_add_u64 v[154:155], s[56:57], 0, v[138:139]
	s_add_i32 m0, s45, 0xe000
	s_nop 0
	global_load_lds_dwordx4 v[154:155], off
	s_waitcnt vmcnt(8)
	s_waitcnt lgkmcnt(0)
	s_setprio 0
	s_barrier
	v_mfma_f32_16x16x32_bf16 v[124:127], v[146:149], v[188:191], v[124:127]
	v_mfma_f32_16x16x32_bf16 v[120:123], v[164:167], v[188:191], v[120:123]
	v_mfma_f32_16x16x32_bf16 v[108:111], v[146:149], v[196:199], v[108:111]
	v_mfma_f32_16x16x32_bf16 v[104:107], v[164:167], v[196:199], v[104:107]
	v_mfma_f32_16x16x32_bf16 v[92:95], v[146:149], v[204:207], v[92:95]
	v_mfma_f32_16x16x32_bf16 v[88:91], v[164:167], v[204:207], v[88:91]
	v_mfma_f32_16x16x32_bf16 v[76:79], v[146:149], v[212:215], v[76:79]
	v_mfma_f32_16x16x32_bf16 v[72:75], v[164:167], v[212:215], v[72:75]
	v_mfma_f32_16x16x32_bf16 v[124:127], v[150:153], v[192:195], v[124:127]
	v_mfma_f32_16x16x32_bf16 v[120:123], v[168:171], v[192:195], v[120:123]
	v_mfma_f32_16x16x32_bf16 v[108:111], v[150:153], v[200:203], v[108:111]
	v_mfma_f32_16x16x32_bf16 v[104:107], v[168:171], v[200:203], v[104:107]
	v_mfma_f32_16x16x32_bf16 v[92:95], v[150:153], v[208:211], v[92:95]
	v_mfma_f32_16x16x32_bf16 v[88:91], v[168:171], v[208:211], v[88:91]
	v_mfma_f32_16x16x32_bf16 v[76:79], v[150:153], v[216:219], v[76:79]
	v_mfma_f32_16x16x32_bf16 v[72:75], v[168:171], v[216:219], v[72:75]
	v_mfma_f32_16x16x32_bf16 v[116:119], v[172:175], v[188:191], v[116:119]
	v_mfma_f32_16x16x32_bf16 v[112:115], v[180:183], v[188:191], v[112:115]
	v_mfma_f32_16x16x32_bf16 v[100:103], v[172:175], v[196:199], v[100:103]
	v_mfma_f32_16x16x32_bf16 v[96:99], v[180:183], v[196:199], v[96:99]
	v_mfma_f32_16x16x32_bf16 v[84:87], v[172:175], v[204:207], v[84:87]
	v_mfma_f32_16x16x32_bf16 v[80:83], v[180:183], v[204:207], v[80:83]
	v_mfma_f32_16x16x32_bf16 v[68:71], v[172:175], v[212:215], v[68:71]
	v_mfma_f32_16x16x32_bf16 v[64:67], v[180:183], v[212:215], v[64:67]
	v_mfma_f32_16x16x32_bf16 v[116:119], v[176:179], v[192:195], v[116:119]
	v_mfma_f32_16x16x32_bf16 v[112:115], v[184:187], v[192:195], v[112:115]
	v_mfma_f32_16x16x32_bf16 v[100:103], v[176:179], v[200:203], v[100:103]
	v_mfma_f32_16x16x32_bf16 v[96:99], v[184:187], v[200:203], v[96:99]
	v_mfma_f32_16x16x32_bf16 v[84:87], v[176:179], v[208:211], v[84:87]
	v_mfma_f32_16x16x32_bf16 v[80:83], v[184:187], v[208:211], v[80:83]
	v_mfma_f32_16x16x32_bf16 v[68:71], v[176:179], v[216:219], v[68:71]
	v_mfma_f32_16x16x32_bf16 v[64:67], v[184:187], v[216:219], v[64:67]
	s_barrier
	s_setprio 1
	s_add_i32 s72, s66, s44
	v_lshl_add_u64 v[154:155], s[58:59], 0, v[130:131]
	s_mov_b32 m0, s72
	ds_read_b128 v[188:191], v161 offset:16384
	ds_read_b128 v[192:195], v161 offset:17408
	ds_read_b128 v[196:199], v161 offset:18432
	ds_read_b128 v[200:203], v161 offset:19456
	ds_read_b128 v[204:207], v161 offset:20480
	ds_read_b128 v[208:211], v161 offset:21504
	ds_read_b128 v[212:215], v161 offset:22528
	ds_read_b128 v[216:219], v161 offset:23552
	global_load_lds_dwordx4 v[154:155], off
	s_add_i32 m0, s72, 0x2000
	s_add_u32 s80, s58, 0x80000
	v_lshl_add_u64 v[220:221], s[58:59], 0, v[134:135]
	s_addc_u32 s81, s59, 0
	s_add_i32 s72, s67, s44
	global_load_lds_dwordx4 v[220:221], off
	v_lshl_add_u64 v[222:223], s[80:81], 0, v[130:131]
	s_mov_b32 m0, s72
	v_lshl_add_u64 v[224:225], s[60:61], 0, v[132:133]
	global_load_lds_dwordx4 v[222:223], off
	v_lshl_add_u64 v[222:223], s[80:81], 0, v[134:135]
	s_add_i32 m0, s72, 0x2000
	s_nop 0
	global_load_lds_dwordx4 v[222:223], off
	v_lshl_add_u64 v[222:223], s[60:61], 0, v[128:129]
	s_mov_b32 m0, s45
	s_nop 0
	global_load_lds_dwordx4 v[222:223], off
	s_mov_b32 m0, s48
	s_nop 0
	global_load_lds_dwordx4 v[224:225], off
	s_waitcnt vmcnt(8)
	s_waitcnt lgkmcnt(0)
	s_setprio 0
	s_barrier
	v_mfma_f32_16x16x32_bf16 v[60:63], v[146:149], v[188:191], v[60:63]
	v_mfma_f32_16x16x32_bf16 v[56:59], v[164:167], v[188:191], v[56:59]
	v_mfma_f32_16x16x32_bf16 v[44:47], v[146:149], v[196:199], v[44:47]
	v_mfma_f32_16x16x32_bf16 v[40:43], v[164:167], v[196:199], v[40:43]
	v_mfma_f32_16x16x32_bf16 v[28:31], v[146:149], v[204:207], v[28:31]
	v_mfma_f32_16x16x32_bf16 v[24:27], v[164:167], v[204:207], v[24:27]
	v_mfma_f32_16x16x32_bf16 v[12:15], v[146:149], v[212:215], v[12:15]
	v_mfma_f32_16x16x32_bf16 v[8:11], v[164:167], v[212:215], v[8:11]
	v_mfma_f32_16x16x32_bf16 v[60:63], v[150:153], v[192:195], v[60:63]
	v_mfma_f32_16x16x32_bf16 v[56:59], v[168:171], v[192:195], v[56:59]
	v_mfma_f32_16x16x32_bf16 v[44:47], v[150:153], v[200:203], v[44:47]
	v_mfma_f32_16x16x32_bf16 v[40:43], v[168:171], v[200:203], v[40:43]
	v_mfma_f32_16x16x32_bf16 v[28:31], v[150:153], v[208:211], v[28:31]
	v_mfma_f32_16x16x32_bf16 v[24:27], v[168:171], v[208:211], v[24:27]
	v_mfma_f32_16x16x32_bf16 v[12:15], v[150:153], v[216:219], v[12:15]
	v_mfma_f32_16x16x32_bf16 v[8:11], v[168:171], v[216:219], v[8:11]
	v_mfma_f32_16x16x32_bf16 v[52:55], v[172:175], v[188:191], v[52:55]
	v_mfma_f32_16x16x32_bf16 v[48:51], v[180:183], v[188:191], v[48:51]
	v_mfma_f32_16x16x32_bf16 v[36:39], v[172:175], v[196:199], v[36:39]
	v_mfma_f32_16x16x32_bf16 v[32:35], v[180:183], v[196:199], v[32:35]
	v_mfma_f32_16x16x32_bf16 v[20:23], v[172:175], v[204:207], v[20:23]
	v_mfma_f32_16x16x32_bf16 v[16:19], v[180:183], v[204:207], v[16:19]
	v_mfma_f32_16x16x32_bf16 v[4:7], v[172:175], v[212:215], v[4:7]
	v_mfma_f32_16x16x32_bf16 v[0:3], v[180:183], v[212:215], v[0:3]
	v_mfma_f32_16x16x32_bf16 v[52:55], v[176:179], v[192:195], v[52:55]
	v_mfma_f32_16x16x32_bf16 v[48:51], v[184:187], v[192:195], v[48:51]
	v_mfma_f32_16x16x32_bf16 v[36:39], v[176:179], v[200:203], v[36:39]
	v_mfma_f32_16x16x32_bf16 v[32:35], v[184:187], v[200:203], v[32:35]
	v_mfma_f32_16x16x32_bf16 v[20:23], v[176:179], v[208:211], v[20:23]
	v_mfma_f32_16x16x32_bf16 v[16:19], v[184:187], v[208:211], v[16:19]
	v_mfma_f32_16x16x32_bf16 v[4:7], v[176:179], v[216:219], v[4:7]
	v_mfma_f32_16x16x32_bf16 v[0:3], v[184:187], v[216:219], v[0:3]
	s_barrier
	s_setprio 1
	s_add_i32 s72, 0, 0x18000
	s_add_i32 s78, 0, 0x1c000
	v_add_u32_e32 v168, s72, v157
	v_add_u32_e32 v184, s78, v157
	ds_read_b128 v[146:149], v168
	ds_read_b128 v[150:153], v168 offset:1024
	ds_read_b128 v[164:167], v168 offset:2048
	ds_read_b128 v[168:171], v168 offset:3072
	ds_read_b128 v[172:175], v184
	ds_read_b128 v[176:179], v184 offset:1024
	ds_read_b128 v[180:183], v184 offset:2048
	ds_read_b128 v[184:187], v184 offset:3072
	s_add_u32 s60, s60, 0x80000
	s_addc_u32 s61, s61, 0
	s_mov_b32 m0, s49
	v_lshl_add_u64 v[226:227], s[60:61], 0, v[128:129]
	ds_read_b128 v[188:191], v161 offset:32768
	ds_read_b128 v[192:195], v161 offset:33792
	ds_read_b128 v[196:199], v161 offset:34816
	ds_read_b128 v[200:203], v161 offset:35840
	ds_read_b128 v[204:207], v161 offset:36864
	ds_read_b128 v[208:211], v161 offset:37888
	ds_read_b128 v[212:215], v161 offset:38912
	ds_read_b128 v[216:219], v161 offset:39936
	global_load_lds_dwordx4 v[226:227], off
	v_lshl_add_u64 v[226:227], s[60:61], 0, v[132:133]
	s_mov_b32 m0, s62
	s_nop 0
	global_load_lds_dwordx4 v[226:227], off
	s_waitcnt vmcnt(8)
	s_waitcnt lgkmcnt(0)
	s_setprio 0
	s_barrier
	v_mfma_f32_16x16x32_bf16 v[124:127], v[146:149], v[188:191], v[124:127]
	v_mfma_f32_16x16x32_bf16 v[120:123], v[164:167], v[188:191], v[120:123]
	v_mfma_f32_16x16x32_bf16 v[108:111], v[146:149], v[196:199], v[108:111]
	v_mfma_f32_16x16x32_bf16 v[104:107], v[164:167], v[196:199], v[104:107]
	v_mfma_f32_16x16x32_bf16 v[92:95], v[146:149], v[204:207], v[92:95]
	v_mfma_f32_16x16x32_bf16 v[88:91], v[164:167], v[204:207], v[88:91]
	v_mfma_f32_16x16x32_bf16 v[76:79], v[146:149], v[212:215], v[76:79]
	v_mfma_f32_16x16x32_bf16 v[72:75], v[164:167], v[212:215], v[72:75]
	v_mfma_f32_16x16x32_bf16 v[124:127], v[150:153], v[192:195], v[124:127]
	v_mfma_f32_16x16x32_bf16 v[120:123], v[168:171], v[192:195], v[120:123]
	v_mfma_f32_16x16x32_bf16 v[108:111], v[150:153], v[200:203], v[108:111]
	v_mfma_f32_16x16x32_bf16 v[104:107], v[168:171], v[200:203], v[104:107]
	v_mfma_f32_16x16x32_bf16 v[92:95], v[150:153], v[208:211], v[92:95]
	v_mfma_f32_16x16x32_bf16 v[88:91], v[168:171], v[208:211], v[88:91]
	v_mfma_f32_16x16x32_bf16 v[76:79], v[150:153], v[216:219], v[76:79]
	v_mfma_f32_16x16x32_bf16 v[72:75], v[168:171], v[216:219], v[72:75]
	v_mfma_f32_16x16x32_bf16 v[116:119], v[172:175], v[188:191], v[116:119]
	v_mfma_f32_16x16x32_bf16 v[112:115], v[180:183], v[188:191], v[112:115]
	v_mfma_f32_16x16x32_bf16 v[100:103], v[172:175], v[196:199], v[100:103]
	v_mfma_f32_16x16x32_bf16 v[96:99], v[180:183], v[196:199], v[96:99]
	v_mfma_f32_16x16x32_bf16 v[84:87], v[172:175], v[204:207], v[84:87]
	v_mfma_f32_16x16x32_bf16 v[80:83], v[180:183], v[204:207], v[80:83]
	v_mfma_f32_16x16x32_bf16 v[68:71], v[172:175], v[212:215], v[68:71]
	v_mfma_f32_16x16x32_bf16 v[64:67], v[180:183], v[212:215], v[64:67]
	v_mfma_f32_16x16x32_bf16 v[116:119], v[176:179], v[192:195], v[116:119]
	v_mfma_f32_16x16x32_bf16 v[112:115], v[184:187], v[192:195], v[112:115]
	v_mfma_f32_16x16x32_bf16 v[100:103], v[176:179], v[200:203], v[100:103]
	v_mfma_f32_16x16x32_bf16 v[96:99], v[184:187], v[200:203], v[96:99]
	v_mfma_f32_16x16x32_bf16 v[84:87], v[176:179], v[208:211], v[84:87]
	v_mfma_f32_16x16x32_bf16 v[80:83], v[184:187], v[208:211], v[80:83]
	v_mfma_f32_16x16x32_bf16 v[68:71], v[176:179], v[216:219], v[68:71]
	v_mfma_f32_16x16x32_bf16 v[64:67], v[184:187], v[216:219], v[64:67]
	s_barrier
	s_setprio 1
	s_add_i32 s60, s72, s44
	v_lshl_add_u64 v[154:155], v[154:155], 0, s[24:25]
	s_mov_b32 m0, s60
	ds_read_b128 v[188:191], v161 offset:49152
	ds_read_b128 v[192:195], v161 offset:50176
	ds_read_b128 v[196:199], v161 offset:51200
	ds_read_b128 v[200:203], v161 offset:52224
	ds_read_b128 v[204:207], v161 offset:53248
	ds_read_b128 v[208:211], v161 offset:54272
	ds_read_b128 v[212:215], v161 offset:55296
	ds_read_b128 v[216:219], v161 offset:56320
	global_load_lds_dwordx4 v[154:155], off
	s_add_i32 m0, s60, 0x2000
	s_add_u32 s58, s58, 0x80080
	v_lshl_add_u64 v[154:155], v[220:221], 0, s[24:25]
	s_addc_u32 s59, s59, 0
	s_add_i32 s60, s78, s44
	global_load_lds_dwordx4 v[154:155], off
	v_lshl_add_u64 v[154:155], s[58:59], 0, v[130:131]
	s_mov_b32 m0, s60
	s_nop 0
	global_load_lds_dwordx4 v[154:155], off
	v_lshl_add_u64 v[154:155], s[58:59], 0, v[134:135]
	s_add_i32 m0, s60, 0x2000
	s_nop 0
	global_load_lds_dwordx4 v[154:155], off
	v_lshl_add_u64 v[154:155], v[222:223], 0, s[24:25]
	s_mov_b32 m0, s64
	s_nop 0
	global_load_lds_dwordx4 v[154:155], off
	v_lshl_add_u64 v[154:155], v[224:225], 0, s[24:25]
	s_mov_b32 m0, s65
	s_nop 0
	global_load_lds_dwordx4 v[154:155], off
	s_waitcnt vmcnt(8)
	s_waitcnt lgkmcnt(0)
	s_setprio 0
	s_barrier
	v_mfma_f32_16x16x32_bf16 v[60:63], v[146:149], v[188:191], v[60:63]
	v_mfma_f32_16x16x32_bf16 v[56:59], v[164:167], v[188:191], v[56:59]
	v_mfma_f32_16x16x32_bf16 v[44:47], v[146:149], v[196:199], v[44:47]
	v_mfma_f32_16x16x32_bf16 v[40:43], v[164:167], v[196:199], v[40:43]
	v_mfma_f32_16x16x32_bf16 v[28:31], v[146:149], v[204:207], v[28:31]
	v_mfma_f32_16x16x32_bf16 v[24:27], v[164:167], v[204:207], v[24:27]
	v_mfma_f32_16x16x32_bf16 v[12:15], v[146:149], v[212:215], v[12:15]
	v_mfma_f32_16x16x32_bf16 v[8:11], v[164:167], v[212:215], v[8:11]
	v_mfma_f32_16x16x32_bf16 v[60:63], v[150:153], v[192:195], v[60:63]
	v_mfma_f32_16x16x32_bf16 v[56:59], v[168:171], v[192:195], v[56:59]
	v_mfma_f32_16x16x32_bf16 v[44:47], v[150:153], v[200:203], v[44:47]
	v_mfma_f32_16x16x32_bf16 v[40:43], v[168:171], v[200:203], v[40:43]
	v_mfma_f32_16x16x32_bf16 v[28:31], v[150:153], v[208:211], v[28:31]
	v_mfma_f32_16x16x32_bf16 v[24:27], v[168:171], v[208:211], v[24:27]
	v_mfma_f32_16x16x32_bf16 v[12:15], v[150:153], v[216:219], v[12:15]
	v_mfma_f32_16x16x32_bf16 v[8:11], v[168:171], v[216:219], v[8:11]
	v_mfma_f32_16x16x32_bf16 v[52:55], v[172:175], v[188:191], v[52:55]
	v_mfma_f32_16x16x32_bf16 v[48:51], v[180:183], v[188:191], v[48:51]
	v_mfma_f32_16x16x32_bf16 v[36:39], v[172:175], v[196:199], v[36:39]
	v_mfma_f32_16x16x32_bf16 v[32:35], v[180:183], v[196:199], v[32:35]
	v_mfma_f32_16x16x32_bf16 v[20:23], v[172:175], v[204:207], v[20:23]
	v_mfma_f32_16x16x32_bf16 v[16:19], v[180:183], v[204:207], v[16:19]
	v_mfma_f32_16x16x32_bf16 v[4:7], v[172:175], v[212:215], v[4:7]
	v_mfma_f32_16x16x32_bf16 v[0:3], v[180:183], v[212:215], v[0:3]
	v_mfma_f32_16x16x32_bf16 v[52:55], v[176:179], v[192:195], v[52:55]
	v_mfma_f32_16x16x32_bf16 v[48:51], v[184:187], v[192:195], v[48:51]
	v_mfma_f32_16x16x32_bf16 v[36:39], v[176:179], v[200:203], v[36:39]
	v_mfma_f32_16x16x32_bf16 v[32:35], v[184:187], v[200:203], v[32:35]
	v_mfma_f32_16x16x32_bf16 v[20:23], v[176:179], v[208:211], v[20:23]
	v_mfma_f32_16x16x32_bf16 v[16:19], v[184:187], v[208:211], v[16:19]
	v_mfma_f32_16x16x32_bf16 v[4:7], v[176:179], v[216:219], v[4:7]
	v_mfma_f32_16x16x32_bf16 v[0:3], v[184:187], v[216:219], v[0:3]
	s_barrier
	s_setprio 1
	s_add_i32 s55, s55, 2
	s_add_u32 s50, s50, 0x100
	s_addc_u32 s51, s51, 0
	s_add_u32 s56, s56, 0x100
	s_addc_u32 s57, s57, 0
	s_cmp_gt_u32 s55, 29
	s_cbranch_scc0 .LBB0_617
	s_and_b64 vcc, exec, s[26:27]
	s_cbranch_vccz .LBB0_620
	s_barrier

.LBB0_708:
	ds_read_b128 v[0:3], v145
	ds_read_b128 v[4:7], v145 offset:1024
	ds_read_b128 v[8:11], v145 offset:2048
	ds_read_b128 v[12:15], v145 offset:3072
	ds_read_b128 v[16:19], v146
	ds_read_b128 v[20:23], v146 offset:1024
	ds_read_b128 v[24:27], v146 offset:2048
	ds_read_b128 v[28:31], v146 offset:3072
	s_ashr_i32 s37, s36, 31
	s_lshl_b64 s[52:53], s[36:37], 17
	s_add_u32 s52, s6, s52
	s_addc_u32 s53, s7, s53
	s_and_b64 s[54:55], s[8:9], exec
	s_cselect_b32 s65, s53, s59
	s_cselect_b32 s64, s52, s58
	s_ashr_i32 s35, s34, 31
	s_lshl_b64 s[54:55], s[34:35], 17
	s_add_u32 s54, s44, s54
	s_addc_u32 s55, s45, s55
	s_and_b64 s[62:63], s[8:9], exec
	s_cselect_b32 s63, s55, s61
	s_cselect_b32 s62, s54, s60
	s_add_u32 s86, s58, 0x10080
	s_addc_u32 s87, s59, 0
	s_mov_b32 m0, s72
	v_lshl_add_u64 v[64:65], s[86:87], 0, v[128:129]
	ds_read_b128 v[32:35], v147
	ds_read_b128 v[36:39], v147 offset:1024
	ds_read_b128 v[40:43], v147 offset:2048
	ds_read_b128 v[44:47], v147 offset:3072
	ds_read_b128 v[48:51], v147 offset:4096
	ds_read_b128 v[52:55], v147 offset:5120
	ds_read_b128 v[56:59], v147 offset:6144
	ds_read_b128 v[60:63], v147 offset:7168
	global_load_lds_dwordx4 v[64:65], off
	v_lshl_add_u64 v[64:65], s[86:87], 0, v[132:133]
	s_mov_b32 m0, s80
	s_nop 0
	global_load_lds_dwordx4 v[64:65], off
	s_waitcnt vmcnt(8)
	s_waitcnt lgkmcnt(0)
	s_setprio 0
	s_barrier
	v_mfma_f32_16x16x32_bf16 v[64:67], v[0:3], v[32:35], 0
	v_mfma_f32_16x16x32_bf16 v[68:71], v[8:11], v[32:35], 0
	v_mfma_f32_16x16x32_bf16 v[72:75], v[0:3], v[40:43], 0
	v_mfma_f32_16x16x32_bf16 v[76:79], v[8:11], v[40:43], 0
	v_mfma_f32_16x16x32_bf16 v[80:83], v[0:3], v[48:51], 0
	v_mfma_f32_16x16x32_bf16 v[84:87], v[8:11], v[48:51], 0
	v_mfma_f32_16x16x32_bf16 v[88:91], v[0:3], v[56:59], 0
	v_mfma_f32_16x16x32_bf16 v[92:95], v[8:11], v[56:59], 0
	v_mfma_f32_16x16x32_bf16 v[64:67], v[4:7], v[36:39], v[64:67]
	v_mfma_f32_16x16x32_bf16 v[68:71], v[12:15], v[36:39], v[68:71]
	v_mfma_f32_16x16x32_bf16 v[72:75], v[4:7], v[44:47], v[72:75]
	v_mfma_f32_16x16x32_bf16 v[76:79], v[12:15], v[44:47], v[76:79]
	v_mfma_f32_16x16x32_bf16 v[80:83], v[4:7], v[52:55], v[80:83]
	v_mfma_f32_16x16x32_bf16 v[84:87], v[12:15], v[52:55], v[84:87]
	v_mfma_f32_16x16x32_bf16 v[88:91], v[4:7], v[60:63], v[88:91]
	v_mfma_f32_16x16x32_bf16 v[92:95], v[12:15], v[60:63], v[92:95]
	v_mfma_f32_16x16x32_bf16 v[96:99], v[16:19], v[32:35], 0
	v_mfma_f32_16x16x32_bf16 v[32:35], v[24:27], v[32:35], 0
	v_mfma_f32_16x16x32_bf16 v[96:99], v[20:23], v[36:39], v[96:99]
	v_mfma_f32_16x16x32_bf16 v[32:35], v[28:31], v[36:39], v[32:35]
	v_mfma_f32_16x16x32_bf16 v[36:39], v[16:19], v[40:43], 0
	v_mfma_f32_16x16x32_bf16 v[40:43], v[24:27], v[40:43], 0
	v_mfma_f32_16x16x32_bf16 v[36:39], v[20:23], v[44:47], v[36:39]
	v_mfma_f32_16x16x32_bf16 v[40:43], v[28:31], v[44:47], v[40:43]
	v_mfma_f32_16x16x32_bf16 v[44:47], v[16:19], v[48:51], 0
	v_mfma_f32_16x16x32_bf16 v[48:51], v[24:27], v[48:51], 0
	v_mfma_f32_16x16x32_bf16 v[44:47], v[20:23], v[52:55], v[44:47]
	v_mfma_f32_16x16x32_bf16 v[48:51], v[28:31], v[52:55], v[48:51]
	v_mfma_f32_16x16x32_bf16 v[52:55], v[16:19], v[56:59], 0
	v_mfma_f32_16x16x32_bf16 v[56:59], v[24:27], v[56:59], 0
	v_mfma_f32_16x16x32_bf16 v[52:55], v[20:23], v[60:63], v[52:55]
	v_mfma_f32_16x16x32_bf16 v[56:59], v[28:31], v[60:63], v[56:59]
	s_barrier
	s_setprio 1
	s_add_i32 s85, s70, s48
	v_lshl_add_u64 v[140:141], s[60:61], 0, v[130:131]
	s_add_i32 s35, s85, 0x2000
	v_lshl_add_u64 v[148:149], v[140:141], 0, s[20:21]
	s_mov_b32 m0, s85
	v_lshl_add_u64 v[212:213], s[60:61], 0, v[134:135]
	s_add_u32 s86, s60, 0x10100
	ds_read_b128 v[60:63], v147 offset:16384
	ds_read_b128 v[100:103], v147 offset:17408
	ds_read_b128 v[104:107], v147 offset:18432
	ds_read_b128 v[108:111], v147 offset:19456
	ds_read_b128 v[112:115], v147 offset:20480
	ds_read_b128 v[116:119], v147 offset:21504
	ds_read_b128 v[120:123], v147 offset:22528
	ds_read_b128 v[124:127], v147 offset:23552
	global_load_lds_dwordx4 v[148:149], off
	v_lshl_add_u64 v[148:149], v[212:213], 0, s[20:21]
	s_mov_b32 m0, s35
	s_addc_u32 s87, s61, 0
	s_add_i32 s37, s71, s48
	global_load_lds_dwordx4 v[148:149], off
	v_lshl_add_u64 v[148:149], s[86:87], 0, v[130:131]
	s_mov_b32 m0, s37
	s_add_i32 s47, s37, 0x2000
	global_load_lds_dwordx4 v[148:149], off
	v_lshl_add_u64 v[148:149], s[86:87], 0, v[134:135]
	s_mov_b32 m0, s47
	v_lshl_add_u64 v[214:215], s[58:59], 0, v[128:129]
	global_load_lds_dwordx4 v[148:149], off
	v_lshl_add_u64 v[148:149], v[214:215], 0, s[20:21]
	s_mov_b32 m0, s49
	v_lshl_add_u64 v[216:217], s[58:59], 0, v[132:133]
	global_load_lds_dwordx4 v[148:149], off
	v_lshl_add_u64 v[148:149], v[216:217], 0, s[20:21]
	s_mov_b32 m0, s50
	s_nop 0
	global_load_lds_dwordx4 v[148:149], off
	s_waitcnt vmcnt(8)
	s_waitcnt lgkmcnt(0)
	s_setprio 0
	s_barrier
	v_mfma_f32_16x16x32_bf16 v[148:151], v[0:3], v[60:63], 0
	v_mfma_f32_16x16x32_bf16 v[156:159], v[0:3], v[104:107], 0
	v_mfma_f32_16x16x32_bf16 v[164:167], v[0:3], v[112:115], 0
	v_mfma_f32_16x16x32_bf16 v[0:3], v[0:3], v[120:123], 0
	v_mfma_f32_16x16x32_bf16 v[148:151], v[4:7], v[100:103], v[148:151]
	v_mfma_f32_16x16x32_bf16 v[156:159], v[4:7], v[108:111], v[156:159]
	v_mfma_f32_16x16x32_bf16 v[164:167], v[4:7], v[116:119], v[164:167]
	v_mfma_f32_16x16x32_bf16 v[0:3], v[4:7], v[124:127], v[0:3]
	v_mfma_f32_16x16x32_bf16 v[4:7], v[8:11], v[120:123], 0
	v_mfma_f32_16x16x32_bf16 v[152:155], v[8:11], v[60:63], 0
	v_mfma_f32_16x16x32_bf16 v[160:163], v[8:11], v[104:107], 0
	v_mfma_f32_16x16x32_bf16 v[168:171], v[8:11], v[112:115], 0
	v_mfma_f32_16x16x32_bf16 v[4:7], v[12:15], v[124:127], v[4:7]
	v_mfma_f32_16x16x32_bf16 v[152:155], v[12:15], v[100:103], v[152:155]
	v_mfma_f32_16x16x32_bf16 v[160:163], v[12:15], v[108:111], v[160:163]
	v_mfma_f32_16x16x32_bf16 v[168:171], v[12:15], v[116:119], v[168:171]
	v_mfma_f32_16x16x32_bf16 v[8:11], v[16:19], v[60:63], 0
	v_mfma_f32_16x16x32_bf16 v[12:15], v[24:27], v[60:63], 0
	v_mfma_f32_16x16x32_bf16 v[8:11], v[20:23], v[100:103], v[8:11]
	v_mfma_f32_16x16x32_bf16 v[12:15], v[28:31], v[100:103], v[12:15]
	v_mfma_f32_16x16x32_bf16 v[60:63], v[16:19], v[104:107], 0
	v_mfma_f32_16x16x32_bf16 v[100:103], v[24:27], v[104:107], 0
	v_mfma_f32_16x16x32_bf16 v[104:107], v[16:19], v[112:115], 0
	v_mfma_f32_16x16x32_bf16 v[16:19], v[16:19], v[120:123], 0
	v_mfma_f32_16x16x32_bf16 v[60:63], v[20:23], v[108:111], v[60:63]
	v_mfma_f32_16x16x32_bf16 v[100:103], v[28:31], v[108:111], v[100:103]
	v_mfma_f32_16x16x32_bf16 v[104:107], v[20:23], v[116:119], v[104:107]
	v_mfma_f32_16x16x32_bf16 v[108:111], v[24:27], v[112:115], 0
	v_mfma_f32_16x16x32_bf16 v[16:19], v[20:23], v[124:127], v[16:19]
	v_mfma_f32_16x16x32_bf16 v[20:23], v[24:27], v[120:123], 0
	v_mfma_f32_16x16x32_bf16 v[108:111], v[28:31], v[116:119], v[108:111]
	v_mfma_f32_16x16x32_bf16 v[20:23], v[28:31], v[124:127], v[20:23]
	s_barrier
	s_setprio 1
	s_add_i32 s78, 0, 0x18000
	s_add_i32 s79, 0, 0x1c000
	v_add_u32_e32 v224, s78, v143
	v_add_u32_e32 v232, s79, v143
	ds_read_b128 v[24:27], v224
	ds_read_b128 v[28:31], v224 offset:1024
	ds_read_b128 v[112:115], v224 offset:2048
	ds_read_b128 v[116:119], v224 offset:3072
	ds_read_b128 v[120:123], v232
	ds_read_b128 v[124:127], v232 offset:1024
	ds_read_b128 v[172:175], v232 offset:2048
	ds_read_b128 v[176:179], v232 offset:3072
	s_add_u32 s86, s58, 0x10100
	s_addc_u32 s87, s59, 0
	s_mov_b32 m0, s51
	v_lshl_add_u64 v[218:219], s[86:87], 0, v[128:129]
	ds_read_b128 v[180:183], v147 offset:32768
	ds_read_b128 v[184:187], v147 offset:33792
	ds_read_b128 v[188:191], v147 offset:34816
	ds_read_b128 v[192:195], v147 offset:35840
	ds_read_b128 v[196:199], v147 offset:36864
	ds_read_b128 v[200:203], v147 offset:37888
	ds_read_b128 v[204:207], v147 offset:38912
	ds_read_b128 v[208:211], v147 offset:39936
	global_load_lds_dwordx4 v[218:219], off
	v_lshl_add_u64 v[218:219], s[86:87], 0, v[132:133]
	s_mov_b32 m0, s57
	s_nop 0
	global_load_lds_dwordx4 v[218:219], off
	s_waitcnt vmcnt(8)
	s_waitcnt lgkmcnt(0)
	s_setprio 0
	s_barrier
	v_mfma_f32_16x16x32_bf16 v[64:67], v[24:27], v[180:183], v[64:67]
	v_mfma_f32_16x16x32_bf16 v[68:71], v[112:115], v[180:183], v[68:71]
	v_mfma_f32_16x16x32_bf16 v[72:75], v[24:27], v[188:191], v[72:75]
	v_mfma_f32_16x16x32_bf16 v[76:79], v[112:115], v[188:191], v[76:79]
	v_mfma_f32_16x16x32_bf16 v[80:83], v[24:27], v[196:199], v[80:83]
	v_mfma_f32_16x16x32_bf16 v[84:87], v[112:115], v[196:199], v[84:87]
	v_mfma_f32_16x16x32_bf16 v[88:91], v[24:27], v[204:207], v[88:91]
	v_mfma_f32_16x16x32_bf16 v[92:95], v[112:115], v[204:207], v[92:95]
	v_mfma_f32_16x16x32_bf16 v[64:67], v[28:31], v[184:187], v[64:67]
	v_mfma_f32_16x16x32_bf16 v[68:71], v[116:119], v[184:187], v[68:71]
	v_mfma_f32_16x16x32_bf16 v[72:75], v[28:31], v[192:195], v[72:75]
	v_mfma_f32_16x16x32_bf16 v[76:79], v[116:119], v[192:195], v[76:79]
	v_mfma_f32_16x16x32_bf16 v[80:83], v[28:31], v[200:203], v[80:83]
	v_mfma_f32_16x16x32_bf16 v[84:87], v[116:119], v[200:203], v[84:87]
	v_mfma_f32_16x16x32_bf16 v[88:91], v[28:31], v[208:211], v[88:91]
	v_mfma_f32_16x16x32_bf16 v[92:95], v[116:119], v[208:211], v[92:95]
	v_mfma_f32_16x16x32_bf16 v[96:99], v[120:123], v[180:183], v[96:99]
	v_mfma_f32_16x16x32_bf16 v[32:35], v[172:175], v[180:183], v[32:35]
	v_mfma_f32_16x16x32_bf16 v[36:39], v[120:123], v[188:191], v[36:39]
	v_mfma_f32_16x16x32_bf16 v[40:43], v[172:175], v[188:191], v[40:43]
	v_mfma_f32_16x16x32_bf16 v[44:47], v[120:123], v[196:199], v[44:47]
	v_mfma_f32_16x16x32_bf16 v[48:51], v[172:175], v[196:199], v[48:51]
	v_mfma_f32_16x16x32_bf16 v[52:55], v[120:123], v[204:207], v[52:55]
	v_mfma_f32_16x16x32_bf16 v[56:59], v[172:175], v[204:207], v[56:59]
	v_mfma_f32_16x16x32_bf16 v[96:99], v[124:127], v[184:187], v[96:99]
	v_mfma_f32_16x16x32_bf16 v[32:35], v[176:179], v[184:187], v[32:35]
	v_mfma_f32_16x16x32_bf16 v[36:39], v[124:127], v[192:195], v[36:39]
	v_mfma_f32_16x16x32_bf16 v[40:43], v[176:179], v[192:195], v[40:43]
	v_mfma_f32_16x16x32_bf16 v[44:47], v[124:127], v[200:203], v[44:47]
	v_mfma_f32_16x16x32_bf16 v[48:51], v[176:179], v[200:203], v[48:51]
	v_mfma_f32_16x16x32_bf16 v[52:55], v[124:127], v[208:211], v[52:55]
	v_mfma_f32_16x16x32_bf16 v[56:59], v[176:179], v[208:211], v[56:59]
	s_barrier
	s_setprio 1
	s_add_i32 s87, s78, s48
	s_add_i32 s86, s87, 0x2000
	v_lshl_add_u64 v[140:141], v[140:141], 0, s[22:23]
	s_mov_b32 m0, s87
	s_add_u32 s88, s60, 0x10180
	ds_read_b128 v[180:183], v147 offset:49152
	ds_read_b128 v[184:187], v147 offset:50176
	ds_read_b128 v[188:191], v147 offset:51200
	ds_read_b128 v[192:195], v147 offset:52224
	ds_read_b128 v[196:199], v147 offset:53248
	ds_read_b128 v[200:203], v147 offset:54272
	ds_read_b128 v[204:207], v147 offset:55296
	ds_read_b128 v[208:211], v147 offset:56320
	global_load_lds_dwordx4 v[140:141], off
	v_lshl_add_u64 v[140:141], v[212:213], 0, s[22:23]
	s_mov_b32 m0, s86
	s_addc_u32 s89, s61, 0
	s_add_i32 s60, s79, s48
	global_load_lds_dwordx4 v[140:141], off
	v_lshl_add_u64 v[140:141], s[88:89], 0, v[130:131]
	s_mov_b32 m0, s60
	s_add_i32 s61, s60, 0x2000
	global_load_lds_dwordx4 v[140:141], off
	v_lshl_add_u64 v[140:141], s[88:89], 0, v[134:135]
	s_mov_b32 m0, s61
	s_nop 0
	global_load_lds_dwordx4 v[140:141], off
	v_lshl_add_u64 v[140:141], v[214:215], 0, s[22:23]
	s_mov_b32 m0, s66
	s_nop 0
	global_load_lds_dwordx4 v[140:141], off
	v_lshl_add_u64 v[140:141], v[216:217], 0, s[22:23]
	s_mov_b32 m0, s67
	s_nop 0
	global_load_lds_dwordx4 v[140:141], off
	s_waitcnt vmcnt(8)
	s_waitcnt lgkmcnt(0)
	s_setprio 0
	s_barrier
	v_mfma_f32_16x16x32_bf16 v[0:3], v[24:27], v[204:207], v[0:3]
	v_mfma_f32_16x16x32_bf16 v[4:7], v[112:115], v[204:207], v[4:7]
	v_mfma_f32_16x16x32_bf16 v[148:151], v[24:27], v[180:183], v[148:151]
	v_mfma_f32_16x16x32_bf16 v[152:155], v[112:115], v[180:183], v[152:155]
	v_mfma_f32_16x16x32_bf16 v[156:159], v[24:27], v[188:191], v[156:159]
	v_mfma_f32_16x16x32_bf16 v[160:163], v[112:115], v[188:191], v[160:163]
	v_mfma_f32_16x16x32_bf16 v[164:167], v[24:27], v[196:199], v[164:167]
	v_mfma_f32_16x16x32_bf16 v[168:171], v[112:115], v[196:199], v[168:171]
	v_mfma_f32_16x16x32_bf16 v[0:3], v[28:31], v[208:211], v[0:3]
	v_mfma_f32_16x16x32_bf16 v[4:7], v[116:119], v[208:211], v[4:7]
	v_mfma_f32_16x16x32_bf16 v[148:151], v[28:31], v[184:187], v[148:151]
	v_mfma_f32_16x16x32_bf16 v[152:155], v[116:119], v[184:187], v[152:155]
	v_mfma_f32_16x16x32_bf16 v[156:159], v[28:31], v[192:195], v[156:159]
	v_mfma_f32_16x16x32_bf16 v[160:163], v[116:119], v[192:195], v[160:163]
	v_mfma_f32_16x16x32_bf16 v[164:167], v[28:31], v[200:203], v[164:167]
	v_mfma_f32_16x16x32_bf16 v[168:171], v[116:119], v[200:203], v[168:171]
	v_mfma_f32_16x16x32_bf16 v[8:11], v[120:123], v[180:183], v[8:11]
	v_mfma_f32_16x16x32_bf16 v[12:15], v[172:175], v[180:183], v[12:15]
	v_mfma_f32_16x16x32_bf16 v[24:27], v[120:123], v[188:191], v[60:63]
	v_mfma_f32_16x16x32_bf16 v[28:31], v[172:175], v[188:191], v[100:103]
	v_mfma_f32_16x16x32_bf16 v[60:63], v[120:123], v[196:199], v[104:107]
	v_mfma_f32_16x16x32_bf16 v[100:103], v[172:175], v[196:199], v[108:111]
	v_mfma_f32_16x16x32_bf16 v[16:19], v[120:123], v[204:207], v[16:19]
	v_mfma_f32_16x16x32_bf16 v[20:23], v[172:175], v[204:207], v[20:23]
	v_mfma_f32_16x16x32_bf16 v[8:11], v[124:127], v[184:187], v[8:11]
	v_mfma_f32_16x16x32_bf16 v[12:15], v[176:179], v[184:187], v[12:15]
	v_mfma_f32_16x16x32_bf16 v[24:27], v[124:127], v[192:195], v[24:27]
	v_mfma_f32_16x16x32_bf16 v[28:31], v[176:179], v[192:195], v[28:31]
	v_mfma_f32_16x16x32_bf16 v[60:63], v[124:127], v[200:203], v[60:63]
	v_mfma_f32_16x16x32_bf16 v[100:103], v[176:179], v[200:203], v[100:103]
	v_mfma_f32_16x16x32_bf16 v[16:19], v[124:127], v[208:211], v[16:19]
	v_mfma_f32_16x16x32_bf16 v[20:23], v[176:179], v[208:211], v[20:23]
	s_barrier
	s_setprio 1
	ds_read_b128 v[104:107], v145
	ds_read_b128 v[108:111], v145 offset:1024
	ds_read_b128 v[112:115], v145 offset:2048
	ds_read_b128 v[116:119], v145 offset:3072
	ds_read_b128 v[120:123], v146
	ds_read_b128 v[124:127], v146 offset:1024
	ds_read_b128 v[172:175], v146 offset:2048
	ds_read_b128 v[176:179], v146 offset:3072
	s_add_u32 s58, s58, 0x10180
	s_addc_u32 s59, s59, 0
	s_mov_b32 m0, s72
	v_lshl_add_u64 v[140:141], s[58:59], 0, v[128:129]
	ds_read_b128 v[180:183], v147
	ds_read_b128 v[184:187], v147 offset:1024
	ds_read_b128 v[188:191], v147 offset:2048
	ds_read_b128 v[192:195], v147 offset:3072
	ds_read_b128 v[196:199], v147 offset:4096
	ds_read_b128 v[200:203], v147 offset:5120
	ds_read_b128 v[204:207], v147 offset:6144
	ds_read_b128 v[208:211], v147 offset:7168
	global_load_lds_dwordx4 v[140:141], off
	v_lshl_add_u64 v[140:141], s[58:59], 0, v[132:133]
	s_mov_b32 m0, s80
	s_nop 0
	global_load_lds_dwordx4 v[140:141], off
	s_waitcnt vmcnt(8)
	s_waitcnt lgkmcnt(0)
	s_setprio 0
	s_barrier
	v_mfma_f32_16x16x32_bf16 v[88:91], v[104:107], v[204:207], v[88:91]
	v_mfma_f32_16x16x32_bf16 v[64:67], v[104:107], v[180:183], v[64:67]
	v_mfma_f32_16x16x32_bf16 v[68:71], v[112:115], v[180:183], v[68:71]
	v_mfma_f32_16x16x32_bf16 v[72:75], v[104:107], v[188:191], v[72:75]
	v_mfma_f32_16x16x32_bf16 v[76:79], v[112:115], v[188:191], v[76:79]
	v_mfma_f32_16x16x32_bf16 v[80:83], v[104:107], v[196:199], v[80:83]
	v_mfma_f32_16x16x32_bf16 v[84:87], v[112:115], v[196:199], v[84:87]
	v_mfma_f32_16x16x32_bf16 v[212:215], v[108:111], v[208:211], v[88:91]
	v_mfma_f32_16x16x32_bf16 v[88:91], v[112:115], v[204:207], v[92:95]
	v_mfma_f32_16x16x32_bf16 v[64:67], v[108:111], v[184:187], v[64:67]
	v_mfma_f32_16x16x32_bf16 v[68:71], v[116:119], v[184:187], v[68:71]
	v_mfma_f32_16x16x32_bf16 v[72:75], v[108:111], v[192:195], v[72:75]
	v_mfma_f32_16x16x32_bf16 v[76:79], v[116:119], v[192:195], v[76:79]
	v_mfma_f32_16x16x32_bf16 v[80:83], v[108:111], v[200:203], v[80:83]
	v_mfma_f32_16x16x32_bf16 v[84:87], v[116:119], v[200:203], v[84:87]
	v_mfma_f32_16x16x32_bf16 v[92:95], v[116:119], v[208:211], v[88:91]
	v_mfma_f32_16x16x32_bf16 v[48:51], v[172:175], v[196:199], v[48:51]
	v_mfma_f32_16x16x32_bf16 v[88:91], v[120:123], v[180:183], v[96:99]
	v_mfma_f32_16x16x32_bf16 v[32:35], v[172:175], v[180:183], v[32:35]
	v_mfma_f32_16x16x32_bf16 v[36:39], v[120:123], v[188:191], v[36:39]
	v_mfma_f32_16x16x32_bf16 v[40:43], v[172:175], v[188:191], v[40:43]
	v_mfma_f32_16x16x32_bf16 v[44:47], v[120:123], v[196:199], v[44:47]
	v_mfma_f32_16x16x32_bf16 v[180:183], v[176:179], v[200:203], v[48:51]
	v_mfma_f32_16x16x32_bf16 v[48:51], v[120:123], v[204:207], v[52:55]
	v_mfma_f32_16x16x32_bf16 v[32:35], v[176:179], v[184:187], v[32:35]
	v_mfma_f32_16x16x32_bf16 v[36:39], v[124:127], v[192:195], v[36:39]
	v_mfma_f32_16x16x32_bf16 v[40:43], v[176:179], v[192:195], v[40:43]
	v_mfma_f32_16x16x32_bf16 v[44:47], v[124:127], v[200:203], v[44:47]
	v_mfma_f32_16x16x32_bf16 v[52:55], v[124:127], v[208:211], v[48:51]
	v_mfma_f32_16x16x32_bf16 v[48:51], v[172:175], v[204:207], v[56:59]
	v_mfma_f32_16x16x32_bf16 v[216:219], v[124:127], v[184:187], v[88:91]
	v_mfma_f32_16x16x32_bf16 v[184:187], v[176:179], v[208:211], v[48:51]
	s_barrier
	s_setprio 1
	s_mov_b32 m0, s85
	v_lshl_add_u64 v[140:141], s[62:63], 0, v[130:131]
	s_add_u32 s58, s62, 0x10000
	s_nop 0
	ds_read_b128 v[48:51], v147 offset:16384
	ds_read_b128 v[56:59], v147 offset:17408
	ds_read_b128 v[88:91], v147 offset:18432
	ds_read_b128 v[96:99], v147 offset:19456
	ds_read_b128 v[188:191], v147 offset:20480
	ds_read_b128 v[192:195], v147 offset:21504
	ds_read_b128 v[196:199], v147 offset:22528
	ds_read_b128 v[200:203], v147 offset:23552
	global_load_lds_dwordx4 v[140:141], off
	v_lshl_add_u64 v[252:253], s[62:63], 0, v[134:135]
	s_mov_b32 m0, s35
	s_addc_u32 s59, s63, 0
	global_load_lds_dwordx4 v[252:253], off
	v_lshl_add_u64 v[204:205], s[58:59], 0, v[130:131]
	s_mov_b32 m0, s37
	v_lshl_add_u64 v[136:137], s[64:65], 0, v[128:129]
	global_load_lds_dwordx4 v[204:205], off
	v_lshl_add_u64 v[204:205], s[58:59], 0, v[134:135]
	s_mov_b32 m0, s47
	v_lshl_add_u64 v[138:139], s[64:65], 0, v[132:133]
	global_load_lds_dwordx4 v[204:205], off
	s_mov_b32 m0, s49
	s_nop 0
	global_load_lds_dwordx4 v[136:137], off
	s_mov_b32 m0, s50
	s_nop 0
	global_load_lds_dwordx4 v[138:139], off
	s_waitcnt vmcnt(8)
	s_waitcnt lgkmcnt(0)
	s_setprio 0
	s_barrier
	v_mfma_f32_16x16x32_bf16 v[0:3], v[104:107], v[196:199], v[0:3]
	v_mfma_f32_16x16x32_bf16 v[4:7], v[112:115], v[196:199], v[4:7]
	v_mfma_f32_16x16x32_bf16 v[148:151], v[104:107], v[48:51], v[148:151]
	v_mfma_f32_16x16x32_bf16 v[152:155], v[112:115], v[48:51], v[152:155]
	v_mfma_f32_16x16x32_bf16 v[156:159], v[104:107], v[88:91], v[156:159]
	v_mfma_f32_16x16x32_bf16 v[160:163], v[112:115], v[88:91], v[160:163]
	v_mfma_f32_16x16x32_bf16 v[164:167], v[104:107], v[188:191], v[164:167]
	v_mfma_f32_16x16x32_bf16 v[168:171], v[112:115], v[188:191], v[168:171]
	v_mfma_f32_16x16x32_bf16 v[0:3], v[108:111], v[200:203], v[0:3]
	v_mfma_f32_16x16x32_bf16 v[4:7], v[116:119], v[200:203], v[4:7]
	v_mfma_f32_16x16x32_bf16 v[148:151], v[108:111], v[56:59], v[148:151]
	v_mfma_f32_16x16x32_bf16 v[152:155], v[116:119], v[56:59], v[152:155]
	v_mfma_f32_16x16x32_bf16 v[156:159], v[108:111], v[96:99], v[156:159]
	v_mfma_f32_16x16x32_bf16 v[160:163], v[116:119], v[96:99], v[160:163]
	v_mfma_f32_16x16x32_bf16 v[164:167], v[108:111], v[192:195], v[164:167]
	v_mfma_f32_16x16x32_bf16 v[168:171], v[116:119], v[192:195], v[168:171]
	v_mfma_f32_16x16x32_bf16 v[12:15], v[172:175], v[48:51], v[12:15]
	v_mfma_f32_16x16x32_bf16 v[204:207], v[176:179], v[56:59], v[12:15]
	v_mfma_f32_16x16x32_bf16 v[12:15], v[120:123], v[88:91], v[24:27]
	v_mfma_f32_16x16x32_bf16 v[24:27], v[124:127], v[96:99], v[12:15]
	v_mfma_f32_16x16x32_bf16 v[12:15], v[172:175], v[88:91], v[28:31]
	v_mfma_f32_16x16x32_bf16 v[208:211], v[176:179], v[96:99], v[12:15]
	v_mfma_f32_16x16x32_bf16 v[12:15], v[120:123], v[188:191], v[60:63]
	v_mfma_f32_16x16x32_bf16 v[220:223], v[124:127], v[192:195], v[12:15]
	v_mfma_f32_16x16x32_bf16 v[12:15], v[172:175], v[188:191], v[100:103]
	v_mfma_f32_16x16x32_bf16 v[8:11], v[120:123], v[48:51], v[8:11]
	v_mfma_f32_16x16x32_bf16 v[188:191], v[176:179], v[192:195], v[12:15]
	v_mfma_f32_16x16x32_bf16 v[12:15], v[120:123], v[196:199], v[16:19]
	v_mfma_f32_16x16x32_bf16 v[8:11], v[124:127], v[56:59], v[8:11]
	v_mfma_f32_16x16x32_bf16 v[192:195], v[124:127], v[200:203], v[12:15]
	v_mfma_f32_16x16x32_bf16 v[12:15], v[172:175], v[196:199], v[20:23]
	v_mfma_f32_16x16x32_bf16 v[172:175], v[176:179], v[200:203], v[12:15]
	s_barrier
	s_setprio 1
	s_nop 4
	ds_read_b128 v[12:15], v224
	ds_read_b128 v[16:19], v224 offset:1024
	ds_read_b128 v[176:179], v224 offset:2048
	ds_read_b128 v[196:199], v224 offset:3072
	ds_read_b128 v[200:203], v232
	ds_read_b128 v[224:227], v232 offset:1024
	ds_read_b128 v[228:231], v232 offset:2048
	ds_read_b128 v[232:235], v232 offset:3072
	s_add_u32 s58, s64, 0x10000
	s_addc_u32 s59, s65, 0
	s_mov_b32 m0, s51
	v_lshl_add_u64 v[48:49], s[58:59], 0, v[128:129]
	ds_read_b128 v[20:23], v147 offset:32768
	ds_read_b128 v[28:31], v147 offset:33792
	ds_read_b128 v[60:63], v147 offset:34816
	ds_read_b128 v[100:103], v147 offset:35840
	ds_read_b128 v[236:239], v147 offset:36864
	ds_read_b128 v[240:243], v147 offset:37888
	ds_read_b128 v[244:247], v147 offset:38912
	ds_read_b128 v[248:251], v147 offset:39936
	global_load_lds_dwordx4 v[48:49], off
	v_lshl_add_u64 v[48:49], s[58:59], 0, v[132:133]
	s_mov_b32 m0, s57
	s_nop 0
	global_load_lds_dwordx4 v[48:49], off
	s_waitcnt vmcnt(8)
	s_waitcnt lgkmcnt(0)
	s_setprio 0
	s_barrier
	v_mfma_f32_16x16x32_bf16 v[48:51], v[12:15], v[20:23], v[64:67]
	v_mfma_f32_16x16x32_bf16 v[120:123], v[16:19], v[28:31], v[48:51]
	v_mfma_f32_16x16x32_bf16 v[48:51], v[176:179], v[20:23], v[68:71]
	v_mfma_f32_16x16x32_bf16 v[112:115], v[196:199], v[28:31], v[48:51]
	v_mfma_f32_16x16x32_bf16 v[48:51], v[12:15], v[60:63], v[72:75]
	v_mfma_f32_16x16x32_bf16 v[104:107], v[16:19], v[100:103], v[48:51]
	v_mfma_f32_16x16x32_bf16 v[48:51], v[176:179], v[60:63], v[76:79]
	v_mfma_f32_16x16x32_bf16 v[96:99], v[196:199], v[100:103], v[48:51]
	v_mfma_f32_16x16x32_bf16 v[48:51], v[12:15], v[236:239], v[80:83]
	v_mfma_f32_16x16x32_bf16 v[88:91], v[16:19], v[240:243], v[48:51]
	v_mfma_f32_16x16x32_bf16 v[48:51], v[176:179], v[236:239], v[84:87]
	v_mfma_f32_16x16x32_bf16 v[80:83], v[196:199], v[240:243], v[48:51]
	v_mfma_f32_16x16x32_bf16 v[48:51], v[12:15], v[244:247], v[212:215]
	v_mfma_f32_16x16x32_bf16 v[56:59], v[16:19], v[248:251], v[48:51]
	v_mfma_f32_16x16x32_bf16 v[48:51], v[176:179], v[244:247], v[92:95]
	v_mfma_f32_16x16x32_bf16 v[48:51], v[196:199], v[248:251], v[48:51]
	v_mfma_f32_16x16x32_bf16 v[64:67], v[200:203], v[20:23], v[216:219]
	v_mfma_f32_16x16x32_bf16 v[20:23], v[228:231], v[20:23], v[32:35]
	v_mfma_f32_16x16x32_bf16 v[116:119], v[232:235], v[28:31], v[20:23]
	v_mfma_f32_16x16x32_bf16 v[20:23], v[200:203], v[60:63], v[36:39]
	v_mfma_f32_16x16x32_bf16 v[108:111], v[224:227], v[100:103], v[20:23]
	v_mfma_f32_16x16x32_bf16 v[20:23], v[228:231], v[60:63], v[40:43]
	v_mfma_f32_16x16x32_bf16 v[100:103], v[232:235], v[100:103], v[20:23]
	v_mfma_f32_16x16x32_bf16 v[20:23], v[200:203], v[236:239], v[44:47]
	v_mfma_f32_16x16x32_bf16 v[92:95], v[224:227], v[240:243], v[20:23]
	v_mfma_f32_16x16x32_bf16 v[20:23], v[228:231], v[236:239], v[180:183]
	v_mfma_f32_16x16x32_bf16 v[84:87], v[232:235], v[240:243], v[20:23]
	v_mfma_f32_16x16x32_bf16 v[20:23], v[200:203], v[244:247], v[52:55]
	v_mfma_f32_16x16x32_bf16 v[60:63], v[224:227], v[248:251], v[20:23]
	v_mfma_f32_16x16x32_bf16 v[20:23], v[228:231], v[244:247], v[184:187]
	v_mfma_f32_16x16x32_bf16 v[124:127], v[224:227], v[28:31], v[64:67]
	v_mfma_f32_16x16x32_bf16 v[52:55], v[232:235], v[248:251], v[20:23]
	s_barrier
	s_setprio 1
	s_mov_b32 m0, s87
	s_nop 2
	v_lshl_add_u64 v[20:21], v[140:141], 0, s[14:15]
	s_add_u32 s58, s62, 0x10080
	ds_read_b128 v[32:35], v147 offset:49152
	ds_read_b128 v[40:43], v147 offset:50176
	ds_read_b128 v[180:183], v147 offset:51200
	ds_read_b128 v[184:187], v147 offset:52224
	ds_read_b128 v[212:215], v147 offset:53248
	ds_read_b128 v[216:219], v147 offset:54272
	ds_read_b128 v[236:239], v147 offset:55296
	ds_read_b128 v[240:243], v147 offset:56320
	global_load_lds_dwordx4 v[20:21], off
	v_lshl_add_u64 v[20:21], v[252:253], 0, s[14:15]
	s_mov_b32 m0, s86
	s_addc_u32 s59, s63, 0
	global_load_lds_dwordx4 v[20:21], off
	v_lshl_add_u64 v[20:21], s[58:59], 0, v[130:131]
	s_mov_b32 m0, s60
	s_nop 0
	global_load_lds_dwordx4 v[20:21], off
	v_lshl_add_u64 v[20:21], s[58:59], 0, v[134:135]
	s_mov_b32 m0, s61
	s_nop 0
	global_load_lds_dwordx4 v[20:21], off
	v_lshl_add_u64 v[20:21], v[136:137], 0, s[14:15]
	s_mov_b32 m0, s66
	s_nop 0
	global_load_lds_dwordx4 v[20:21], off
	v_lshl_add_u64 v[20:21], v[138:139], 0, s[14:15]
	s_mov_b32 m0, s67
	s_nop 0
	global_load_lds_dwordx4 v[20:21], off
	s_waitcnt vmcnt(8)
	s_waitcnt lgkmcnt(0)
	s_setprio 0
	s_barrier
	v_mfma_f32_16x16x32_bf16 v[20:23], v[12:15], v[32:35], v[148:151]
	v_mfma_f32_16x16x32_bf16 v[76:79], v[16:19], v[40:43], v[20:23]
	v_mfma_f32_16x16x32_bf16 v[20:23], v[176:179], v[32:35], v[152:155]
	v_mfma_f32_16x16x32_bf16 v[68:71], v[196:199], v[40:43], v[20:23]
	v_mfma_f32_16x16x32_bf16 v[20:23], v[12:15], v[180:183], v[156:159]
	v_mfma_f32_16x16x32_bf16 v[44:47], v[16:19], v[184:187], v[20:23]
	v_mfma_f32_16x16x32_bf16 v[20:23], v[176:179], v[180:183], v[160:163]
	v_mfma_f32_16x16x32_bf16 v[36:39], v[196:199], v[184:187], v[20:23]
	v_mfma_f32_16x16x32_bf16 v[20:23], v[12:15], v[212:215], v[164:167]
	v_mfma_f32_16x16x32_bf16 v[0:3], v[12:15], v[236:239], v[0:3]
	v_mfma_f32_16x16x32_bf16 v[28:31], v[16:19], v[216:219], v[20:23]
	v_mfma_f32_16x16x32_bf16 v[20:23], v[176:179], v[212:215], v[168:171]
	v_mfma_f32_16x16x32_bf16 v[12:15], v[16:19], v[240:243], v[0:3]
	v_mfma_f32_16x16x32_bf16 v[0:3], v[176:179], v[236:239], v[4:7]
	v_mfma_f32_16x16x32_bf16 v[20:23], v[196:199], v[216:219], v[20:23]
	v_mfma_f32_16x16x32_bf16 v[4:7], v[196:199], v[240:243], v[0:3]
	v_mfma_f32_16x16x32_bf16 v[0:3], v[200:203], v[32:35], v[8:11]
	v_mfma_f32_16x16x32_bf16 v[72:75], v[224:227], v[40:43], v[0:3]
	v_mfma_f32_16x16x32_bf16 v[0:3], v[228:231], v[32:35], v[204:207]
	v_mfma_f32_16x16x32_bf16 v[64:67], v[232:235], v[40:43], v[0:3]
	v_mfma_f32_16x16x32_bf16 v[0:3], v[200:203], v[180:183], v[24:27]
	v_mfma_f32_16x16x32_bf16 v[40:43], v[224:227], v[184:187], v[0:3]
	v_mfma_f32_16x16x32_bf16 v[0:3], v[228:231], v[180:183], v[208:211]
	v_mfma_f32_16x16x32_bf16 v[32:35], v[232:235], v[184:187], v[0:3]
	v_mfma_f32_16x16x32_bf16 v[0:3], v[200:203], v[212:215], v[220:223]
	v_mfma_f32_16x16x32_bf16 v[24:27], v[224:227], v[216:219], v[0:3]
	v_mfma_f32_16x16x32_bf16 v[0:3], v[228:231], v[212:215], v[188:191]
	v_mfma_f32_16x16x32_bf16 v[16:19], v[232:235], v[216:219], v[0:3]
	v_mfma_f32_16x16x32_bf16 v[0:3], v[200:203], v[236:239], v[192:195]
	v_mfma_f32_16x16x32_bf16 v[8:11], v[224:227], v[240:243], v[0:3]
	v_mfma_f32_16x16x32_bf16 v[0:3], v[228:231], v[236:239], v[172:175]
	v_mfma_f32_16x16x32_bf16 v[0:3], v[232:235], v[240:243], v[0:3]
	s_barrier
	s_setprio 1
	s_andn2_b64 vcc, exec, s[16:17]
	s_cbranch_vccnz .LBB0_710
	s_barrier

.LBB0_731:
	ds_read_b128 v[146:149], v153
	ds_read_b128 v[158:161], v153 offset:1024
	ds_read_b128 v[162:165], v153 offset:2048
	ds_read_b128 v[166:169], v153 offset:3072
	ds_read_b128 v[170:173], v154
	ds_read_b128 v[174:177], v154 offset:1024
	ds_read_b128 v[178:181], v154 offset:2048
	ds_read_b128 v[182:185], v154 offset:3072
	s_add_u32 s34, s30, 0xfff80080
	s_addc_u32 s35, s31, -1
	s_cmp_eq_u32 s61, 28
	s_cselect_b32 s37, s21, s35
	s_cselect_b32 s36, s46, s34
	s_cselect_b32 s35, s19, s60
	s_cselect_b32 s34, s47, s59
	v_lshl_add_u64 v[218:219], s[30:31], 0, v[140:141]
	s_add_i32 m0, s27, 0xc000
	ds_read_b128 v[186:189], v155
	ds_read_b128 v[190:193], v155 offset:1024
	ds_read_b128 v[194:197], v155 offset:2048
	ds_read_b128 v[198:201], v155 offset:3072
	ds_read_b128 v[202:205], v155 offset:4096
	ds_read_b128 v[206:209], v155 offset:5120
	ds_read_b128 v[210:213], v155 offset:6144
	ds_read_b128 v[214:217], v155 offset:7168
	global_load_lds_dwordx4 v[218:219], off
	v_lshl_add_u64 v[218:219], s[30:31], 0, v[138:139]
	s_add_i32 m0, s27, 0xe000
	s_nop 0
	global_load_lds_dwordx4 v[218:219], off
	s_waitcnt vmcnt(8)
	s_waitcnt lgkmcnt(0)
	s_setprio 0
	s_barrier
	v_mfma_f32_16x16x32_bf16 v[124:127], v[146:149], v[186:189], v[124:127]
	v_mfma_f32_16x16x32_bf16 v[120:123], v[162:165], v[186:189], v[120:123]
	v_mfma_f32_16x16x32_bf16 v[108:111], v[146:149], v[194:197], v[108:111]
	v_mfma_f32_16x16x32_bf16 v[104:107], v[162:165], v[194:197], v[104:107]
	v_mfma_f32_16x16x32_bf16 v[92:95], v[146:149], v[202:205], v[92:95]
	v_mfma_f32_16x16x32_bf16 v[88:91], v[162:165], v[202:205], v[88:91]
	v_mfma_f32_16x16x32_bf16 v[76:79], v[146:149], v[210:213], v[76:79]
	v_mfma_f32_16x16x32_bf16 v[72:75], v[162:165], v[210:213], v[72:75]
	v_mfma_f32_16x16x32_bf16 v[124:127], v[158:161], v[190:193], v[124:127]
	v_mfma_f32_16x16x32_bf16 v[120:123], v[166:169], v[190:193], v[120:123]
	v_mfma_f32_16x16x32_bf16 v[108:111], v[158:161], v[198:201], v[108:111]
	v_mfma_f32_16x16x32_bf16 v[104:107], v[166:169], v[198:201], v[104:107]
	v_mfma_f32_16x16x32_bf16 v[92:95], v[158:161], v[206:209], v[92:95]
	v_mfma_f32_16x16x32_bf16 v[88:91], v[166:169], v[206:209], v[88:91]
	v_mfma_f32_16x16x32_bf16 v[76:79], v[158:161], v[214:217], v[76:79]
	v_mfma_f32_16x16x32_bf16 v[72:75], v[166:169], v[214:217], v[72:75]
	v_mfma_f32_16x16x32_bf16 v[116:119], v[170:173], v[186:189], v[116:119]
	v_mfma_f32_16x16x32_bf16 v[112:115], v[178:181], v[186:189], v[112:115]
	v_mfma_f32_16x16x32_bf16 v[100:103], v[170:173], v[194:197], v[100:103]
	v_mfma_f32_16x16x32_bf16 v[96:99], v[178:181], v[194:197], v[96:99]
	v_mfma_f32_16x16x32_bf16 v[84:87], v[170:173], v[202:205], v[84:87]
	v_mfma_f32_16x16x32_bf16 v[80:83], v[178:181], v[202:205], v[80:83]
	v_mfma_f32_16x16x32_bf16 v[68:71], v[170:173], v[210:213], v[68:71]
	v_mfma_f32_16x16x32_bf16 v[64:67], v[178:181], v[210:213], v[64:67]
	v_mfma_f32_16x16x32_bf16 v[116:119], v[174:177], v[190:193], v[116:119]
	v_mfma_f32_16x16x32_bf16 v[112:115], v[182:185], v[190:193], v[112:115]
	v_mfma_f32_16x16x32_bf16 v[100:103], v[174:177], v[198:201], v[100:103]
	v_mfma_f32_16x16x32_bf16 v[96:99], v[182:185], v[198:201], v[96:99]
	v_mfma_f32_16x16x32_bf16 v[84:87], v[174:177], v[206:209], v[84:87]
	v_mfma_f32_16x16x32_bf16 v[80:83], v[182:185], v[206:209], v[80:83]
	v_mfma_f32_16x16x32_bf16 v[68:71], v[174:177], v[214:217], v[68:71]
	v_mfma_f32_16x16x32_bf16 v[64:67], v[182:185], v[214:217], v[64:67]
	s_barrier
	s_setprio 1
	s_add_i32 s62, s55, s48
	v_lshl_add_u64 v[218:219], s[34:35], 0, v[130:131]
	s_mov_b32 m0, s62
	ds_read_b128 v[186:189], v155 offset:16384
	ds_read_b128 v[190:193], v155 offset:17408
	ds_read_b128 v[194:197], v155 offset:18432
	ds_read_b128 v[198:201], v155 offset:19456
	ds_read_b128 v[202:205], v155 offset:20480
	ds_read_b128 v[206:209], v155 offset:21504
	ds_read_b128 v[210:213], v155 offset:22528
	ds_read_b128 v[214:217], v155 offset:23552
	global_load_lds_dwordx4 v[218:219], off
	s_add_i32 m0, s62, 0x2000
	s_add_u32 s62, s34, 0x80000
	v_lshl_add_u64 v[220:221], s[34:35], 0, v[134:135]
	s_addc_u32 s63, s35, 0
	s_add_i32 s64, s56, s48
	global_load_lds_dwordx4 v[220:221], off
	v_lshl_add_u64 v[222:223], s[62:63], 0, v[130:131]
	s_mov_b32 m0, s64
	v_lshl_add_u64 v[224:225], s[36:37], 0, v[132:133]
	global_load_lds_dwordx4 v[222:223], off
	v_lshl_add_u64 v[222:223], s[62:63], 0, v[134:135]
	s_add_i32 m0, s64, 0x2000
	s_nop 0
	global_load_lds_dwordx4 v[222:223], off
	v_lshl_add_u64 v[222:223], s[36:37], 0, v[128:129]
	s_mov_b32 m0, s27
	s_nop 0
	global_load_lds_dwordx4 v[222:223], off
	s_mov_b32 m0, s49
	s_nop 0
	global_load_lds_dwordx4 v[224:225], off
	s_waitcnt vmcnt(8)
	s_waitcnt lgkmcnt(0)
	s_setprio 0
	s_barrier
	v_mfma_f32_16x16x32_bf16 v[60:63], v[146:149], v[186:189], v[60:63]
	v_mfma_f32_16x16x32_bf16 v[56:59], v[162:165], v[186:189], v[56:59]
	v_mfma_f32_16x16x32_bf16 v[44:47], v[146:149], v[194:197], v[44:47]
	v_mfma_f32_16x16x32_bf16 v[40:43], v[162:165], v[194:197], v[40:43]
	v_mfma_f32_16x16x32_bf16 v[28:31], v[146:149], v[202:205], v[28:31]
	v_mfma_f32_16x16x32_bf16 v[24:27], v[162:165], v[202:205], v[24:27]
	v_mfma_f32_16x16x32_bf16 v[12:15], v[146:149], v[210:213], v[12:15]
	v_mfma_f32_16x16x32_bf16 v[8:11], v[162:165], v[210:213], v[8:11]
	v_mfma_f32_16x16x32_bf16 v[60:63], v[158:161], v[190:193], v[60:63]
	v_mfma_f32_16x16x32_bf16 v[56:59], v[166:169], v[190:193], v[56:59]
	v_mfma_f32_16x16x32_bf16 v[44:47], v[158:161], v[198:201], v[44:47]
	v_mfma_f32_16x16x32_bf16 v[40:43], v[166:169], v[198:201], v[40:43]
	v_mfma_f32_16x16x32_bf16 v[28:31], v[158:161], v[206:209], v[28:31]
	v_mfma_f32_16x16x32_bf16 v[24:27], v[166:169], v[206:209], v[24:27]
	v_mfma_f32_16x16x32_bf16 v[12:15], v[158:161], v[214:217], v[12:15]
	v_mfma_f32_16x16x32_bf16 v[8:11], v[166:169], v[214:217], v[8:11]
	v_mfma_f32_16x16x32_bf16 v[52:55], v[170:173], v[186:189], v[52:55]
	v_mfma_f32_16x16x32_bf16 v[48:51], v[178:181], v[186:189], v[48:51]
	v_mfma_f32_16x16x32_bf16 v[36:39], v[170:173], v[194:197], v[36:39]
	v_mfma_f32_16x16x32_bf16 v[32:35], v[178:181], v[194:197], v[32:35]
	v_mfma_f32_16x16x32_bf16 v[20:23], v[170:173], v[202:205], v[20:23]
	v_mfma_f32_16x16x32_bf16 v[16:19], v[178:181], v[202:205], v[16:19]
	v_mfma_f32_16x16x32_bf16 v[4:7], v[170:173], v[210:213], v[4:7]
	v_mfma_f32_16x16x32_bf16 v[0:3], v[178:181], v[210:213], v[0:3]
	v_mfma_f32_16x16x32_bf16 v[52:55], v[174:177], v[190:193], v[52:55]
	v_mfma_f32_16x16x32_bf16 v[48:51], v[182:185], v[190:193], v[48:51]
	v_mfma_f32_16x16x32_bf16 v[36:39], v[174:177], v[198:201], v[36:39]
	v_mfma_f32_16x16x32_bf16 v[32:35], v[182:185], v[198:201], v[32:35]
	v_mfma_f32_16x16x32_bf16 v[20:23], v[174:177], v[206:209], v[20:23]
	v_mfma_f32_16x16x32_bf16 v[16:19], v[182:185], v[206:209], v[16:19]
	v_mfma_f32_16x16x32_bf16 v[4:7], v[174:177], v[214:217], v[4:7]
	v_mfma_f32_16x16x32_bf16 v[0:3], v[182:185], v[214:217], v[0:3]
	s_barrier
	s_setprio 1
	s_add_i32 s62, 0, 0x18000
	s_add_i32 s63, 0, 0x1c000
	v_add_u32_e32 v166, s62, v151
	v_add_u32_e32 v182, s63, v151
	ds_read_b128 v[146:149], v166
	ds_read_b128 v[158:161], v166 offset:1024
	ds_read_b128 v[162:165], v166 offset:2048
	ds_read_b128 v[166:169], v166 offset:3072
	ds_read_b128 v[170:173], v182
	ds_read_b128 v[174:177], v182 offset:1024
	ds_read_b128 v[178:181], v182 offset:2048
	ds_read_b128 v[182:185], v182 offset:3072
	s_add_u32 s36, s36, 0x80000
	s_addc_u32 s37, s37, 0
	s_mov_b32 m0, s50
	v_lshl_add_u64 v[226:227], s[36:37], 0, v[128:129]
	ds_read_b128 v[186:189], v155 offset:32768
	ds_read_b128 v[190:193], v155 offset:33792
	ds_read_b128 v[194:197], v155 offset:34816
	ds_read_b128 v[198:201], v155 offset:35840
	ds_read_b128 v[202:205], v155 offset:36864
	ds_read_b128 v[206:209], v155 offset:37888
	ds_read_b128 v[210:213], v155 offset:38912
	ds_read_b128 v[214:217], v155 offset:39936
	global_load_lds_dwordx4 v[226:227], off
	v_lshl_add_u64 v[226:227], s[36:37], 0, v[132:133]
	s_mov_b32 m0, s51
	s_nop 0
	global_load_lds_dwordx4 v[226:227], off
	s_waitcnt vmcnt(8)
	s_waitcnt lgkmcnt(0)
	s_setprio 0
	s_barrier
	v_mfma_f32_16x16x32_bf16 v[124:127], v[146:149], v[186:189], v[124:127]
	v_mfma_f32_16x16x32_bf16 v[120:123], v[162:165], v[186:189], v[120:123]
	v_mfma_f32_16x16x32_bf16 v[108:111], v[146:149], v[194:197], v[108:111]
	v_mfma_f32_16x16x32_bf16 v[104:107], v[162:165], v[194:197], v[104:107]
	v_mfma_f32_16x16x32_bf16 v[92:95], v[146:149], v[202:205], v[92:95]
	v_mfma_f32_16x16x32_bf16 v[88:91], v[162:165], v[202:205], v[88:91]
	v_mfma_f32_16x16x32_bf16 v[76:79], v[146:149], v[210:213], v[76:79]
	v_mfma_f32_16x16x32_bf16 v[72:75], v[162:165], v[210:213], v[72:75]
	v_mfma_f32_16x16x32_bf16 v[124:127], v[158:161], v[190:193], v[124:127]
	v_mfma_f32_16x16x32_bf16 v[120:123], v[166:169], v[190:193], v[120:123]
	v_mfma_f32_16x16x32_bf16 v[108:111], v[158:161], v[198:201], v[108:111]
	v_mfma_f32_16x16x32_bf16 v[104:107], v[166:169], v[198:201], v[104:107]
	v_mfma_f32_16x16x32_bf16 v[92:95], v[158:161], v[206:209], v[92:95]
	v_mfma_f32_16x16x32_bf16 v[88:91], v[166:169], v[206:209], v[88:91]
	v_mfma_f32_16x16x32_bf16 v[76:79], v[158:161], v[214:217], v[76:79]
	v_mfma_f32_16x16x32_bf16 v[72:75], v[166:169], v[214:217], v[72:75]
	v_mfma_f32_16x16x32_bf16 v[116:119], v[170:173], v[186:189], v[116:119]
	v_mfma_f32_16x16x32_bf16 v[112:115], v[178:181], v[186:189], v[112:115]
	v_mfma_f32_16x16x32_bf16 v[100:103], v[170:173], v[194:197], v[100:103]
	v_mfma_f32_16x16x32_bf16 v[96:99], v[178:181], v[194:197], v[96:99]
	v_mfma_f32_16x16x32_bf16 v[84:87], v[170:173], v[202:205], v[84:87]
	v_mfma_f32_16x16x32_bf16 v[80:83], v[178:181], v[202:205], v[80:83]
	v_mfma_f32_16x16x32_bf16 v[68:71], v[170:173], v[210:213], v[68:71]
	v_mfma_f32_16x16x32_bf16 v[64:67], v[178:181], v[210:213], v[64:67]
	v_mfma_f32_16x16x32_bf16 v[116:119], v[174:177], v[190:193], v[116:119]
	v_mfma_f32_16x16x32_bf16 v[112:115], v[182:185], v[190:193], v[112:115]
	v_mfma_f32_16x16x32_bf16 v[100:103], v[174:177], v[198:201], v[100:103]
	v_mfma_f32_16x16x32_bf16 v[96:99], v[182:185], v[198:201], v[96:99]
	v_mfma_f32_16x16x32_bf16 v[84:87], v[174:177], v[206:209], v[84:87]
	v_mfma_f32_16x16x32_bf16 v[80:83], v[182:185], v[206:209], v[80:83]
	v_mfma_f32_16x16x32_bf16 v[68:71], v[174:177], v[214:217], v[68:71]
	v_mfma_f32_16x16x32_bf16 v[64:67], v[182:185], v[214:217], v[64:67]
	s_barrier
	s_setprio 1
	s_add_i32 s36, s62, s48
	v_lshl_add_u64 v[218:219], v[218:219], 0, s[14:15]
	s_mov_b32 m0, s36
	ds_read_b128 v[186:189], v155 offset:49152
	ds_read_b128 v[190:193], v155 offset:50176
	ds_read_b128 v[194:197], v155 offset:51200
	ds_read_b128 v[198:201], v155 offset:52224
	ds_read_b128 v[202:205], v155 offset:53248
	ds_read_b128 v[206:209], v155 offset:54272
	ds_read_b128 v[210:213], v155 offset:55296
	ds_read_b128 v[214:217], v155 offset:56320
	global_load_lds_dwordx4 v[218:219], off
	s_add_i32 m0, s36, 0x2000
	s_add_u32 s34, s34, 0x80080
	v_lshl_add_u64 v[218:219], v[220:221], 0, s[14:15]
	s_addc_u32 s35, s35, 0
	s_add_i32 s36, s63, s48
	global_load_lds_dwordx4 v[218:219], off
	v_lshl_add_u64 v[218:219], s[34:35], 0, v[130:131]
	s_mov_b32 m0, s36
	s_nop 0
	global_load_lds_dwordx4 v[218:219], off
	v_lshl_add_u64 v[218:219], s[34:35], 0, v[134:135]
	s_add_i32 m0, s36, 0x2000
	s_nop 0
	global_load_lds_dwordx4 v[218:219], off
	v_lshl_add_u64 v[218:219], v[222:223], 0, s[14:15]
	s_mov_b32 m0, s53
	s_nop 0
	global_load_lds_dwordx4 v[218:219], off
	v_lshl_add_u64 v[218:219], v[224:225], 0, s[14:15]
	s_mov_b32 m0, s54
	s_nop 0
	global_load_lds_dwordx4 v[218:219], off
	s_waitcnt vmcnt(8)
	s_waitcnt lgkmcnt(0)
	s_setprio 0
	s_barrier
	v_mfma_f32_16x16x32_bf16 v[60:63], v[146:149], v[186:189], v[60:63]
	v_mfma_f32_16x16x32_bf16 v[56:59], v[162:165], v[186:189], v[56:59]
	v_mfma_f32_16x16x32_bf16 v[44:47], v[146:149], v[194:197], v[44:47]
	v_mfma_f32_16x16x32_bf16 v[40:43], v[162:165], v[194:197], v[40:43]
	v_mfma_f32_16x16x32_bf16 v[28:31], v[146:149], v[202:205], v[28:31]
	v_mfma_f32_16x16x32_bf16 v[24:27], v[162:165], v[202:205], v[24:27]
	v_mfma_f32_16x16x32_bf16 v[12:15], v[146:149], v[210:213], v[12:15]
	v_mfma_f32_16x16x32_bf16 v[8:11], v[162:165], v[210:213], v[8:11]
	v_mfma_f32_16x16x32_bf16 v[60:63], v[158:161], v[190:193], v[60:63]
	v_mfma_f32_16x16x32_bf16 v[56:59], v[166:169], v[190:193], v[56:59]
	v_mfma_f32_16x16x32_bf16 v[44:47], v[158:161], v[198:201], v[44:47]
	v_mfma_f32_16x16x32_bf16 v[40:43], v[166:169], v[198:201], v[40:43]
	v_mfma_f32_16x16x32_bf16 v[28:31], v[158:161], v[206:209], v[28:31]
	v_mfma_f32_16x16x32_bf16 v[24:27], v[166:169], v[206:209], v[24:27]
	v_mfma_f32_16x16x32_bf16 v[12:15], v[158:161], v[214:217], v[12:15]
	v_mfma_f32_16x16x32_bf16 v[8:11], v[166:169], v[214:217], v[8:11]
	v_mfma_f32_16x16x32_bf16 v[52:55], v[170:173], v[186:189], v[52:55]
	v_mfma_f32_16x16x32_bf16 v[48:51], v[178:181], v[186:189], v[48:51]
	v_mfma_f32_16x16x32_bf16 v[36:39], v[170:173], v[194:197], v[36:39]
	v_mfma_f32_16x16x32_bf16 v[32:35], v[178:181], v[194:197], v[32:35]
	v_mfma_f32_16x16x32_bf16 v[20:23], v[170:173], v[202:205], v[20:23]
	v_mfma_f32_16x16x32_bf16 v[16:19], v[178:181], v[202:205], v[16:19]
	v_mfma_f32_16x16x32_bf16 v[4:7], v[170:173], v[210:213], v[4:7]
	v_mfma_f32_16x16x32_bf16 v[0:3], v[178:181], v[210:213], v[0:3]
	v_mfma_f32_16x16x32_bf16 v[52:55], v[174:177], v[190:193], v[52:55]
	v_mfma_f32_16x16x32_bf16 v[48:51], v[182:185], v[190:193], v[48:51]
	v_mfma_f32_16x16x32_bf16 v[36:39], v[174:177], v[198:201], v[36:39]
	v_mfma_f32_16x16x32_bf16 v[32:35], v[182:185], v[198:201], v[32:35]
	v_mfma_f32_16x16x32_bf16 v[20:23], v[174:177], v[206:209], v[20:23]
	v_mfma_f32_16x16x32_bf16 v[16:19], v[182:185], v[206:209], v[16:19]
	v_mfma_f32_16x16x32_bf16 v[4:7], v[174:177], v[214:217], v[4:7]
	v_mfma_f32_16x16x32_bf16 v[0:3], v[182:185], v[214:217], v[0:3]
	s_barrier
	s_setprio 1
	s_add_i32 s61, s61, 2
	s_add_u32 s59, s59, 0x100
	s_addc_u32 s60, s60, 0
	s_add_u32 s30, s30, 0x100
	s_addc_u32 s31, s31, 0
	s_cmp_gt_u32 s61, 29
	s_cbranch_scc0 .LBB0_731
	s_and_b64 vcc, exec, s[16:17]
	s_cbranch_vccz .LBB0_734
	s_barrier

.LBB0_952:
	ds_read_b128 v[144:147], v151
	ds_read_b128 v[156:159], v151 offset:1024
	ds_read_b128 v[160:163], v151 offset:2048
	ds_read_b128 v[164:167], v151 offset:3072
	ds_read_b128 v[168:171], v152
	ds_read_b128 v[172:175], v152 offset:1024
	ds_read_b128 v[176:179], v152 offset:2048
	ds_read_b128 v[180:183], v152 offset:3072
	s_add_u32 s54, s52, 0xfff80080
	s_addc_u32 s55, s53, -1
	s_cmp_eq_u32 s68, 28
	s_cselect_b32 s57, s27, s55
	s_cselect_b32 s56, s37, s54
	s_cselect_b32 s55, s25, s67
	s_cselect_b32 s54, s46, s47
	v_lshl_add_u64 v[216:217], s[52:53], 0, v[138:139]
	s_add_i32 m0, s59, 0xc000
	ds_read_b128 v[184:187], v153
	ds_read_b128 v[188:191], v153 offset:1024
	ds_read_b128 v[192:195], v153 offset:2048
	ds_read_b128 v[196:199], v153 offset:3072
	ds_read_b128 v[200:203], v153 offset:4096
	ds_read_b128 v[204:207], v153 offset:5120
	ds_read_b128 v[208:211], v153 offset:6144
	ds_read_b128 v[212:215], v153 offset:7168
	global_load_lds_dwordx4 v[216:217], off
	v_lshl_add_u64 v[216:217], s[52:53], 0, v[136:137]
	s_add_i32 m0, s59, 0xe000
	s_nop 0
	global_load_lds_dwordx4 v[216:217], off
	s_waitcnt vmcnt(8)
	s_waitcnt lgkmcnt(0)
	s_setprio 0
	s_barrier
	v_mfma_f32_16x16x32_bf16 v[116:119], v[144:147], v[184:187], v[116:119]
	v_mfma_f32_16x16x32_bf16 v[112:115], v[160:163], v[184:187], v[112:115]
	v_mfma_f32_16x16x32_bf16 v[104:107], v[144:147], v[192:195], v[104:107]
	v_mfma_f32_16x16x32_bf16 v[96:99], v[160:163], v[192:195], v[96:99]
	v_mfma_f32_16x16x32_bf16 v[88:91], v[144:147], v[200:203], v[88:91]
	v_mfma_f32_16x16x32_bf16 v[80:83], v[160:163], v[200:203], v[80:83]
	v_mfma_f32_16x16x32_bf16 v[72:75], v[144:147], v[208:211], v[72:75]
	v_mfma_f32_16x16x32_bf16 v[64:67], v[160:163], v[208:211], v[64:67]
	v_mfma_f32_16x16x32_bf16 v[116:119], v[156:159], v[188:191], v[116:119]
	v_mfma_f32_16x16x32_bf16 v[112:115], v[164:167], v[188:191], v[112:115]
	v_mfma_f32_16x16x32_bf16 v[104:107], v[156:159], v[196:199], v[104:107]
	v_mfma_f32_16x16x32_bf16 v[96:99], v[164:167], v[196:199], v[96:99]
	v_mfma_f32_16x16x32_bf16 v[88:91], v[156:159], v[204:207], v[88:91]
	v_mfma_f32_16x16x32_bf16 v[80:83], v[164:167], v[204:207], v[80:83]
	v_mfma_f32_16x16x32_bf16 v[72:75], v[156:159], v[212:215], v[72:75]
	v_mfma_f32_16x16x32_bf16 v[64:67], v[164:167], v[212:215], v[64:67]
	v_mfma_f32_16x16x32_bf16 v[124:127], v[168:171], v[184:187], v[124:127]
	v_mfma_f32_16x16x32_bf16 v[120:123], v[176:179], v[184:187], v[120:123]
	v_mfma_f32_16x16x32_bf16 v[108:111], v[168:171], v[192:195], v[108:111]
	v_mfma_f32_16x16x32_bf16 v[100:103], v[176:179], v[192:195], v[100:103]
	v_mfma_f32_16x16x32_bf16 v[92:95], v[168:171], v[200:203], v[92:95]
	v_mfma_f32_16x16x32_bf16 v[84:87], v[176:179], v[200:203], v[84:87]
	v_mfma_f32_16x16x32_bf16 v[76:79], v[168:171], v[208:211], v[76:79]
	v_mfma_f32_16x16x32_bf16 v[68:71], v[176:179], v[208:211], v[68:71]
	v_mfma_f32_16x16x32_bf16 v[124:127], v[172:175], v[188:191], v[124:127]
	v_mfma_f32_16x16x32_bf16 v[120:123], v[180:183], v[188:191], v[120:123]
	v_mfma_f32_16x16x32_bf16 v[108:111], v[172:175], v[196:199], v[108:111]
	v_mfma_f32_16x16x32_bf16 v[100:103], v[180:183], v[196:199], v[100:103]
	v_mfma_f32_16x16x32_bf16 v[92:95], v[172:175], v[204:207], v[92:95]
	v_mfma_f32_16x16x32_bf16 v[84:87], v[180:183], v[204:207], v[84:87]
	v_mfma_f32_16x16x32_bf16 v[76:79], v[172:175], v[212:215], v[76:79]
	v_mfma_f32_16x16x32_bf16 v[68:71], v[180:183], v[212:215], v[68:71]
	s_barrier
	s_setprio 1
	s_add_i32 s69, s64, s58
	v_lshl_add_u64 v[216:217], s[54:55], 0, v[130:131]
	s_mov_b32 m0, s69
	ds_read_b128 v[184:187], v153 offset:16384
	ds_read_b128 v[188:191], v153 offset:17408
	ds_read_b128 v[192:195], v153 offset:18432
	ds_read_b128 v[196:199], v153 offset:19456
	ds_read_b128 v[200:203], v153 offset:20480
	ds_read_b128 v[204:207], v153 offset:21504
	ds_read_b128 v[208:211], v153 offset:22528
	ds_read_b128 v[212:215], v153 offset:23552
	global_load_lds_dwordx4 v[216:217], off
	s_add_i32 m0, s69, 0x2000
	s_add_u32 s70, s54, 0x80000
	v_lshl_add_u64 v[218:219], s[54:55], 0, v[134:135]
	s_addc_u32 s71, s55, 0
	s_add_i32 s69, s65, s58
	global_load_lds_dwordx4 v[218:219], off
	v_lshl_add_u64 v[220:221], s[70:71], 0, v[130:131]
	s_mov_b32 m0, s69
	v_lshl_add_u64 v[222:223], s[56:57], 0, v[132:133]
	global_load_lds_dwordx4 v[220:221], off
	v_lshl_add_u64 v[220:221], s[70:71], 0, v[134:135]
	s_add_i32 m0, s69, 0x2000
	s_nop 0
	global_load_lds_dwordx4 v[220:221], off
	v_lshl_add_u64 v[220:221], s[56:57], 0, v[128:129]
	s_mov_b32 m0, s59
	s_nop 0
	global_load_lds_dwordx4 v[220:221], off
	s_mov_b32 m0, s50
	s_nop 0
	global_load_lds_dwordx4 v[222:223], off
	s_waitcnt vmcnt(8)
	s_waitcnt lgkmcnt(0)
	s_setprio 0
	s_barrier
	v_mfma_f32_16x16x32_bf16 v[56:59], v[144:147], v[184:187], v[56:59]
	v_mfma_f32_16x16x32_bf16 v[48:51], v[160:163], v[184:187], v[48:51]
	v_mfma_f32_16x16x32_bf16 v[40:43], v[144:147], v[192:195], v[40:43]
	v_mfma_f32_16x16x32_bf16 v[32:35], v[160:163], v[192:195], v[32:35]
	v_mfma_f32_16x16x32_bf16 v[24:27], v[144:147], v[200:203], v[24:27]
	v_mfma_f32_16x16x32_bf16 v[16:19], v[160:163], v[200:203], v[16:19]
	v_mfma_f32_16x16x32_bf16 v[8:11], v[144:147], v[208:211], v[8:11]
	v_mfma_f32_16x16x32_bf16 v[0:3], v[160:163], v[208:211], v[0:3]
	v_mfma_f32_16x16x32_bf16 v[56:59], v[156:159], v[188:191], v[56:59]
	v_mfma_f32_16x16x32_bf16 v[48:51], v[164:167], v[188:191], v[48:51]
	v_mfma_f32_16x16x32_bf16 v[40:43], v[156:159], v[196:199], v[40:43]
	v_mfma_f32_16x16x32_bf16 v[32:35], v[164:167], v[196:199], v[32:35]
	v_mfma_f32_16x16x32_bf16 v[24:27], v[156:159], v[204:207], v[24:27]
	v_mfma_f32_16x16x32_bf16 v[16:19], v[164:167], v[204:207], v[16:19]
	v_mfma_f32_16x16x32_bf16 v[8:11], v[156:159], v[212:215], v[8:11]
	v_mfma_f32_16x16x32_bf16 v[0:3], v[164:167], v[212:215], v[0:3]
	v_mfma_f32_16x16x32_bf16 v[60:63], v[168:171], v[184:187], v[60:63]
	v_mfma_f32_16x16x32_bf16 v[52:55], v[176:179], v[184:187], v[52:55]
	v_mfma_f32_16x16x32_bf16 v[44:47], v[168:171], v[192:195], v[44:47]
	v_mfma_f32_16x16x32_bf16 v[36:39], v[176:179], v[192:195], v[36:39]
	v_mfma_f32_16x16x32_bf16 v[28:31], v[168:171], v[200:203], v[28:31]
	v_mfma_f32_16x16x32_bf16 v[20:23], v[176:179], v[200:203], v[20:23]
	v_mfma_f32_16x16x32_bf16 v[12:15], v[168:171], v[208:211], v[12:15]
	v_mfma_f32_16x16x32_bf16 v[4:7], v[176:179], v[208:211], v[4:7]
	v_mfma_f32_16x16x32_bf16 v[60:63], v[172:175], v[188:191], v[60:63]
	v_mfma_f32_16x16x32_bf16 v[52:55], v[180:183], v[188:191], v[52:55]
	v_mfma_f32_16x16x32_bf16 v[44:47], v[172:175], v[196:199], v[44:47]
	v_mfma_f32_16x16x32_bf16 v[36:39], v[180:183], v[196:199], v[36:39]
	v_mfma_f32_16x16x32_bf16 v[28:31], v[172:175], v[204:207], v[28:31]
	v_mfma_f32_16x16x32_bf16 v[20:23], v[180:183], v[204:207], v[20:23]
	v_mfma_f32_16x16x32_bf16 v[12:15], v[172:175], v[212:215], v[12:15]
	v_mfma_f32_16x16x32_bf16 v[4:7], v[180:183], v[212:215], v[4:7]
	s_barrier
	s_setprio 1
	s_add_i32 s69, 0, 0x18000
	v_add_u32_e32 v155, s69, v149
	s_add_i32 s70, 0, 0x1c000
	ds_read_b128 v[144:147], v155
	ds_read_b128 v[156:159], v155 offset:1024
	ds_read_b128 v[160:163], v155 offset:2048
	ds_read_b128 v[164:167], v155 offset:3072
	v_add_u32_e32 v155, s70, v149
	ds_read_b128 v[168:171], v155
	ds_read_b128 v[172:175], v155 offset:1024
	ds_read_b128 v[176:179], v155 offset:2048
	ds_read_b128 v[180:183], v155 offset:3072
	s_add_u32 s56, s56, 0x80000
	s_addc_u32 s57, s57, 0
	s_mov_b32 m0, s51
	v_lshl_add_u64 v[224:225], s[56:57], 0, v[128:129]
	ds_read_b128 v[184:187], v153 offset:32768
	ds_read_b128 v[188:191], v153 offset:33792
	ds_read_b128 v[192:195], v153 offset:34816
	ds_read_b128 v[196:199], v153 offset:35840
	ds_read_b128 v[200:203], v153 offset:36864
	ds_read_b128 v[204:207], v153 offset:37888
	ds_read_b128 v[208:211], v153 offset:38912
	ds_read_b128 v[212:215], v153 offset:39936
	global_load_lds_dwordx4 v[224:225], off
	v_lshl_add_u64 v[224:225], s[56:57], 0, v[132:133]
	s_mov_b32 m0, s60
	s_nop 0
	global_load_lds_dwordx4 v[224:225], off
	s_waitcnt vmcnt(8)
	s_waitcnt lgkmcnt(0)
	s_setprio 0
	s_barrier
	v_mfma_f32_16x16x32_bf16 v[116:119], v[144:147], v[184:187], v[116:119]
	v_mfma_f32_16x16x32_bf16 v[112:115], v[160:163], v[184:187], v[112:115]
	v_mfma_f32_16x16x32_bf16 v[104:107], v[144:147], v[192:195], v[104:107]
	v_mfma_f32_16x16x32_bf16 v[96:99], v[160:163], v[192:195], v[96:99]
	v_mfma_f32_16x16x32_bf16 v[88:91], v[144:147], v[200:203], v[88:91]
	v_mfma_f32_16x16x32_bf16 v[80:83], v[160:163], v[200:203], v[80:83]
	v_mfma_f32_16x16x32_bf16 v[72:75], v[144:147], v[208:211], v[72:75]
	v_mfma_f32_16x16x32_bf16 v[64:67], v[160:163], v[208:211], v[64:67]
	v_mfma_f32_16x16x32_bf16 v[116:119], v[156:159], v[188:191], v[116:119]
	v_mfma_f32_16x16x32_bf16 v[112:115], v[164:167], v[188:191], v[112:115]
	v_mfma_f32_16x16x32_bf16 v[104:107], v[156:159], v[196:199], v[104:107]
	v_mfma_f32_16x16x32_bf16 v[96:99], v[164:167], v[196:199], v[96:99]
	v_mfma_f32_16x16x32_bf16 v[88:91], v[156:159], v[204:207], v[88:91]
	v_mfma_f32_16x16x32_bf16 v[80:83], v[164:167], v[204:207], v[80:83]
	v_mfma_f32_16x16x32_bf16 v[72:75], v[156:159], v[212:215], v[72:75]
	v_mfma_f32_16x16x32_bf16 v[64:67], v[164:167], v[212:215], v[64:67]
	v_mfma_f32_16x16x32_bf16 v[124:127], v[168:171], v[184:187], v[124:127]
	v_mfma_f32_16x16x32_bf16 v[120:123], v[176:179], v[184:187], v[120:123]
	v_mfma_f32_16x16x32_bf16 v[108:111], v[168:171], v[192:195], v[108:111]
	v_mfma_f32_16x16x32_bf16 v[100:103], v[176:179], v[192:195], v[100:103]
	v_mfma_f32_16x16x32_bf16 v[92:95], v[168:171], v[200:203], v[92:95]
	v_mfma_f32_16x16x32_bf16 v[84:87], v[176:179], v[200:203], v[84:87]
	v_mfma_f32_16x16x32_bf16 v[76:79], v[168:171], v[208:211], v[76:79]
	v_mfma_f32_16x16x32_bf16 v[68:71], v[176:179], v[208:211], v[68:71]
	v_mfma_f32_16x16x32_bf16 v[124:127], v[172:175], v[188:191], v[124:127]
	v_mfma_f32_16x16x32_bf16 v[120:123], v[180:183], v[188:191], v[120:123]
	v_mfma_f32_16x16x32_bf16 v[108:111], v[172:175], v[196:199], v[108:111]
	v_mfma_f32_16x16x32_bf16 v[100:103], v[180:183], v[196:199], v[100:103]
	v_mfma_f32_16x16x32_bf16 v[92:95], v[172:175], v[204:207], v[92:95]
	v_mfma_f32_16x16x32_bf16 v[84:87], v[180:183], v[204:207], v[84:87]
	v_mfma_f32_16x16x32_bf16 v[76:79], v[172:175], v[212:215], v[76:79]
	v_mfma_f32_16x16x32_bf16 v[68:71], v[180:183], v[212:215], v[68:71]
	s_barrier
	s_setprio 1
	s_add_i32 s56, s69, s58
	v_lshl_add_u64 v[216:217], v[216:217], 0, s[20:21]
	s_mov_b32 m0, s56
	ds_read_b128 v[184:187], v153 offset:49152
	ds_read_b128 v[188:191], v153 offset:50176
	ds_read_b128 v[192:195], v153 offset:51200
	ds_read_b128 v[196:199], v153 offset:52224
	ds_read_b128 v[200:203], v153 offset:53248
	ds_read_b128 v[204:207], v153 offset:54272
	ds_read_b128 v[208:211], v153 offset:55296
	ds_read_b128 v[212:215], v153 offset:56320
	global_load_lds_dwordx4 v[216:217], off
	s_add_i32 m0, s56, 0x2000
	s_add_u32 s54, s54, 0x80080
	v_lshl_add_u64 v[216:217], v[218:219], 0, s[20:21]
	s_addc_u32 s55, s55, 0
	s_add_i32 s56, s70, s58
	global_load_lds_dwordx4 v[216:217], off
	v_lshl_add_u64 v[216:217], s[54:55], 0, v[130:131]
	s_mov_b32 m0, s56
	s_nop 0
	global_load_lds_dwordx4 v[216:217], off
	v_lshl_add_u64 v[216:217], s[54:55], 0, v[134:135]
	s_add_i32 m0, s56, 0x2000
	s_nop 0
	global_load_lds_dwordx4 v[216:217], off
	v_lshl_add_u64 v[216:217], v[220:221], 0, s[20:21]
	s_mov_b32 m0, s62
	s_nop 0
	global_load_lds_dwordx4 v[216:217], off
	v_lshl_add_u64 v[216:217], v[222:223], 0, s[20:21]
	s_mov_b32 m0, s63
	s_nop 0
	global_load_lds_dwordx4 v[216:217], off
	s_waitcnt vmcnt(8)
	s_waitcnt lgkmcnt(0)
	s_setprio 0
	s_barrier
	v_mfma_f32_16x16x32_bf16 v[56:59], v[144:147], v[184:187], v[56:59]
	v_mfma_f32_16x16x32_bf16 v[48:51], v[160:163], v[184:187], v[48:51]
	v_mfma_f32_16x16x32_bf16 v[40:43], v[144:147], v[192:195], v[40:43]
	v_mfma_f32_16x16x32_bf16 v[32:35], v[160:163], v[192:195], v[32:35]
	v_mfma_f32_16x16x32_bf16 v[24:27], v[144:147], v[200:203], v[24:27]
	v_mfma_f32_16x16x32_bf16 v[16:19], v[160:163], v[200:203], v[16:19]
	v_mfma_f32_16x16x32_bf16 v[8:11], v[144:147], v[208:211], v[8:11]
	v_mfma_f32_16x16x32_bf16 v[0:3], v[160:163], v[208:211], v[0:3]
	v_mfma_f32_16x16x32_bf16 v[56:59], v[156:159], v[188:191], v[56:59]
	v_mfma_f32_16x16x32_bf16 v[48:51], v[164:167], v[188:191], v[48:51]
	v_mfma_f32_16x16x32_bf16 v[40:43], v[156:159], v[196:199], v[40:43]
	v_mfma_f32_16x16x32_bf16 v[32:35], v[164:167], v[196:199], v[32:35]
	v_mfma_f32_16x16x32_bf16 v[24:27], v[156:159], v[204:207], v[24:27]
	v_mfma_f32_16x16x32_bf16 v[16:19], v[164:167], v[204:207], v[16:19]
	v_mfma_f32_16x16x32_bf16 v[8:11], v[156:159], v[212:215], v[8:11]
	v_mfma_f32_16x16x32_bf16 v[0:3], v[164:167], v[212:215], v[0:3]
	v_mfma_f32_16x16x32_bf16 v[60:63], v[168:171], v[184:187], v[60:63]
	v_mfma_f32_16x16x32_bf16 v[52:55], v[176:179], v[184:187], v[52:55]
	v_mfma_f32_16x16x32_bf16 v[44:47], v[168:171], v[192:195], v[44:47]
	v_mfma_f32_16x16x32_bf16 v[36:39], v[176:179], v[192:195], v[36:39]
	v_mfma_f32_16x16x32_bf16 v[28:31], v[168:171], v[200:203], v[28:31]
	v_mfma_f32_16x16x32_bf16 v[20:23], v[176:179], v[200:203], v[20:23]
	v_mfma_f32_16x16x32_bf16 v[12:15], v[168:171], v[208:211], v[12:15]
	v_mfma_f32_16x16x32_bf16 v[4:7], v[176:179], v[208:211], v[4:7]
	v_mfma_f32_16x16x32_bf16 v[60:63], v[172:175], v[188:191], v[60:63]
	v_mfma_f32_16x16x32_bf16 v[52:55], v[180:183], v[188:191], v[52:55]
	v_mfma_f32_16x16x32_bf16 v[44:47], v[172:175], v[196:199], v[44:47]
	v_mfma_f32_16x16x32_bf16 v[36:39], v[180:183], v[196:199], v[36:39]
	v_mfma_f32_16x16x32_bf16 v[28:31], v[172:175], v[204:207], v[28:31]
	v_mfma_f32_16x16x32_bf16 v[20:23], v[180:183], v[204:207], v[20:23]
	v_mfma_f32_16x16x32_bf16 v[12:15], v[172:175], v[212:215], v[12:15]
	v_mfma_f32_16x16x32_bf16 v[4:7], v[180:183], v[212:215], v[4:7]
	s_barrier
	s_setprio 1
	s_add_i32 s68, s68, 2
	s_add_u32 s47, s47, 0x100
	s_addc_u32 s67, s67, 0
	s_add_u32 s52, s52, 0x100
	s_addc_u32 s53, s53, 0
	s_cmp_gt_u32 s68, 29
	s_cbranch_scc0 .LBB0_952
	s_and_b64 vcc, exec, s[22:23]
	s_cbranch_vccz .LBB0_955
	s_barrier

.LBB0_1049:
	ds_read_b128 v[148:151], v222
	ds_read_b128 v[152:155], v222 offset:1024
	ds_read_b128 v[156:159], v222 offset:2048
	ds_read_b128 v[160:163], v222 offset:3072
	ds_read_b128 v[132:135], v223
	ds_read_b128 v[136:139], v223 offset:1024
	ds_read_b128 v[140:143], v223 offset:2048
	ds_read_b128 v[144:147], v223 offset:3072
	s_add_u32 s8, s48, 0xfff80080
	s_addc_u32 s9, s49, -1
	s_cmp_eq_u32 s81, 28
	s_cselect_b32 s53, s23, s9
	s_cselect_b32 s52, s46, s8
	s_cselect_b32 s51, s21, s80
	s_cselect_b32 s50, s47, s79
	v_lshl_add_u64 v[2:3], s[48:49], 0, v[208:209]
	s_add_i32 m0, s35, 0xc000
	s_waitcnt lgkmcnt(0)
	ds_read_b128 v[164:167], v224
	ds_read_b128 v[168:171], v224 offset:1024
	ds_read_b128 v[172:175], v224 offset:2048
	ds_read_b128 v[176:179], v224 offset:3072
	ds_read_b128 v[180:183], v224 offset:4096
	ds_read_b128 v[184:187], v224 offset:5120
	ds_read_b128 v[188:191], v224 offset:6144
	ds_read_b128 v[192:195], v224 offset:7168
	global_load_lds_dwordx4 v[2:3], off
	v_lshl_add_u64 v[2:3], s[48:49], 0, v[206:207]
	s_add_i32 m0, s35, 0xe000
	s_nop 0
	global_load_lds_dwordx4 v[2:3], off
	s_waitcnt vmcnt(8)
	s_waitcnt lgkmcnt(0)
	s_setprio 0
	s_barrier
	v_mfma_f32_16x16x32_bf16 v[124:127], v[148:151], v[164:167], v[124:127]
	v_mfma_f32_16x16x32_bf16 v[120:123], v[156:159], v[164:167], v[120:123]
	v_mfma_f32_16x16x32_bf16 v[104:107], v[148:151], v[172:175], v[104:107]
	v_mfma_f32_16x16x32_bf16 v[100:103], v[156:159], v[172:175], v[100:103]
	v_mfma_f32_16x16x32_bf16 v[88:91], v[148:151], v[180:183], v[88:91]
	v_mfma_f32_16x16x32_bf16 v[84:87], v[156:159], v[180:183], v[84:87]
	v_mfma_f32_16x16x32_bf16 v[76:79], v[148:151], v[188:191], v[76:79]
	v_mfma_f32_16x16x32_bf16 v[72:75], v[156:159], v[188:191], v[72:75]
	v_mfma_f32_16x16x32_bf16 v[124:127], v[152:155], v[168:171], v[124:127]
	v_mfma_f32_16x16x32_bf16 v[120:123], v[160:163], v[168:171], v[120:123]
	v_mfma_f32_16x16x32_bf16 v[104:107], v[152:155], v[176:179], v[104:107]
	v_mfma_f32_16x16x32_bf16 v[100:103], v[160:163], v[176:179], v[100:103]
	v_mfma_f32_16x16x32_bf16 v[88:91], v[152:155], v[184:187], v[88:91]
	v_mfma_f32_16x16x32_bf16 v[84:87], v[160:163], v[184:187], v[84:87]
	v_mfma_f32_16x16x32_bf16 v[76:79], v[152:155], v[192:195], v[76:79]
	v_mfma_f32_16x16x32_bf16 v[72:75], v[160:163], v[192:195], v[72:75]
	v_mfma_f32_16x16x32_bf16 v[128:131], v[132:135], v[164:167], v[128:131]
	v_mfma_f32_16x16x32_bf16 v[116:119], v[140:143], v[164:167], v[116:119]
	v_mfma_f32_16x16x32_bf16 v[112:115], v[132:135], v[172:175], v[112:115]
	v_mfma_f32_16x16x32_bf16 v[108:111], v[140:143], v[172:175], v[108:111]
	v_mfma_f32_16x16x32_bf16 v[96:99], v[132:135], v[180:183], v[96:99]
	v_mfma_f32_16x16x32_bf16 v[92:95], v[140:143], v[180:183], v[92:95]
	v_mfma_f32_16x16x32_bf16 v[80:83], v[132:135], v[188:191], v[80:83]
	v_mfma_f32_16x16x32_bf16 v[68:71], v[140:143], v[188:191], v[68:71]
	v_mfma_f32_16x16x32_bf16 v[128:131], v[136:139], v[168:171], v[128:131]
	v_mfma_f32_16x16x32_bf16 v[116:119], v[144:147], v[168:171], v[116:119]
	v_mfma_f32_16x16x32_bf16 v[112:115], v[136:139], v[176:179], v[112:115]
	v_mfma_f32_16x16x32_bf16 v[108:111], v[144:147], v[176:179], v[108:111]
	v_mfma_f32_16x16x32_bf16 v[96:99], v[136:139], v[184:187], v[96:99]
	v_mfma_f32_16x16x32_bf16 v[92:95], v[144:147], v[184:187], v[92:95]
	v_mfma_f32_16x16x32_bf16 v[80:83], v[136:139], v[192:195], v[80:83]
	v_mfma_f32_16x16x32_bf16 v[68:71], v[144:147], v[192:195], v[68:71]
	s_barrier
	s_setprio 1
	s_add_i32 s8, s65, s56
	v_lshl_add_u64 v[2:3], s[50:51], 0, v[198:199]
	s_mov_b32 m0, s8
	ds_read_b128 v[188:191], v224 offset:16384
	ds_read_b128 v[192:195], v224 offset:17408
	ds_read_b128 v[180:183], v224 offset:18432
	ds_read_b128 v[184:187], v224 offset:19456
	ds_read_b128 v[172:175], v224 offset:20480
	ds_read_b128 v[176:179], v224 offset:21504
	ds_read_b128 v[164:167], v224 offset:22528
	ds_read_b128 v[168:171], v224 offset:23552
	global_load_lds_dwordx4 v[2:3], off
	s_add_i32 m0, s8, 0x2000
	s_add_u32 s8, s50, 0x80000
	v_lshl_add_u64 v[212:213], s[50:51], 0, v[202:203]
	s_addc_u32 s9, s51, 0
	s_add_i32 s78, s66, s56
	global_load_lds_dwordx4 v[212:213], off
	v_lshl_add_u64 v[214:215], s[8:9], 0, v[198:199]
	s_mov_b32 m0, s78
	v_lshl_add_u64 v[216:217], s[52:53], 0, v[200:201]
	global_load_lds_dwordx4 v[214:215], off
	v_lshl_add_u64 v[214:215], s[8:9], 0, v[202:203]
	s_add_i32 m0, s78, 0x2000
	v_cmp_ne_u32_e64 s[8:9], 1, v227
	global_load_lds_dwordx4 v[214:215], off
	v_lshl_add_u64 v[214:215], s[52:53], 0, v[196:197]
	s_mov_b32 m0, s35
	s_andn2_b64 vcc, exec, s[36:37]
	global_load_lds_dwordx4 v[214:215], off
	s_mov_b32 m0, s58
	s_nop 0
	global_load_lds_dwordx4 v[216:217], off
	s_waitcnt vmcnt(8)
	s_waitcnt lgkmcnt(0)
	s_cbranch_vccnz .Lsegskip_2
	s_setprio 0
	s_barrier
	v_mfma_f32_16x16x32_bf16 v[56:59], v[148:151], v[188:191], v[56:59]
	v_mfma_f32_16x16x32_bf16 v[52:55], v[156:159], v[188:191], v[52:55]
	v_mfma_f32_16x16x32_bf16 v[40:43], v[148:151], v[180:183], v[40:43]
	v_mfma_f32_16x16x32_bf16 v[36:39], v[156:159], v[180:183], v[36:39]
	v_mfma_f32_16x16x32_bf16 v[24:27], v[148:151], v[172:175], v[24:27]
	v_mfma_f32_16x16x32_bf16 v[20:23], v[156:159], v[172:175], v[20:23]
	v_mfma_f32_16x16x32_bf16 v[8:11], v[148:151], v[164:167], v[8:11]
	v_mfma_f32_16x16x32_bf16 v[4:7], v[156:159], v[164:167], v[4:7]
	v_mfma_f32_16x16x32_bf16 v[56:59], v[152:155], v[192:195], v[56:59]
	v_mfma_f32_16x16x32_bf16 v[52:55], v[160:163], v[192:195], v[52:55]
	v_mfma_f32_16x16x32_bf16 v[40:43], v[152:155], v[184:187], v[40:43]
	v_mfma_f32_16x16x32_bf16 v[36:39], v[160:163], v[184:187], v[36:39]
	v_mfma_f32_16x16x32_bf16 v[24:27], v[152:155], v[176:179], v[24:27]
	v_mfma_f32_16x16x32_bf16 v[20:23], v[160:163], v[176:179], v[20:23]
	v_mfma_f32_16x16x32_bf16 v[8:11], v[152:155], v[168:171], v[8:11]
	v_mfma_f32_16x16x32_bf16 v[4:7], v[160:163], v[168:171], v[4:7]
	v_mfma_f32_16x16x32_bf16 v[64:67], v[132:135], v[188:191], v[64:67]
	v_mfma_f32_16x16x32_bf16 v[60:63], v[140:143], v[188:191], v[60:63]
	v_mfma_f32_16x16x32_bf16 v[48:51], v[132:135], v[180:183], v[48:51]
	v_mfma_f32_16x16x32_bf16 v[44:47], v[140:143], v[180:183], v[44:47]
	v_mfma_f32_16x16x32_bf16 v[32:35], v[132:135], v[172:175], v[32:35]
	v_mfma_f32_16x16x32_bf16 v[28:31], v[140:143], v[172:175], v[28:31]
	v_mfma_f32_16x16x32_bf16 v[16:19], v[132:135], v[164:167], v[16:19]
	v_mfma_f32_16x16x32_bf16 v[12:15], v[140:143], v[164:167], v[12:15]
	v_mfma_f32_16x16x32_bf16 v[64:67], v[136:139], v[192:195], v[64:67]
	v_mfma_f32_16x16x32_bf16 v[60:63], v[144:147], v[192:195], v[60:63]
	v_mfma_f32_16x16x32_bf16 v[48:51], v[136:139], v[184:187], v[48:51]
	v_mfma_f32_16x16x32_bf16 v[44:47], v[144:147], v[184:187], v[44:47]
	v_mfma_f32_16x16x32_bf16 v[32:35], v[136:139], v[176:179], v[32:35]
	v_mfma_f32_16x16x32_bf16 v[28:31], v[144:147], v[176:179], v[28:31]
	v_mfma_f32_16x16x32_bf16 v[16:19], v[136:139], v[168:171], v[16:19]
	v_mfma_f32_16x16x32_bf16 v[12:15], v[144:147], v[168:171], v[12:15]
.LBB0_1051:
	s_barrier
	s_setprio 1
	s_add_i32 s78, 0, 0x18000
	v_add_u32_e32 v1, s78, v220
	s_add_i32 s82, 0, 0x1c000
	ds_read_b128 v[148:151], v1
	ds_read_b128 v[152:155], v1 offset:1024
	ds_read_b128 v[156:159], v1 offset:2048
	ds_read_b128 v[160:163], v1 offset:3072
	v_add_u32_e32 v1, s82, v220
	ds_read_b128 v[132:135], v1
	ds_read_b128 v[136:139], v1 offset:1024
	ds_read_b128 v[140:143], v1 offset:2048
	ds_read_b128 v[144:147], v1 offset:3072
	s_add_u32 s52, s52, 0x80000
	s_addc_u32 s53, s53, 0
	s_mov_b32 m0, s59
	v_lshl_add_u64 v[228:229], s[52:53], 0, v[196:197]
	s_waitcnt lgkmcnt(0)
	ds_read_b128 v[164:167], v224 offset:32768
	ds_read_b128 v[168:171], v224 offset:33792
	ds_read_b128 v[172:175], v224 offset:34816
	ds_read_b128 v[176:179], v224 offset:35840
	ds_read_b128 v[180:183], v224 offset:36864
	ds_read_b128 v[184:187], v224 offset:37888
	ds_read_b128 v[188:191], v224 offset:38912
	ds_read_b128 v[192:195], v224 offset:39936
	global_load_lds_dwordx4 v[228:229], off
	v_lshl_add_u64 v[228:229], s[52:53], 0, v[200:201]
	s_mov_b32 m0, s60
	s_nop 0
	global_load_lds_dwordx4 v[228:229], off
	s_waitcnt vmcnt(8)
	s_waitcnt lgkmcnt(0)
	s_setprio 0
	s_barrier
	v_mfma_f32_16x16x32_bf16 v[124:127], v[148:151], v[164:167], v[124:127]
	v_mfma_f32_16x16x32_bf16 v[120:123], v[156:159], v[164:167], v[120:123]
	v_mfma_f32_16x16x32_bf16 v[104:107], v[148:151], v[172:175], v[104:107]
	v_mfma_f32_16x16x32_bf16 v[100:103], v[156:159], v[172:175], v[100:103]
	v_mfma_f32_16x16x32_bf16 v[88:91], v[148:151], v[180:183], v[88:91]
	v_mfma_f32_16x16x32_bf16 v[84:87], v[156:159], v[180:183], v[84:87]
	v_mfma_f32_16x16x32_bf16 v[76:79], v[148:151], v[188:191], v[76:79]
	v_mfma_f32_16x16x32_bf16 v[72:75], v[156:159], v[188:191], v[72:75]
	v_mfma_f32_16x16x32_bf16 v[124:127], v[152:155], v[168:171], v[124:127]
	v_mfma_f32_16x16x32_bf16 v[120:123], v[160:163], v[168:171], v[120:123]
	v_mfma_f32_16x16x32_bf16 v[104:107], v[152:155], v[176:179], v[104:107]
	v_mfma_f32_16x16x32_bf16 v[100:103], v[160:163], v[176:179], v[100:103]
	v_mfma_f32_16x16x32_bf16 v[88:91], v[152:155], v[184:187], v[88:91]
	v_mfma_f32_16x16x32_bf16 v[84:87], v[160:163], v[184:187], v[84:87]
	v_mfma_f32_16x16x32_bf16 v[76:79], v[152:155], v[192:195], v[76:79]
	v_mfma_f32_16x16x32_bf16 v[72:75], v[160:163], v[192:195], v[72:75]
	v_mfma_f32_16x16x32_bf16 v[128:131], v[132:135], v[164:167], v[128:131]
	v_mfma_f32_16x16x32_bf16 v[116:119], v[140:143], v[164:167], v[116:119]
	v_mfma_f32_16x16x32_bf16 v[112:115], v[132:135], v[172:175], v[112:115]
	v_mfma_f32_16x16x32_bf16 v[108:111], v[140:143], v[172:175], v[108:111]
	v_mfma_f32_16x16x32_bf16 v[96:99], v[132:135], v[180:183], v[96:99]
	v_mfma_f32_16x16x32_bf16 v[92:95], v[140:143], v[180:183], v[92:95]
	v_mfma_f32_16x16x32_bf16 v[80:83], v[132:135], v[188:191], v[80:83]
	v_mfma_f32_16x16x32_bf16 v[68:71], v[140:143], v[188:191], v[68:71]
	v_mfma_f32_16x16x32_bf16 v[128:131], v[136:139], v[168:171], v[128:131]
	v_mfma_f32_16x16x32_bf16 v[116:119], v[144:147], v[168:171], v[116:119]
	v_mfma_f32_16x16x32_bf16 v[112:115], v[136:139], v[176:179], v[112:115]
	v_mfma_f32_16x16x32_bf16 v[108:111], v[144:147], v[176:179], v[108:111]
	v_mfma_f32_16x16x32_bf16 v[96:99], v[136:139], v[184:187], v[96:99]
	v_mfma_f32_16x16x32_bf16 v[92:95], v[144:147], v[184:187], v[92:95]
	v_mfma_f32_16x16x32_bf16 v[80:83], v[136:139], v[192:195], v[80:83]
	v_mfma_f32_16x16x32_bf16 v[68:71], v[144:147], v[192:195], v[68:71]
	s_barrier
	s_setprio 1
	s_add_i32 s52, s78, s56
	v_lshl_add_u64 v[2:3], v[2:3], 0, s[14:15]
	s_mov_b32 m0, s52
	ds_read_b128 v[188:191], v224 offset:49152
	ds_read_b128 v[192:195], v224 offset:50176
	ds_read_b128 v[180:183], v224 offset:51200
	ds_read_b128 v[184:187], v224 offset:52224
	ds_read_b128 v[172:175], v224 offset:53248
	ds_read_b128 v[176:179], v224 offset:54272
	ds_read_b128 v[164:167], v224 offset:55296
	ds_read_b128 v[168:171], v224 offset:56320
	global_load_lds_dwordx4 v[2:3], off
	s_add_i32 m0, s52, 0x2000
	s_add_u32 s50, s50, 0x80080
	v_lshl_add_u64 v[2:3], v[212:213], 0, s[14:15]
	s_addc_u32 s51, s51, 0
	s_add_i32 s52, s82, s56
	global_load_lds_dwordx4 v[2:3], off
	v_lshl_add_u64 v[2:3], s[50:51], 0, v[198:199]
	s_mov_b32 m0, s52
	s_and_b64 vcc, exec, s[8:9]
	global_load_lds_dwordx4 v[2:3], off
	v_lshl_add_u64 v[2:3], s[50:51], 0, v[202:203]
	s_add_i32 m0, s52, 0x2000
	s_nop 0
	global_load_lds_dwordx4 v[2:3], off
	v_lshl_add_u64 v[2:3], v[214:215], 0, s[14:15]
	s_mov_b32 m0, s61
	s_nop 0
	global_load_lds_dwordx4 v[2:3], off
	v_lshl_add_u64 v[2:3], v[216:217], 0, s[14:15]
	s_mov_b32 m0, s62
	s_nop 0
	global_load_lds_dwordx4 v[2:3], off
	s_waitcnt vmcnt(8)
	s_waitcnt lgkmcnt(0)
	s_cbranch_vccnz .Lsegskip_3
	s_setprio 0
	s_barrier
	v_mfma_f32_16x16x32_bf16 v[56:59], v[148:151], v[188:191], v[56:59]
	v_mfma_f32_16x16x32_bf16 v[52:55], v[156:159], v[188:191], v[52:55]
	v_mfma_f32_16x16x32_bf16 v[40:43], v[148:151], v[180:183], v[40:43]
	v_mfma_f32_16x16x32_bf16 v[36:39], v[156:159], v[180:183], v[36:39]
	v_mfma_f32_16x16x32_bf16 v[24:27], v[148:151], v[172:175], v[24:27]
	v_mfma_f32_16x16x32_bf16 v[20:23], v[156:159], v[172:175], v[20:23]
	v_mfma_f32_16x16x32_bf16 v[8:11], v[148:151], v[164:167], v[8:11]
	v_mfma_f32_16x16x32_bf16 v[2:5], v[156:159], v[164:167], v[4:7]
	v_mfma_f32_16x16x32_bf16 v[56:59], v[152:155], v[192:195], v[56:59]
	v_mfma_f32_16x16x32_bf16 v[52:55], v[160:163], v[192:195], v[52:55]
	v_mfma_f32_16x16x32_bf16 v[40:43], v[152:155], v[184:187], v[40:43]
	v_mfma_f32_16x16x32_bf16 v[36:39], v[160:163], v[184:187], v[36:39]
	v_mfma_f32_16x16x32_bf16 v[24:27], v[152:155], v[176:179], v[24:27]
	v_mfma_f32_16x16x32_bf16 v[20:23], v[160:163], v[176:179], v[20:23]
	v_mfma_f32_16x16x32_bf16 v[8:11], v[152:155], v[168:171], v[8:11]
	v_mfma_f32_16x16x32_bf16 v[4:7], v[160:163], v[168:171], v[2:5]
	v_mfma_f32_16x16x32_bf16 v[64:67], v[132:135], v[188:191], v[64:67]
	v_mfma_f32_16x16x32_bf16 v[60:63], v[140:143], v[188:191], v[60:63]
	v_mfma_f32_16x16x32_bf16 v[48:51], v[132:135], v[180:183], v[48:51]
	v_mfma_f32_16x16x32_bf16 v[44:47], v[140:143], v[180:183], v[44:47]
	v_mfma_f32_16x16x32_bf16 v[32:35], v[132:135], v[172:175], v[32:35]
	v_mfma_f32_16x16x32_bf16 v[28:31], v[140:143], v[172:175], v[28:31]
	v_mfma_f32_16x16x32_bf16 v[16:19], v[132:135], v[164:167], v[16:19]
	v_mfma_f32_16x16x32_bf16 v[12:15], v[140:143], v[164:167], v[12:15]
	v_mfma_f32_16x16x32_bf16 v[64:67], v[136:139], v[192:195], v[64:67]
	v_mfma_f32_16x16x32_bf16 v[60:63], v[144:147], v[192:195], v[60:63]
	v_mfma_f32_16x16x32_bf16 v[48:51], v[136:139], v[184:187], v[48:51]
	v_mfma_f32_16x16x32_bf16 v[44:47], v[144:147], v[184:187], v[44:47]
	v_mfma_f32_16x16x32_bf16 v[32:35], v[136:139], v[176:179], v[32:35]
	v_mfma_f32_16x16x32_bf16 v[28:31], v[144:147], v[176:179], v[28:31]
	v_mfma_f32_16x16x32_bf16 v[16:19], v[136:139], v[168:171], v[16:19]
	v_mfma_f32_16x16x32_bf16 v[12:15], v[144:147], v[168:171], v[12:15]
	s_barrier
	s_setprio 1
	s_branch .Lsegback_3

.LBB0_1137:
	ds_read_b128 v[144:147], v151
	ds_read_b128 v[156:159], v151 offset:1024
	ds_read_b128 v[160:163], v151 offset:2048
	ds_read_b128 v[164:167], v151 offset:3072
	ds_read_b128 v[168:171], v152
	ds_read_b128 v[172:175], v152 offset:1024
	ds_read_b128 v[176:179], v152 offset:2048
	ds_read_b128 v[180:183], v152 offset:3072
	s_add_u32 s34, s30, 0x100
	s_addc_u32 s35, s31, 0
	s_cmpk_eq_i32 s66, 0x54
	s_cselect_b32 s49, s11, s35
	s_cselect_b32 s48, s10, s34
	s_cselect_b32 s37, s27, s47
	s_cselect_b32 s36, s26, s46
	v_lshl_add_u64 v[216:217], s[30:31], 0, v[138:139]
	s_add_i32 m0, s53, 0xc000
	ds_read_b128 v[184:187], v153
	ds_read_b128 v[188:191], v153 offset:1024
	ds_read_b128 v[192:195], v153 offset:2048
	ds_read_b128 v[196:199], v153 offset:3072
	ds_read_b128 v[200:203], v153 offset:4096
	ds_read_b128 v[204:207], v153 offset:5120
	ds_read_b128 v[208:211], v153 offset:6144
	ds_read_b128 v[212:215], v153 offset:7168
	global_load_lds_dwordx4 v[216:217], off
	v_lshl_add_u64 v[216:217], s[30:31], 0, v[136:137]
	s_add_i32 m0, s53, 0xe000
	s_nop 0
	global_load_lds_dwordx4 v[216:217], off
	s_waitcnt vmcnt(8)
	s_waitcnt lgkmcnt(0)
	s_setprio 0
	s_barrier
	v_mfma_f32_16x16x32_bf16 v[124:127], v[144:147], v[184:187], v[124:127]
	v_mfma_f32_16x16x32_bf16 v[120:123], v[160:163], v[184:187], v[120:123]
	v_mfma_f32_16x16x32_bf16 v[108:111], v[144:147], v[192:195], v[108:111]
	v_mfma_f32_16x16x32_bf16 v[104:107], v[160:163], v[192:195], v[104:107]
	v_mfma_f32_16x16x32_bf16 v[92:95], v[144:147], v[200:203], v[92:95]
	v_mfma_f32_16x16x32_bf16 v[88:91], v[160:163], v[200:203], v[88:91]
	v_mfma_f32_16x16x32_bf16 v[76:79], v[144:147], v[208:211], v[76:79]
	v_mfma_f32_16x16x32_bf16 v[72:75], v[160:163], v[208:211], v[72:75]
	v_mfma_f32_16x16x32_bf16 v[124:127], v[156:159], v[188:191], v[124:127]
	v_mfma_f32_16x16x32_bf16 v[120:123], v[164:167], v[188:191], v[120:123]
	v_mfma_f32_16x16x32_bf16 v[108:111], v[156:159], v[196:199], v[108:111]
	v_mfma_f32_16x16x32_bf16 v[104:107], v[164:167], v[196:199], v[104:107]
	v_mfma_f32_16x16x32_bf16 v[92:95], v[156:159], v[204:207], v[92:95]
	v_mfma_f32_16x16x32_bf16 v[88:91], v[164:167], v[204:207], v[88:91]
	v_mfma_f32_16x16x32_bf16 v[76:79], v[156:159], v[212:215], v[76:79]
	v_mfma_f32_16x16x32_bf16 v[72:75], v[164:167], v[212:215], v[72:75]
	v_mfma_f32_16x16x32_bf16 v[116:119], v[168:171], v[184:187], v[116:119]
	v_mfma_f32_16x16x32_bf16 v[112:115], v[176:179], v[184:187], v[112:115]
	v_mfma_f32_16x16x32_bf16 v[100:103], v[168:171], v[192:195], v[100:103]
	v_mfma_f32_16x16x32_bf16 v[96:99], v[176:179], v[192:195], v[96:99]
	v_mfma_f32_16x16x32_bf16 v[84:87], v[168:171], v[200:203], v[84:87]
	v_mfma_f32_16x16x32_bf16 v[80:83], v[176:179], v[200:203], v[80:83]
	v_mfma_f32_16x16x32_bf16 v[68:71], v[168:171], v[208:211], v[68:71]
	v_mfma_f32_16x16x32_bf16 v[64:67], v[176:179], v[208:211], v[64:67]
	v_mfma_f32_16x16x32_bf16 v[116:119], v[172:175], v[188:191], v[116:119]
	v_mfma_f32_16x16x32_bf16 v[112:115], v[180:183], v[188:191], v[112:115]
	v_mfma_f32_16x16x32_bf16 v[100:103], v[172:175], v[196:199], v[100:103]
	v_mfma_f32_16x16x32_bf16 v[96:99], v[180:183], v[196:199], v[96:99]
	v_mfma_f32_16x16x32_bf16 v[84:87], v[172:175], v[204:207], v[84:87]
	v_mfma_f32_16x16x32_bf16 v[80:83], v[180:183], v[204:207], v[80:83]
	v_mfma_f32_16x16x32_bf16 v[68:71], v[172:175], v[212:215], v[68:71]
	v_mfma_f32_16x16x32_bf16 v[64:67], v[180:183], v[212:215], v[64:67]
	s_barrier
	s_setprio 1
	s_add_i32 s30, s60, s52
	v_lshl_add_u64 v[216:217], s[36:37], 0, v[130:131]
	s_mov_b32 m0, s30
	ds_read_b128 v[184:187], v153 offset:16384
	ds_read_b128 v[188:191], v153 offset:17408
	ds_read_b128 v[192:195], v153 offset:18432
	ds_read_b128 v[196:199], v153 offset:19456
	ds_read_b128 v[200:203], v153 offset:20480
	ds_read_b128 v[204:207], v153 offset:21504
	ds_read_b128 v[208:211], v153 offset:22528
	ds_read_b128 v[212:215], v153 offset:23552
	global_load_lds_dwordx4 v[216:217], off
	s_add_i32 m0, s30, 0x2000
	s_add_u32 s30, s36, 0x160000
	v_lshl_add_u64 v[218:219], s[36:37], 0, v[134:135]
	s_addc_u32 s31, s37, 0
	s_add_i32 s67, s61, s52
	global_load_lds_dwordx4 v[218:219], off
	v_lshl_add_u64 v[220:221], s[30:31], 0, v[130:131]
	s_mov_b32 m0, s67
	v_lshl_add_u64 v[222:223], s[48:49], 0, v[132:133]
	global_load_lds_dwordx4 v[220:221], off
	v_lshl_add_u64 v[220:221], s[30:31], 0, v[134:135]
	s_add_i32 m0, s67, 0x2000
	s_nop 0
	global_load_lds_dwordx4 v[220:221], off
	v_lshl_add_u64 v[220:221], s[48:49], 0, v[128:129]
	s_mov_b32 m0, s53
	s_nop 0
	global_load_lds_dwordx4 v[220:221], off
	s_mov_b32 m0, s54
	s_nop 0
	global_load_lds_dwordx4 v[222:223], off
	s_waitcnt vmcnt(8)
	s_waitcnt lgkmcnt(0)
	s_setprio 0
	s_barrier
	v_mfma_f32_16x16x32_bf16 v[60:63], v[144:147], v[184:187], v[60:63]
	v_mfma_f32_16x16x32_bf16 v[56:59], v[160:163], v[184:187], v[56:59]
	v_mfma_f32_16x16x32_bf16 v[44:47], v[144:147], v[192:195], v[44:47]
	v_mfma_f32_16x16x32_bf16 v[40:43], v[160:163], v[192:195], v[40:43]
	v_mfma_f32_16x16x32_bf16 v[28:31], v[144:147], v[200:203], v[28:31]
	v_mfma_f32_16x16x32_bf16 v[24:27], v[160:163], v[200:203], v[24:27]
	v_mfma_f32_16x16x32_bf16 v[12:15], v[144:147], v[208:211], v[12:15]
	v_mfma_f32_16x16x32_bf16 v[8:11], v[160:163], v[208:211], v[8:11]
	v_mfma_f32_16x16x32_bf16 v[60:63], v[156:159], v[188:191], v[60:63]
	v_mfma_f32_16x16x32_bf16 v[56:59], v[164:167], v[188:191], v[56:59]
	v_mfma_f32_16x16x32_bf16 v[44:47], v[156:159], v[196:199], v[44:47]
	v_mfma_f32_16x16x32_bf16 v[40:43], v[164:167], v[196:199], v[40:43]
	v_mfma_f32_16x16x32_bf16 v[28:31], v[156:159], v[204:207], v[28:31]
	v_mfma_f32_16x16x32_bf16 v[24:27], v[164:167], v[204:207], v[24:27]
	v_mfma_f32_16x16x32_bf16 v[12:15], v[156:159], v[212:215], v[12:15]
	v_mfma_f32_16x16x32_bf16 v[8:11], v[164:167], v[212:215], v[8:11]
	v_mfma_f32_16x16x32_bf16 v[52:55], v[168:171], v[184:187], v[52:55]
	v_mfma_f32_16x16x32_bf16 v[48:51], v[176:179], v[184:187], v[48:51]
	v_mfma_f32_16x16x32_bf16 v[36:39], v[168:171], v[192:195], v[36:39]
	v_mfma_f32_16x16x32_bf16 v[32:35], v[176:179], v[192:195], v[32:35]
	v_mfma_f32_16x16x32_bf16 v[20:23], v[168:171], v[200:203], v[20:23]
	v_mfma_f32_16x16x32_bf16 v[16:19], v[176:179], v[200:203], v[16:19]
	v_mfma_f32_16x16x32_bf16 v[4:7], v[168:171], v[208:211], v[4:7]
	v_mfma_f32_16x16x32_bf16 v[0:3], v[176:179], v[208:211], v[0:3]
	v_mfma_f32_16x16x32_bf16 v[52:55], v[172:175], v[188:191], v[52:55]
	v_mfma_f32_16x16x32_bf16 v[48:51], v[180:183], v[188:191], v[48:51]
	v_mfma_f32_16x16x32_bf16 v[36:39], v[172:175], v[196:199], v[36:39]
	v_mfma_f32_16x16x32_bf16 v[32:35], v[180:183], v[196:199], v[32:35]
	v_mfma_f32_16x16x32_bf16 v[20:23], v[172:175], v[204:207], v[20:23]
	v_mfma_f32_16x16x32_bf16 v[16:19], v[180:183], v[204:207], v[16:19]
	v_mfma_f32_16x16x32_bf16 v[4:7], v[172:175], v[212:215], v[4:7]
	v_mfma_f32_16x16x32_bf16 v[0:3], v[180:183], v[212:215], v[0:3]
	s_barrier
	s_setprio 1
	s_add_i32 s67, 0, 0x18000
	v_add_u32_e32 v155, s67, v149
	s_add_i32 s68, 0, 0x1c000
	ds_read_b128 v[144:147], v155
	ds_read_b128 v[156:159], v155 offset:1024
	ds_read_b128 v[160:163], v155 offset:2048
	ds_read_b128 v[164:167], v155 offset:3072
	v_add_u32_e32 v155, s68, v149
	ds_read_b128 v[168:171], v155
	ds_read_b128 v[172:175], v155 offset:1024
	ds_read_b128 v[176:179], v155 offset:2048
	ds_read_b128 v[180:183], v155 offset:3072
	s_add_u32 s30, s48, 0x160000
	s_addc_u32 s31, s49, 0
	s_mov_b32 m0, s55
	v_lshl_add_u64 v[224:225], s[30:31], 0, v[128:129]
	ds_read_b128 v[184:187], v153 offset:32768
	ds_read_b128 v[188:191], v153 offset:33792
	ds_read_b128 v[192:195], v153 offset:34816
	ds_read_b128 v[196:199], v153 offset:35840
	ds_read_b128 v[200:203], v153 offset:36864
	ds_read_b128 v[204:207], v153 offset:37888
	ds_read_b128 v[208:211], v153 offset:38912
	ds_read_b128 v[212:215], v153 offset:39936
	global_load_lds_dwordx4 v[224:225], off
	v_lshl_add_u64 v[224:225], s[30:31], 0, v[132:133]
	s_mov_b32 m0, s56
	s_nop 0
	global_load_lds_dwordx4 v[224:225], off
	s_waitcnt vmcnt(8)
	s_waitcnt lgkmcnt(0)
	s_setprio 0
	s_barrier
	v_mfma_f32_16x16x32_bf16 v[124:127], v[144:147], v[184:187], v[124:127]
	v_mfma_f32_16x16x32_bf16 v[120:123], v[160:163], v[184:187], v[120:123]
	v_mfma_f32_16x16x32_bf16 v[108:111], v[144:147], v[192:195], v[108:111]
	v_mfma_f32_16x16x32_bf16 v[104:107], v[160:163], v[192:195], v[104:107]
	v_mfma_f32_16x16x32_bf16 v[92:95], v[144:147], v[200:203], v[92:95]
	v_mfma_f32_16x16x32_bf16 v[88:91], v[160:163], v[200:203], v[88:91]
	v_mfma_f32_16x16x32_bf16 v[76:79], v[144:147], v[208:211], v[76:79]
	v_mfma_f32_16x16x32_bf16 v[72:75], v[160:163], v[208:211], v[72:75]
	v_mfma_f32_16x16x32_bf16 v[124:127], v[156:159], v[188:191], v[124:127]
	v_mfma_f32_16x16x32_bf16 v[120:123], v[164:167], v[188:191], v[120:123]
	v_mfma_f32_16x16x32_bf16 v[108:111], v[156:159], v[196:199], v[108:111]
	v_mfma_f32_16x16x32_bf16 v[104:107], v[164:167], v[196:199], v[104:107]
	v_mfma_f32_16x16x32_bf16 v[92:95], v[156:159], v[204:207], v[92:95]
	v_mfma_f32_16x16x32_bf16 v[88:91], v[164:167], v[204:207], v[88:91]
	v_mfma_f32_16x16x32_bf16 v[76:79], v[156:159], v[212:215], v[76:79]
	v_mfma_f32_16x16x32_bf16 v[72:75], v[164:167], v[212:215], v[72:75]
	v_mfma_f32_16x16x32_bf16 v[116:119], v[168:171], v[184:187], v[116:119]
	v_mfma_f32_16x16x32_bf16 v[112:115], v[176:179], v[184:187], v[112:115]
	v_mfma_f32_16x16x32_bf16 v[100:103], v[168:171], v[192:195], v[100:103]
	v_mfma_f32_16x16x32_bf16 v[96:99], v[176:179], v[192:195], v[96:99]
	v_mfma_f32_16x16x32_bf16 v[84:87], v[168:171], v[200:203], v[84:87]
	v_mfma_f32_16x16x32_bf16 v[80:83], v[176:179], v[200:203], v[80:83]
	v_mfma_f32_16x16x32_bf16 v[68:71], v[168:171], v[208:211], v[68:71]
	v_mfma_f32_16x16x32_bf16 v[64:67], v[176:179], v[208:211], v[64:67]
	v_mfma_f32_16x16x32_bf16 v[116:119], v[172:175], v[188:191], v[116:119]
	v_mfma_f32_16x16x32_bf16 v[112:115], v[180:183], v[188:191], v[112:115]
	v_mfma_f32_16x16x32_bf16 v[100:103], v[172:175], v[196:199], v[100:103]
	v_mfma_f32_16x16x32_bf16 v[96:99], v[180:183], v[196:199], v[96:99]
	v_mfma_f32_16x16x32_bf16 v[84:87], v[172:175], v[204:207], v[84:87]
	v_mfma_f32_16x16x32_bf16 v[80:83], v[180:183], v[204:207], v[80:83]
	v_mfma_f32_16x16x32_bf16 v[68:71], v[172:175], v[212:215], v[68:71]
	v_mfma_f32_16x16x32_bf16 v[64:67], v[180:183], v[212:215], v[64:67]
	s_barrier
	s_setprio 1
	s_add_i32 s30, s67, s52
	v_lshl_add_u64 v[216:217], v[216:217], 0, s[22:23]
	s_mov_b32 m0, s30
	ds_read_b128 v[184:187], v153 offset:49152
	ds_read_b128 v[188:191], v153 offset:50176
	ds_read_b128 v[192:195], v153 offset:51200
	ds_read_b128 v[196:199], v153 offset:52224
	ds_read_b128 v[200:203], v153 offset:53248
	ds_read_b128 v[204:207], v153 offset:54272
	ds_read_b128 v[208:211], v153 offset:55296
	ds_read_b128 v[212:215], v153 offset:56320
	global_load_lds_dwordx4 v[216:217], off
	s_add_i32 m0, s30, 0x2000
	s_add_u32 s30, s36, 0x160080
	v_lshl_add_u64 v[216:217], v[218:219], 0, s[22:23]
	s_addc_u32 s31, s37, 0
	s_add_i32 s36, s68, s52
	global_load_lds_dwordx4 v[216:217], off
	v_lshl_add_u64 v[216:217], s[30:31], 0, v[130:131]
	s_mov_b32 m0, s36
	s_nop 0
	global_load_lds_dwordx4 v[216:217], off
	v_lshl_add_u64 v[216:217], s[30:31], 0, v[134:135]
	s_add_i32 m0, s36, 0x2000
	s_nop 0
	global_load_lds_dwordx4 v[216:217], off
	v_lshl_add_u64 v[216:217], v[220:221], 0, s[22:23]
	s_mov_b32 m0, s58
	s_nop 0
	global_load_lds_dwordx4 v[216:217], off
	v_lshl_add_u64 v[216:217], v[222:223], 0, s[22:23]
	s_mov_b32 m0, s59
	s_nop 0
	global_load_lds_dwordx4 v[216:217], off
	s_waitcnt vmcnt(8)
	s_waitcnt lgkmcnt(0)
	s_setprio 0
	s_barrier
	v_mfma_f32_16x16x32_bf16 v[60:63], v[144:147], v[184:187], v[60:63]
	v_mfma_f32_16x16x32_bf16 v[56:59], v[160:163], v[184:187], v[56:59]
	v_mfma_f32_16x16x32_bf16 v[44:47], v[144:147], v[192:195], v[44:47]
	v_mfma_f32_16x16x32_bf16 v[40:43], v[160:163], v[192:195], v[40:43]
	v_mfma_f32_16x16x32_bf16 v[28:31], v[144:147], v[200:203], v[28:31]
	v_mfma_f32_16x16x32_bf16 v[24:27], v[160:163], v[200:203], v[24:27]
	v_mfma_f32_16x16x32_bf16 v[12:15], v[144:147], v[208:211], v[12:15]
	v_mfma_f32_16x16x32_bf16 v[8:11], v[160:163], v[208:211], v[8:11]
	v_mfma_f32_16x16x32_bf16 v[60:63], v[156:159], v[188:191], v[60:63]
	v_mfma_f32_16x16x32_bf16 v[56:59], v[164:167], v[188:191], v[56:59]
	v_mfma_f32_16x16x32_bf16 v[44:47], v[156:159], v[196:199], v[44:47]
	v_mfma_f32_16x16x32_bf16 v[40:43], v[164:167], v[196:199], v[40:43]
	v_mfma_f32_16x16x32_bf16 v[28:31], v[156:159], v[204:207], v[28:31]
	v_mfma_f32_16x16x32_bf16 v[24:27], v[164:167], v[204:207], v[24:27]
	v_mfma_f32_16x16x32_bf16 v[12:15], v[156:159], v[212:215], v[12:15]
	v_mfma_f32_16x16x32_bf16 v[8:11], v[164:167], v[212:215], v[8:11]
	v_mfma_f32_16x16x32_bf16 v[52:55], v[168:171], v[184:187], v[52:55]
	v_mfma_f32_16x16x32_bf16 v[48:51], v[176:179], v[184:187], v[48:51]
	v_mfma_f32_16x16x32_bf16 v[36:39], v[168:171], v[192:195], v[36:39]
	v_mfma_f32_16x16x32_bf16 v[32:35], v[176:179], v[192:195], v[32:35]
	v_mfma_f32_16x16x32_bf16 v[20:23], v[168:171], v[200:203], v[20:23]
	v_mfma_f32_16x16x32_bf16 v[16:19], v[176:179], v[200:203], v[16:19]
	v_mfma_f32_16x16x32_bf16 v[4:7], v[168:171], v[208:211], v[4:7]
	v_mfma_f32_16x16x32_bf16 v[0:3], v[176:179], v[208:211], v[0:3]
	v_mfma_f32_16x16x32_bf16 v[52:55], v[172:175], v[188:191], v[52:55]
	v_mfma_f32_16x16x32_bf16 v[48:51], v[180:183], v[188:191], v[48:51]
	v_mfma_f32_16x16x32_bf16 v[36:39], v[172:175], v[196:199], v[36:39]
	v_mfma_f32_16x16x32_bf16 v[32:35], v[180:183], v[196:199], v[32:35]
	v_mfma_f32_16x16x32_bf16 v[20:23], v[172:175], v[204:207], v[20:23]
	v_mfma_f32_16x16x32_bf16 v[16:19], v[180:183], v[204:207], v[16:19]
	v_mfma_f32_16x16x32_bf16 v[4:7], v[172:175], v[212:215], v[4:7]
	v_mfma_f32_16x16x32_bf16 v[0:3], v[180:183], v[212:215], v[0:3]
	s_barrier
	s_setprio 1
	s_add_i32 s66, s66, 2
	s_add_u32 s46, s46, 0x100
	s_addc_u32 s47, s47, 0
	s_cmpk_gt_u32 s66, 0x55
	s_mov_b64 s[30:31], s[34:35]
	s_cbranch_scc0 .LBB0_1137
	s_and_b64 vcc, exec, s[24:25]
	s_cbranch_vccz .LBB0_1140
	s_barrier

.LBB0_1227:
	v_add_u32_e32 v164, s56, v150
	v_add_u32_e32 v180, s57, v150
	s_add_u32 s34, s16, s30
	ds_read_b128 v[152:155], v164
	ds_read_b128 v[156:159], v164 offset:1024
	ds_read_b128 v[160:163], v164 offset:2048
	ds_read_b128 v[164:167], v164 offset:3072
	ds_read_b128 v[168:171], v180
	ds_read_b128 v[172:175], v180 offset:1024
	ds_read_b128 v[176:179], v180 offset:2048
	ds_read_b128 v[180:183], v180 offset:3072
	s_addc_u32 s35, s17, s31
	s_add_u32 s34, s34, 0x100
	s_addc_u32 s35, s35, 0
	s_add_u32 s64, s59, s30
	s_addc_u32 s65, s60, s31
	s_cmpk_eq_i32 s30, 0xf00
	s_cselect_b32 s37, s23, s35
	s_cselect_b32 s36, s61, s34
	s_cselect_b32 s35, s21, s65
	s_cselect_b32 s34, s62, s64
	v_lshl_add_u64 v[216:217], v[146:147], 0, s[30:31]
	s_add_i32 m0, s48, 0xc000
	ds_read_b128 v[184:187], v151
	ds_read_b128 v[188:191], v151 offset:1024
	ds_read_b128 v[192:195], v151 offset:2048
	ds_read_b128 v[196:199], v151 offset:3072
	ds_read_b128 v[200:203], v151 offset:4096
	ds_read_b128 v[204:207], v151 offset:5120
	ds_read_b128 v[208:211], v151 offset:6144
	ds_read_b128 v[212:215], v151 offset:7168
	global_load_lds_dwordx4 v[216:217], off
	v_lshl_add_u64 v[216:217], v[144:145], 0, s[30:31]
	s_add_i32 m0, s48, 0xe000
	s_nop 0
	global_load_lds_dwordx4 v[216:217], off
	s_waitcnt vmcnt(8)
	s_waitcnt lgkmcnt(0)
	s_setprio 0
	s_barrier
	v_mfma_f32_16x16x32_bf16 v[124:127], v[152:155], v[184:187], v[124:127]
	v_mfma_f32_16x16x32_bf16 v[120:123], v[160:163], v[184:187], v[120:123]
	v_mfma_f32_16x16x32_bf16 v[108:111], v[152:155], v[192:195], v[108:111]
	v_mfma_f32_16x16x32_bf16 v[104:107], v[160:163], v[192:195], v[104:107]
	v_mfma_f32_16x16x32_bf16 v[92:95], v[152:155], v[200:203], v[92:95]
	v_mfma_f32_16x16x32_bf16 v[88:91], v[160:163], v[200:203], v[88:91]
	v_mfma_f32_16x16x32_bf16 v[76:79], v[152:155], v[208:211], v[76:79]
	v_mfma_f32_16x16x32_bf16 v[72:75], v[160:163], v[208:211], v[72:75]
	v_mfma_f32_16x16x32_bf16 v[124:127], v[156:159], v[188:191], v[124:127]
	v_mfma_f32_16x16x32_bf16 v[120:123], v[164:167], v[188:191], v[120:123]
	v_mfma_f32_16x16x32_bf16 v[108:111], v[156:159], v[196:199], v[108:111]
	v_mfma_f32_16x16x32_bf16 v[104:107], v[164:167], v[196:199], v[104:107]
	v_mfma_f32_16x16x32_bf16 v[92:95], v[156:159], v[204:207], v[92:95]
	v_mfma_f32_16x16x32_bf16 v[88:91], v[164:167], v[204:207], v[88:91]
	v_mfma_f32_16x16x32_bf16 v[76:79], v[156:159], v[212:215], v[76:79]
	v_mfma_f32_16x16x32_bf16 v[72:75], v[164:167], v[212:215], v[72:75]
	v_mfma_f32_16x16x32_bf16 v[116:119], v[168:171], v[184:187], v[116:119]
	v_mfma_f32_16x16x32_bf16 v[112:115], v[176:179], v[184:187], v[112:115]
	v_mfma_f32_16x16x32_bf16 v[100:103], v[168:171], v[192:195], v[100:103]
	v_mfma_f32_16x16x32_bf16 v[96:99], v[176:179], v[192:195], v[96:99]
	v_mfma_f32_16x16x32_bf16 v[84:87], v[168:171], v[200:203], v[84:87]
	v_mfma_f32_16x16x32_bf16 v[80:83], v[176:179], v[200:203], v[80:83]
	v_mfma_f32_16x16x32_bf16 v[68:71], v[168:171], v[208:211], v[68:71]
	v_mfma_f32_16x16x32_bf16 v[64:67], v[176:179], v[208:211], v[64:67]
	v_mfma_f32_16x16x32_bf16 v[116:119], v[172:175], v[188:191], v[116:119]
	v_mfma_f32_16x16x32_bf16 v[112:115], v[180:183], v[188:191], v[112:115]
	v_mfma_f32_16x16x32_bf16 v[100:103], v[172:175], v[196:199], v[100:103]
	v_mfma_f32_16x16x32_bf16 v[96:99], v[180:183], v[196:199], v[96:99]
	v_mfma_f32_16x16x32_bf16 v[84:87], v[172:175], v[204:207], v[84:87]
	v_mfma_f32_16x16x32_bf16 v[80:83], v[180:183], v[204:207], v[80:83]
	v_mfma_f32_16x16x32_bf16 v[68:71], v[172:175], v[212:215], v[68:71]
	v_mfma_f32_16x16x32_bf16 v[64:67], v[180:183], v[212:215], v[64:67]
	s_barrier
	s_setprio 1
	s_add_i32 s64, s56, s47
	v_lshl_add_u64 v[216:217], s[34:35], 0, v[130:131]
	s_mov_b32 m0, s64
	ds_read_b128 v[184:187], v151 offset:16384
	ds_read_b128 v[188:191], v151 offset:17408
	ds_read_b128 v[192:195], v151 offset:18432
	ds_read_b128 v[196:199], v151 offset:19456
	ds_read_b128 v[200:203], v151 offset:20480
	ds_read_b128 v[204:207], v151 offset:21504
	ds_read_b128 v[208:211], v151 offset:22528
	ds_read_b128 v[212:215], v151 offset:23552
	global_load_lds_dwordx4 v[216:217], off
	s_add_i32 m0, s64, 0x2000
	s_add_u32 s64, s34, 0x80000
	v_lshl_add_u64 v[218:219], s[34:35], 0, v[134:135]
	s_addc_u32 s65, s35, 0
	s_add_i32 s66, s57, s47
	global_load_lds_dwordx4 v[218:219], off
	v_lshl_add_u64 v[220:221], s[64:65], 0, v[130:131]
	s_mov_b32 m0, s66
	v_lshl_add_u64 v[222:223], s[36:37], 0, v[132:133]
	global_load_lds_dwordx4 v[220:221], off
	v_lshl_add_u64 v[220:221], s[64:65], 0, v[134:135]
	s_add_i32 m0, s66, 0x2000
	s_nop 0
	global_load_lds_dwordx4 v[220:221], off
	v_lshl_add_u64 v[220:221], s[36:37], 0, v[128:129]
	s_mov_b32 m0, s48
	s_nop 0
	global_load_lds_dwordx4 v[220:221], off
	s_mov_b32 m0, s49
	s_nop 0
	global_load_lds_dwordx4 v[222:223], off
	s_waitcnt vmcnt(8)
	s_waitcnt lgkmcnt(0)
	s_setprio 0
	s_barrier
	v_mfma_f32_16x16x32_bf16 v[60:63], v[152:155], v[184:187], v[60:63]
	v_mfma_f32_16x16x32_bf16 v[56:59], v[160:163], v[184:187], v[56:59]
	v_mfma_f32_16x16x32_bf16 v[44:47], v[152:155], v[192:195], v[44:47]
	v_mfma_f32_16x16x32_bf16 v[40:43], v[160:163], v[192:195], v[40:43]
	v_mfma_f32_16x16x32_bf16 v[28:31], v[152:155], v[200:203], v[28:31]
	v_mfma_f32_16x16x32_bf16 v[24:27], v[160:163], v[200:203], v[24:27]
	v_mfma_f32_16x16x32_bf16 v[12:15], v[152:155], v[208:211], v[12:15]
	v_mfma_f32_16x16x32_bf16 v[8:11], v[160:163], v[208:211], v[8:11]
	v_mfma_f32_16x16x32_bf16 v[60:63], v[156:159], v[188:191], v[60:63]
	v_mfma_f32_16x16x32_bf16 v[56:59], v[164:167], v[188:191], v[56:59]
	v_mfma_f32_16x16x32_bf16 v[44:47], v[156:159], v[196:199], v[44:47]
	v_mfma_f32_16x16x32_bf16 v[40:43], v[164:167], v[196:199], v[40:43]
	v_mfma_f32_16x16x32_bf16 v[28:31], v[156:159], v[204:207], v[28:31]
	v_mfma_f32_16x16x32_bf16 v[24:27], v[164:167], v[204:207], v[24:27]
	v_mfma_f32_16x16x32_bf16 v[12:15], v[156:159], v[212:215], v[12:15]
	v_mfma_f32_16x16x32_bf16 v[8:11], v[164:167], v[212:215], v[8:11]
	v_mfma_f32_16x16x32_bf16 v[52:55], v[168:171], v[184:187], v[52:55]
	v_mfma_f32_16x16x32_bf16 v[48:51], v[176:179], v[184:187], v[48:51]
	v_mfma_f32_16x16x32_bf16 v[36:39], v[168:171], v[192:195], v[36:39]
	v_mfma_f32_16x16x32_bf16 v[32:35], v[176:179], v[192:195], v[32:35]
	v_mfma_f32_16x16x32_bf16 v[20:23], v[168:171], v[200:203], v[20:23]
	v_mfma_f32_16x16x32_bf16 v[16:19], v[176:179], v[200:203], v[16:19]
	v_mfma_f32_16x16x32_bf16 v[4:7], v[168:171], v[208:211], v[4:7]
	v_mfma_f32_16x16x32_bf16 v[0:3], v[176:179], v[208:211], v[0:3]
	v_mfma_f32_16x16x32_bf16 v[52:55], v[172:175], v[188:191], v[52:55]
	v_mfma_f32_16x16x32_bf16 v[48:51], v[180:183], v[188:191], v[48:51]
	v_mfma_f32_16x16x32_bf16 v[36:39], v[172:175], v[196:199], v[36:39]
	v_mfma_f32_16x16x32_bf16 v[32:35], v[180:183], v[196:199], v[32:35]
	v_mfma_f32_16x16x32_bf16 v[20:23], v[172:175], v[204:207], v[20:23]
	v_mfma_f32_16x16x32_bf16 v[16:19], v[180:183], v[204:207], v[16:19]
	v_mfma_f32_16x16x32_bf16 v[4:7], v[172:175], v[212:215], v[4:7]
	v_mfma_f32_16x16x32_bf16 v[0:3], v[180:183], v[212:215], v[0:3]
	s_barrier
	s_setprio 1
	s_add_i32 s64, 0, 0x18000
	s_add_i32 s65, 0, 0x1c000
	v_add_u32_e32 v164, s64, v150
	v_add_u32_e32 v180, s65, v150
	ds_read_b128 v[152:155], v164
	ds_read_b128 v[156:159], v164 offset:1024
	ds_read_b128 v[160:163], v164 offset:2048
	ds_read_b128 v[164:167], v164 offset:3072
	ds_read_b128 v[168:171], v180
	ds_read_b128 v[172:175], v180 offset:1024
	ds_read_b128 v[176:179], v180 offset:2048
	ds_read_b128 v[180:183], v180 offset:3072
	s_add_u32 s36, s36, 0x80000
	s_addc_u32 s37, s37, 0
	s_mov_b32 m0, s50
	v_lshl_add_u64 v[224:225], s[36:37], 0, v[128:129]
	ds_read_b128 v[184:187], v151 offset:32768
	ds_read_b128 v[188:191], v151 offset:33792
	ds_read_b128 v[192:195], v151 offset:34816
	ds_read_b128 v[196:199], v151 offset:35840
	ds_read_b128 v[200:203], v151 offset:36864
	ds_read_b128 v[204:207], v151 offset:37888
	ds_read_b128 v[208:211], v151 offset:38912
	ds_read_b128 v[212:215], v151 offset:39936
	global_load_lds_dwordx4 v[224:225], off
	v_lshl_add_u64 v[224:225], s[36:37], 0, v[132:133]
	s_mov_b32 m0, s51
	s_nop 0
	global_load_lds_dwordx4 v[224:225], off
	s_waitcnt vmcnt(8)
	s_waitcnt lgkmcnt(0)
	s_setprio 0
	s_barrier
	v_mfma_f32_16x16x32_bf16 v[124:127], v[152:155], v[184:187], v[124:127]
	v_mfma_f32_16x16x32_bf16 v[120:123], v[160:163], v[184:187], v[120:123]
	v_mfma_f32_16x16x32_bf16 v[108:111], v[152:155], v[192:195], v[108:111]
	v_mfma_f32_16x16x32_bf16 v[104:107], v[160:163], v[192:195], v[104:107]
	v_mfma_f32_16x16x32_bf16 v[92:95], v[152:155], v[200:203], v[92:95]
	v_mfma_f32_16x16x32_bf16 v[88:91], v[160:163], v[200:203], v[88:91]
	v_mfma_f32_16x16x32_bf16 v[76:79], v[152:155], v[208:211], v[76:79]
	v_mfma_f32_16x16x32_bf16 v[72:75], v[160:163], v[208:211], v[72:75]
	v_mfma_f32_16x16x32_bf16 v[124:127], v[156:159], v[188:191], v[124:127]
	v_mfma_f32_16x16x32_bf16 v[120:123], v[164:167], v[188:191], v[120:123]
	v_mfma_f32_16x16x32_bf16 v[108:111], v[156:159], v[196:199], v[108:111]
	v_mfma_f32_16x16x32_bf16 v[104:107], v[164:167], v[196:199], v[104:107]
	v_mfma_f32_16x16x32_bf16 v[92:95], v[156:159], v[204:207], v[92:95]
	v_mfma_f32_16x16x32_bf16 v[88:91], v[164:167], v[204:207], v[88:91]
	v_mfma_f32_16x16x32_bf16 v[76:79], v[156:159], v[212:215], v[76:79]
	v_mfma_f32_16x16x32_bf16 v[72:75], v[164:167], v[212:215], v[72:75]
	v_mfma_f32_16x16x32_bf16 v[116:119], v[168:171], v[184:187], v[116:119]
	v_mfma_f32_16x16x32_bf16 v[112:115], v[176:179], v[184:187], v[112:115]
	v_mfma_f32_16x16x32_bf16 v[100:103], v[168:171], v[192:195], v[100:103]
	v_mfma_f32_16x16x32_bf16 v[96:99], v[176:179], v[192:195], v[96:99]
	v_mfma_f32_16x16x32_bf16 v[84:87], v[168:171], v[200:203], v[84:87]
	v_mfma_f32_16x16x32_bf16 v[80:83], v[176:179], v[200:203], v[80:83]
	v_mfma_f32_16x16x32_bf16 v[68:71], v[168:171], v[208:211], v[68:71]
	v_mfma_f32_16x16x32_bf16 v[64:67], v[176:179], v[208:211], v[64:67]
	v_mfma_f32_16x16x32_bf16 v[116:119], v[172:175], v[188:191], v[116:119]
	v_mfma_f32_16x16x32_bf16 v[112:115], v[180:183], v[188:191], v[112:115]
	v_mfma_f32_16x16x32_bf16 v[100:103], v[172:175], v[196:199], v[100:103]
	v_mfma_f32_16x16x32_bf16 v[96:99], v[180:183], v[196:199], v[96:99]
	v_mfma_f32_16x16x32_bf16 v[84:87], v[172:175], v[204:207], v[84:87]
	v_mfma_f32_16x16x32_bf16 v[80:83], v[180:183], v[204:207], v[80:83]
	v_mfma_f32_16x16x32_bf16 v[68:71], v[172:175], v[212:215], v[68:71]
	v_mfma_f32_16x16x32_bf16 v[64:67], v[180:183], v[212:215], v[64:67]
	s_barrier
	s_setprio 1
	s_add_i32 s36, s64, s47
	v_lshl_add_u64 v[216:217], v[216:217], 0, s[18:19]
	s_mov_b32 m0, s36
	ds_read_b128 v[184:187], v151 offset:49152
	ds_read_b128 v[188:191], v151 offset:50176
	ds_read_b128 v[192:195], v151 offset:51200
	ds_read_b128 v[196:199], v151 offset:52224
	ds_read_b128 v[200:203], v151 offset:53248
	ds_read_b128 v[204:207], v151 offset:54272
	ds_read_b128 v[208:211], v151 offset:55296
	ds_read_b128 v[212:215], v151 offset:56320
	global_load_lds_dwordx4 v[216:217], off
	s_add_i32 m0, s36, 0x2000
	s_add_u32 s34, s34, 0x80080
	v_lshl_add_u64 v[216:217], v[218:219], 0, s[18:19]
	s_addc_u32 s35, s35, 0
	s_add_i32 s36, s65, s47
	global_load_lds_dwordx4 v[216:217], off
	v_lshl_add_u64 v[216:217], s[34:35], 0, v[130:131]
	s_mov_b32 m0, s36
	s_nop 0
	global_load_lds_dwordx4 v[216:217], off
	v_lshl_add_u64 v[216:217], s[34:35], 0, v[134:135]
	s_add_i32 m0, s36, 0x2000
	s_nop 0
	global_load_lds_dwordx4 v[216:217], off
	v_lshl_add_u64 v[216:217], v[220:221], 0, s[18:19]
	s_mov_b32 m0, s54
	s_nop 0
	global_load_lds_dwordx4 v[216:217], off
	v_lshl_add_u64 v[216:217], v[222:223], 0, s[18:19]
	s_mov_b32 m0, s55
	s_nop 0
	global_load_lds_dwordx4 v[216:217], off
	s_waitcnt vmcnt(8)
	s_waitcnt lgkmcnt(0)
	s_setprio 0
	s_barrier
	v_mfma_f32_16x16x32_bf16 v[60:63], v[152:155], v[184:187], v[60:63]
	v_mfma_f32_16x16x32_bf16 v[56:59], v[160:163], v[184:187], v[56:59]
	v_mfma_f32_16x16x32_bf16 v[44:47], v[152:155], v[192:195], v[44:47]
	v_mfma_f32_16x16x32_bf16 v[40:43], v[160:163], v[192:195], v[40:43]
	v_mfma_f32_16x16x32_bf16 v[28:31], v[152:155], v[200:203], v[28:31]
	v_mfma_f32_16x16x32_bf16 v[24:27], v[160:163], v[200:203], v[24:27]
	v_mfma_f32_16x16x32_bf16 v[12:15], v[152:155], v[208:211], v[12:15]
	v_mfma_f32_16x16x32_bf16 v[8:11], v[160:163], v[208:211], v[8:11]
	v_mfma_f32_16x16x32_bf16 v[60:63], v[156:159], v[188:191], v[60:63]
	v_mfma_f32_16x16x32_bf16 v[56:59], v[164:167], v[188:191], v[56:59]
	v_mfma_f32_16x16x32_bf16 v[44:47], v[156:159], v[196:199], v[44:47]
	v_mfma_f32_16x16x32_bf16 v[40:43], v[164:167], v[196:199], v[40:43]
	v_mfma_f32_16x16x32_bf16 v[28:31], v[156:159], v[204:207], v[28:31]
	v_mfma_f32_16x16x32_bf16 v[24:27], v[164:167], v[204:207], v[24:27]
	v_mfma_f32_16x16x32_bf16 v[12:15], v[156:159], v[212:215], v[12:15]
	v_mfma_f32_16x16x32_bf16 v[8:11], v[164:167], v[212:215], v[8:11]
	v_mfma_f32_16x16x32_bf16 v[52:55], v[168:171], v[184:187], v[52:55]
	v_mfma_f32_16x16x32_bf16 v[48:51], v[176:179], v[184:187], v[48:51]
	v_mfma_f32_16x16x32_bf16 v[36:39], v[168:171], v[192:195], v[36:39]
	v_mfma_f32_16x16x32_bf16 v[32:35], v[176:179], v[192:195], v[32:35]
	v_mfma_f32_16x16x32_bf16 v[20:23], v[168:171], v[200:203], v[20:23]
	v_mfma_f32_16x16x32_bf16 v[16:19], v[176:179], v[200:203], v[16:19]
	v_mfma_f32_16x16x32_bf16 v[4:7], v[168:171], v[208:211], v[4:7]
	v_mfma_f32_16x16x32_bf16 v[0:3], v[176:179], v[208:211], v[0:3]
	v_mfma_f32_16x16x32_bf16 v[52:55], v[172:175], v[188:191], v[52:55]
	v_mfma_f32_16x16x32_bf16 v[48:51], v[180:183], v[188:191], v[48:51]
	v_mfma_f32_16x16x32_bf16 v[36:39], v[172:175], v[196:199], v[36:39]
	v_mfma_f32_16x16x32_bf16 v[32:35], v[180:183], v[196:199], v[32:35]
	v_mfma_f32_16x16x32_bf16 v[20:23], v[172:175], v[204:207], v[20:23]
	v_mfma_f32_16x16x32_bf16 v[16:19], v[180:183], v[204:207], v[16:19]
	v_mfma_f32_16x16x32_bf16 v[4:7], v[172:175], v[212:215], v[4:7]
	v_mfma_f32_16x16x32_bf16 v[0:3], v[180:183], v[212:215], v[0:3]
	s_barrier
	s_setprio 1
	s_add_i32 s63, s63, 2
	s_add_u32 s30, s30, 0x100
	s_addc_u32 s31, s31, 0
	s_cmp_gt_u32 s63, 29
	s_cbranch_scc0 .LBB0_1227
	s_add_u32 s30, s59, 0xffffff00
	s_addc_u32 s31, s60, -1
	s_andn2_b64 vcc, exec, s[4:5]
	s_cbranch_vccnz .LBB0_1230
	v_mov_b32_e32 v0, 0
	s_mov_b32 s15, s20
	s_mov_b32 s14, s22
	s_mov_b64 s[16:17], s[26:27]
	s_mov_b32 s53, s58
	v_mov_b32_e32 v1, v0
	v_pk_mov_b32 v[2:3], 0, 0
	v_pk_mov_b32 v[4:5], 0, 0
	v_pk_mov_b32 v[6:7], 0, 0
	v_pk_mov_b32 v[16:17], 0, 0
	v_pk_mov_b32 v[18:19], 0, 0
	v_pk_mov_b32 v[20:21], 0, 0
	v_pk_mov_b32 v[22:23], 0, 0
	v_pk_mov_b32 v[32:33], 0, 0
	v_pk_mov_b32 v[34:35], 0, 0
	v_pk_mov_b32 v[36:37], 0, 0
	v_pk_mov_b32 v[38:39], 0, 0
	v_pk_mov_b32 v[48:49], 0, 0
	v_pk_mov_b32 v[50:51], 0, 0
	v_pk_mov_b32 v[52:53], 0, 0
	v_pk_mov_b32 v[54:55], 0, 0
	v_pk_mov_b32 v[8:9], 0, 0
	v_pk_mov_b32 v[10:11], 0, 0
	v_pk_mov_b32 v[12:13], 0, 0
	v_pk_mov_b32 v[14:15], 0, 0
	v_pk_mov_b32 v[24:25], 0, 0
	v_pk_mov_b32 v[26:27], 0, 0
	v_pk_mov_b32 v[28:29], 0, 0
	v_pk_mov_b32 v[30:31], 0, 0
	v_pk_mov_b32 v[40:41], 0, 0
	v_pk_mov_b32 v[42:43], 0, 0
	v_pk_mov_b32 v[44:45], 0, 0
	v_pk_mov_b32 v[46:47], 0, 0
	v_pk_mov_b32 v[56:57], 0, 0
	v_pk_mov_b32 v[58:59], 0, 0
	v_pk_mov_b32 v[60:61], 0, 0
	v_pk_mov_b32 v[62:63], 0, 0
	v_pk_mov_b32 v[64:65], 0, 0
	v_pk_mov_b32 v[66:67], 0, 0
	v_pk_mov_b32 v[68:69], 0, 0
	v_pk_mov_b32 v[70:71], 0, 0
	v_pk_mov_b32 v[80:81], 0, 0
	v_pk_mov_b32 v[82:83], 0, 0
	v_pk_mov_b32 v[84:85], 0, 0
	v_pk_mov_b32 v[86:87], 0, 0
	v_pk_mov_b32 v[96:97], 0, 0
	v_pk_mov_b32 v[98:99], 0, 0
	v_pk_mov_b32 v[100:101], 0, 0
	v_pk_mov_b32 v[102:103], 0, 0
	v_pk_mov_b32 v[112:113], 0, 0
	v_pk_mov_b32 v[114:115], 0, 0
	v_pk_mov_b32 v[116:117], 0, 0
	v_pk_mov_b32 v[118:119], 0, 0
	v_pk_mov_b32 v[72:73], 0, 0
	v_pk_mov_b32 v[74:75], 0, 0
	v_pk_mov_b32 v[76:77], 0, 0
	v_pk_mov_b32 v[78:79], 0, 0
	v_pk_mov_b32 v[88:89], 0, 0
	v_pk_mov_b32 v[90:91], 0, 0
	v_pk_mov_b32 v[92:93], 0, 0
	v_pk_mov_b32 v[94:95], 0, 0
	v_pk_mov_b32 v[104:105], 0, 0
	v_pk_mov_b32 v[106:107], 0, 0
	v_pk_mov_b32 v[108:109], 0, 0
	v_pk_mov_b32 v[110:111], 0, 0
	v_pk_mov_b32 v[120:121], 0, 0
	v_pk_mov_b32 v[122:123], 0, 0
	v_pk_mov_b32 v[124:125], 0, 0
	v_pk_mov_b32 v[126:127], 0, 0
	s_andn2_b64 vcc, exec, s[0:1]
	s_cbranch_vccnz .LBB0_1231
	s_branch .LBB0_1232
